# hand-written rnn_combine (all 48 row loads in flight per wave, interleaved wave reductions) on top of the stack
# speedup vs baseline: 1.0013x; 1.0013x over previous
; __device__ __forceinline__ void rnn_combine(const Params& p) {
;     const int tid = threadIdx.x, lane = tid & 63, wave = tid >> 6;
;     unsigned char* ws = p.ws;
;     const bf16_t* P = (const bf16_t*)(ws + WS_P); const bf16_t* H0 = (const bf16_t*)(ws + WS_H); const bf16_t* H1 = H0 + (size_t)MT * 512;
;     bf16_t* MIX = (bf16_t*)(ws + WS_MIX); float* ss_b = (float*)(ws + WS_SS) + 2 * MT + MR;
;     const int NW = gridDim.x * 8;
;     for (int r0 = blockIdx.x * 8 + wave; r0 < MR; r0 += 4 * NW) {
;         u32x4 hf[4], hb[4], gw[4];
; #pragma unroll
;         for (int k = 0; k < 4; ++k) { const int rr = (r0 + k * NW < MR) ? r0 + k * NW : r0; const int b = rr / SEQ, sidx = rr % SEQ; const size_t src = (size_t)b * TT + sidx + NMETA;
;             hf[k] = *(const u32x4*)(H0 + src * 512 + 8 * lane); hb[k] = *(const u32x4*)(H1 + src * 512 + 8 * lane); gw[k] = *(const u32x4*)(P + src * INP + C_GATE + 8 * lane); }
.LBB0_695:
	s_cmp_lt_i32 s24, 4
	s_cselect_b64 s[2:3], -1, 0
	s_and_b64 s[86:87], s[2:3], s[0:1]
	s_andn2_b64 vcc, exec, s[86:87]
	s_cbranch_vccnz .LBB0_777
	s_bitcmp1_b32 s92, 3
	s_cselect_b64 s[88:89], -1, 0
	s_and_b64 vcc, exec, s[88:89]
	s_cbranch_vccnz .LBB0_712
	s_cmpk_lg_i32 s28, 0x100
	s_cbranch_scc1 .Lcomb_orig_a
	v_readfirstlane_b32 s0, v162
	v_and_b32_e32 v0, 63, v163
	s_lshl_b32 s1, s18, 3
	v_lshlrev_b32_e32 v7, 4, v0
	s_add_i32 s0, s0, s1
	v_xor_b32_e32 v1, 1, v0
	v_xor_b32_e32 v2, 2, v0
	v_xor_b32_e32 v3, 4, v0
	v_xor_b32_e32 v4, 8, v0
	v_xor_b32_e32 v5, 16, v0
	v_xor_b32_e32 v6, 32, v0
	v_lshlrev_b32_e32 v1, 2, v1
	v_lshlrev_b32_e32 v2, 2, v2
	v_lshlrev_b32_e32 v3, 2, v3
	v_lshlrev_b32_e32 v4, 2, v4
	v_lshlrev_b32_e32 v5, 2, v5
	v_lshlrev_b32_e32 v6, 2, v6
	s_add_i32 s1, s0, 16
	s_lshl_b32 s2, s1, 10
	s_add_u32 s4, s22, s2
	s_addc_u32 s5, s23, 0
	s_add_u32 s4, s4, 0x19800000
	s_addc_u32 s5, s5, 0
	s_add_u32 s8, s4, 0x2040000
	s_addc_u32 s9, s5, 0
	s_mul_i32 s2, s1, 0xe00
	s_add_u32 s6, s22, s2
	s_addc_u32 s7, s23, 0
	s_add_u32 s6, s6, 0x6400940
	s_addc_u32 s7, s7, 0
	global_load_dwordx4 v[32:35], v7, s[4:5]
	global_load_dwordx4 v[36:39], v7, s[8:9]
	global_load_dwordx4 v[40:43], v7, s[6:7]
	s_add_u32 s4, s4, 0x204000
	s_addc_u32 s5, s5, 0
	s_add_u32 s8, s8, 0x204000
	s_addc_u32 s9, s9, 0
	s_add_u32 s6, s6, 0x70e000
	s_addc_u32 s7, s7, 0
	global_load_dwordx4 v[44:47], v7, s[4:5]
	global_load_dwordx4 v[48:51], v7, s[8:9]
	global_load_dwordx4 v[52:55], v7, s[6:7]
	s_add_u32 s4, s4, 0x204000
	s_addc_u32 s5, s5, 0
	s_add_u32 s8, s8, 0x204000
	s_addc_u32 s9, s9, 0
	s_add_u32 s6, s6, 0x70e000
	s_addc_u32 s7, s7, 0
	global_load_dwordx4 v[56:59], v7, s[4:5]
	global_load_dwordx4 v[60:63], v7, s[8:9]
	global_load_dwordx4 v[64:67], v7, s[6:7]
	s_add_u32 s4, s4, 0x204000
	s_addc_u32 s5, s5, 0
	s_add_u32 s8, s8, 0x204000
	s_addc_u32 s9, s9, 0
	s_add_u32 s6, s6, 0x70e000
	s_addc_u32 s7, s7, 0
	global_load_dwordx4 v[68:71], v7, s[4:5]
	global_load_dwordx4 v[72:75], v7, s[8:9]
	global_load_dwordx4 v[76:79], v7, s[6:7]
	s_add_u32 s4, s4, 0x204000
	s_addc_u32 s5, s5, 0
	s_add_u32 s8, s8, 0x204000
	s_addc_u32 s9, s9, 0
	s_add_u32 s6, s6, 0x70e000
	s_addc_u32 s7, s7, 0
	global_load_dwordx4 v[80:83], v7, s[4:5]
	global_load_dwordx4 v[84:87], v7, s[8:9]
	global_load_dwordx4 v[88:91], v7, s[6:7]
	s_add_u32 s4, s4, 0x204000
	s_addc_u32 s5, s5, 0
	s_add_u32 s8, s8, 0x204000
	s_addc_u32 s9, s9, 0
	s_add_u32 s6, s6, 0x70e000
	s_addc_u32 s7, s7, 0
	global_load_dwordx4 v[92:95], v7, s[4:5]
	global_load_dwordx4 v[96:99], v7, s[8:9]
	global_load_dwordx4 v[100:103], v7, s[6:7]
	s_add_u32 s4, s4, 0x204000
	s_addc_u32 s5, s5, 0
	s_add_u32 s8, s8, 0x204000
	s_addc_u32 s9, s9, 0
	s_add_u32 s6, s6, 0x70e000
	s_addc_u32 s7, s7, 0
	global_load_dwordx4 v[104:107], v7, s[4:5]
	global_load_dwordx4 v[108:111], v7, s[8:9]
	global_load_dwordx4 v[112:115], v7, s[6:7]
	s_add_u32 s4, s4, 0x204000
	s_addc_u32 s5, s5, 0
	s_add_u32 s8, s8, 0x204000
	s_addc_u32 s9, s9, 0
	s_add_u32 s6, s6, 0x70e000
	s_addc_u32 s7, s7, 0
	global_load_dwordx4 v[116:119], v7, s[4:5]
	global_load_dwordx4 v[120:123], v7, s[8:9]
	global_load_dwordx4 v[124:127], v7, s[6:7]
	s_add_u32 s4, s4, 0x204000
	s_addc_u32 s5, s5, 0
	s_add_u32 s8, s8, 0x204000
	s_addc_u32 s9, s9, 0
	s_add_u32 s6, s6, 0x70e000
	s_addc_u32 s7, s7, 0
	global_load_dwordx4 v[128:131], v7, s[4:5]
	global_load_dwordx4 v[132:135], v7, s[8:9]
	global_load_dwordx4 v[136:139], v7, s[6:7]
	s_add_u32 s4, s4, 0x204000
	s_addc_u32 s5, s5, 0
	s_add_u32 s8, s8, 0x204000
	s_addc_u32 s9, s9, 0
	s_add_u32 s6, s6, 0x70e000
	s_addc_u32 s7, s7, 0
	global_load_dwordx4 v[140:143], v7, s[4:5]
	global_load_dwordx4 v[144:147], v7, s[8:9]
	global_load_dwordx4 v[148:151], v7, s[6:7]
	s_add_u32 s4, s4, 0x204000
	s_addc_u32 s5, s5, 0
	s_add_u32 s8, s8, 0x204000
	s_addc_u32 s9, s9, 0
	s_add_u32 s6, s6, 0x70e000
	s_addc_u32 s7, s7, 0
	global_load_dwordx4 v[164:167], v7, s[4:5]
	global_load_dwordx4 v[168:171], v7, s[8:9]
	global_load_dwordx4 v[172:175], v7, s[6:7]
	s_add_u32 s4, s4, 0x204000
	s_addc_u32 s5, s5, 0
	s_add_u32 s8, s8, 0x204000
	s_addc_u32 s9, s9, 0
	s_add_u32 s6, s6, 0x70e000
	s_addc_u32 s7, s7, 0
	global_load_dwordx4 v[176:179], v7, s[4:5]
	global_load_dwordx4 v[180:183], v7, s[8:9]
	global_load_dwordx4 v[184:187], v7, s[6:7]
	s_add_u32 s4, s4, 0x204000
	s_addc_u32 s5, s5, 0
	s_add_u32 s8, s8, 0x204000
	s_addc_u32 s9, s9, 0
	s_add_u32 s6, s6, 0x70e000
	s_addc_u32 s7, s7, 0
	global_load_dwordx4 v[188:191], v7, s[4:5]
	global_load_dwordx4 v[192:195], v7, s[8:9]
	global_load_dwordx4 v[196:199], v7, s[6:7]
	s_add_u32 s4, s4, 0x204000
	s_addc_u32 s5, s5, 0
	s_add_u32 s8, s8, 0x204000
	s_addc_u32 s9, s9, 0
	s_add_u32 s6, s6, 0x70e000
	s_addc_u32 s7, s7, 0
	global_load_dwordx4 v[200:203], v7, s[4:5]
	global_load_dwordx4 v[204:207], v7, s[8:9]
	global_load_dwordx4 v[208:211], v7, s[6:7]
	s_add_u32 s4, s4, 0x204000
	s_addc_u32 s5, s5, 0
	s_add_u32 s8, s8, 0x204000
	s_addc_u32 s9, s9, 0
	s_add_u32 s6, s6, 0x70e000
	s_addc_u32 s7, s7, 0
	global_load_dwordx4 v[212:215], v7, s[4:5]
	global_load_dwordx4 v[216:219], v7, s[8:9]
	global_load_dwordx4 v[220:223], v7, s[6:7]
	s_add_u32 s4, s4, 0x204000
	s_addc_u32 s5, s5, 0
	s_add_u32 s8, s8, 0x204000
	s_addc_u32 s9, s9, 0
	s_add_u32 s6, s6, 0x70e000
	s_addc_u32 s7, s7, 0
	global_load_dwordx4 v[224:227], v7, s[4:5]
	global_load_dwordx4 v[228:231], v7, s[8:9]
	global_load_dwordx4 v[232:235], v7, s[6:7]
	s_waitcnt vmcnt(45)
; __device__ __forceinline__ unsigned cvt_pk(float lo, float hi) { unsigned r; asm("v_cvt_pk_bf16_f32 %0, %1, %2" : "=v"(r) : "v"(lo), "v"(hi)); return r; }
; __device__ __forceinline__ float bflo(unsigned w) { return __uint_as_float(w << 16); }
; __device__ __forceinline__ float bfhi(unsigned w) { return __uint_as_float(w & 0xffff0000u); }
; __device__ __forceinline__ void rnn_combine(const Params& p) {
;     ...
;         for (int k = 0; k < 4; ++k) { const int rr = r0 + k * NW;
;             float y[8]; float q = 0.f;
; #pragma unroll
;             for (int i = 0; i < 4; ++i) { const unsigned a = hf[k][i], c = hb[k][i], gg = gw[k][i];
; #pragma unroll
;                 for (int e = 0; e < 2; ++e) { const float hs = (e ? bfhi(a) : bflo(a)) + (e ? bfhi(c) : bflo(c)); const float gt = e ? bfhi(gg) : bflo(gg);
;                     const float u = 0.7978845608028654f * (gt + 0.044715f * gt * gt * gt); const float th = 1.0f - 2.0f * __builtin_amdgcn_rcpf(1.0f + __builtin_amdgcn_exp2f(2.8853900817779268f * u));
;                     const float yv = hs * (0.5f * gt * (1.0f + th)); y[2 * i + e] = yv; q += yv * yv; } }
;             q = wave_sum(q);
;             if (rr < MR) { u32x4 w; w.x = cvt_pk(y[0], y[1]); w.y = cvt_pk(y[2], y[3]); w.z = cvt_pk(y[4], y[5]); w.w = cvt_pk(y[6], y[7]);
	v_lshlrev_b32_e32 v8, 16, v40
	v_and_b32_e32 v9, 0xffff0000, v40
	v_lshlrev_b32_e32 v10, 16, v41
	v_and_b32_e32 v11, 0xffff0000, v41
	v_lshlrev_b32_e32 v12, 16, v42
	v_and_b32_e32 v13, 0xffff0000, v42
	v_lshlrev_b32_e32 v14, 16, v43
	v_and_b32_e32 v15, 0xffff0000, v43
	v_mul_f32_e32 v16, 0x3d372713, v8
	v_mul_f32_e32 v17, 0x3d372713, v9
	v_mul_f32_e32 v18, 0x3d372713, v10
	v_mul_f32_e32 v19, 0x3d372713, v11
	v_mul_f32_e32 v20, 0x3d372713, v12
	v_mul_f32_e32 v21, 0x3d372713, v13
	v_mul_f32_e32 v22, 0x3d372713, v14
	v_mul_f32_e32 v23, 0x3d372713, v15
	v_mul_f32_e32 v16, v16, v8
	v_mul_f32_e32 v17, v17, v9
	v_mul_f32_e32 v18, v18, v10
	v_mul_f32_e32 v19, v19, v11
	v_mul_f32_e32 v20, v20, v12
	v_mul_f32_e32 v21, v21, v13
	v_mul_f32_e32 v22, v22, v14
	v_mul_f32_e32 v23, v23, v15
	v_fma_f32 v16, v16, v8, v8
	v_fma_f32 v17, v17, v9, v9
	v_fma_f32 v18, v18, v10, v10
	v_fma_f32 v19, v19, v11, v11
	v_fma_f32 v20, v20, v12, v12
	v_fma_f32 v21, v21, v13, v13
	v_fma_f32 v22, v22, v14, v14
	v_fma_f32 v23, v23, v15, v15
	v_mul_f32_e32 v16, 0x3f4c422a, v16
	v_mul_f32_e32 v17, 0x3f4c422a, v17
	v_mul_f32_e32 v18, 0x3f4c422a, v18
	v_mul_f32_e32 v19, 0x3f4c422a, v19
	v_mul_f32_e32 v20, 0x3f4c422a, v20
	v_mul_f32_e32 v21, 0x3f4c422a, v21
	v_mul_f32_e32 v22, 0x3f4c422a, v22
	v_mul_f32_e32 v23, 0x3f4c422a, v23
	v_mul_f32_e32 v16, 0x4038aa3b, v16
	v_mul_f32_e32 v17, 0x4038aa3b, v17
	v_mul_f32_e32 v18, 0x4038aa3b, v18
	v_mul_f32_e32 v19, 0x4038aa3b, v19
	v_mul_f32_e32 v20, 0x4038aa3b, v20
	v_mul_f32_e32 v21, 0x4038aa3b, v21
	v_mul_f32_e32 v22, 0x4038aa3b, v22
	v_mul_f32_e32 v23, 0x4038aa3b, v23
	v_exp_f32_e32 v16, v16
	v_exp_f32_e32 v17, v17
	v_exp_f32_e32 v18, v18
	v_exp_f32_e32 v19, v19
	v_exp_f32_e32 v20, v20
	v_exp_f32_e32 v21, v21
	v_exp_f32_e32 v22, v22
	v_exp_f32_e32 v23, v23
	v_lshlrev_b32_e32 v24, 16, v32
	v_and_b32_e32 v25, 0xffff0000, v32
	v_lshlrev_b32_e32 v26, 16, v33
	v_and_b32_e32 v27, 0xffff0000, v33
	v_lshlrev_b32_e32 v28, 16, v34
	v_and_b32_e32 v29, 0xffff0000, v34
	v_lshlrev_b32_e32 v30, 16, v35
	v_and_b32_e32 v31, 0xffff0000, v35
	v_add_f32_e32 v16, 1.0, v16
	v_add_f32_e32 v17, 1.0, v17
	v_add_f32_e32 v18, 1.0, v18
	v_add_f32_e32 v19, 1.0, v19
	v_add_f32_e32 v20, 1.0, v20
	v_add_f32_e32 v21, 1.0, v21
	v_add_f32_e32 v22, 1.0, v22
	v_add_f32_e32 v23, 1.0, v23
	v_rcp_f32_e32 v16, v16
	v_rcp_f32_e32 v17, v17
	v_rcp_f32_e32 v18, v18
	v_rcp_f32_e32 v19, v19
	v_rcp_f32_e32 v20, v20
	v_rcp_f32_e32 v21, v21
	v_rcp_f32_e32 v22, v22
	v_rcp_f32_e32 v23, v23
	v_lshlrev_b32_e32 v32, 16, v36
	v_and_b32_e32 v36, 0xffff0000, v36
	v_lshlrev_b32_e32 v33, 16, v37
	v_and_b32_e32 v37, 0xffff0000, v37
	v_lshlrev_b32_e32 v34, 16, v38
	v_and_b32_e32 v38, 0xffff0000, v38
	v_lshlrev_b32_e32 v35, 16, v39
	v_and_b32_e32 v39, 0xffff0000, v39
	v_add_f32_e32 v24, v32, v24
	v_add_f32_e32 v25, v36, v25
	v_add_f32_e32 v26, v33, v26
	v_add_f32_e32 v27, v37, v27
	v_add_f32_e32 v28, v34, v28
	v_add_f32_e32 v29, v38, v29
	v_add_f32_e32 v30, v35, v30
	v_add_f32_e32 v31, v39, v31
	v_fma_f32 v16, v16, -2.0, 1.0
	v_fma_f32 v17, v17, -2.0, 1.0
	v_fma_f32 v18, v18, -2.0, 1.0
	v_fma_f32 v19, v19, -2.0, 1.0
	v_fma_f32 v20, v20, -2.0, 1.0
	v_fma_f32 v21, v21, -2.0, 1.0
	v_fma_f32 v22, v22, -2.0, 1.0
	v_fma_f32 v23, v23, -2.0, 1.0
	v_mul_f32_e32 v8, 0.5, v8
	v_mul_f32_e32 v9, 0.5, v9
	v_mul_f32_e32 v10, 0.5, v10
	v_mul_f32_e32 v11, 0.5, v11
	v_mul_f32_e32 v12, 0.5, v12
	v_mul_f32_e32 v13, 0.5, v13
	v_mul_f32_e32 v14, 0.5, v14
	v_mul_f32_e32 v15, 0.5, v15
	v_add_f32_e32 v16, 1.0, v16
	v_add_f32_e32 v17, 1.0, v17
	v_add_f32_e32 v18, 1.0, v18
	v_add_f32_e32 v19, 1.0, v19
	v_add_f32_e32 v20, 1.0, v20
	v_add_f32_e32 v21, 1.0, v21
	v_add_f32_e32 v22, 1.0, v22
	v_add_f32_e32 v23, 1.0, v23
	v_mul_f32_e32 v8, v8, v16
	v_mul_f32_e32 v9, v9, v17
	v_mul_f32_e32 v10, v10, v18
	v_mul_f32_e32 v11, v11, v19
	v_mul_f32_e32 v12, v12, v20
	v_mul_f32_e32 v13, v13, v21
	v_mul_f32_e32 v14, v14, v22
	v_mul_f32_e32 v15, v15, v23
	v_mul_f32_e32 v24, v24, v8
	v_mul_f32_e32 v25, v25, v9
	v_mul_f32_e32 v26, v26, v10
	v_mul_f32_e32 v27, v27, v11
	v_mul_f32_e32 v28, v28, v12
	v_mul_f32_e32 v29, v29, v13
	v_mul_f32_e32 v30, v30, v14
	v_mul_f32_e32 v31, v31, v15
	v_mul_f32_e32 v36, v25, v25
	v_cvt_pk_bf16_f32 v32, v24, v25
	v_fmac_f32_e32 v36, v24, v24
	v_cvt_pk_bf16_f32 v33, v26, v27
	v_fmac_f32_e32 v36, v26, v26
	v_cvt_pk_bf16_f32 v34, v28, v29
	v_fmac_f32_e32 v36, v27, v27
	v_cvt_pk_bf16_f32 v35, v30, v31
	v_fmac_f32_e32 v36, v28, v28
	v_fmac_f32_e32 v36, v29, v29
	v_fmac_f32_e32 v36, v30, v30
	v_fmac_f32_e32 v36, v31, v31
	s_waitcnt vmcnt(42)
; __device__ __forceinline__ unsigned cvt_pk(float lo, float hi) { unsigned r; asm("v_cvt_pk_bf16_f32 %0, %1, %2" : "=v"(r) : "v"(lo), "v"(hi)); return r; }
; __device__ __forceinline__ float bflo(unsigned w) { return __uint_as_float(w << 16); }
; __device__ __forceinline__ float bfhi(unsigned w) { return __uint_as_float(w & 0xffff0000u); }
; __device__ __forceinline__ void rnn_combine(const Params& p) {
;     ...
;         for (int k = 0; k < 4; ++k) { const int rr = r0 + k * NW;
;             float y[8]; float q = 0.f;
; #pragma unroll
;             for (int i = 0; i < 4; ++i) { const unsigned a = hf[k][i], c = hb[k][i], gg = gw[k][i];
; #pragma unroll
;                 for (int e = 0; e < 2; ++e) { const float hs = (e ? bfhi(a) : bflo(a)) + (e ? bfhi(c) : bflo(c)); const float gt = e ? bfhi(gg) : bflo(gg);
;                     const float u = 0.7978845608028654f * (gt + 0.044715f * gt * gt * gt); const float th = 1.0f - 2.0f * __builtin_amdgcn_rcpf(1.0f + __builtin_amdgcn_exp2f(2.8853900817779268f * u));
;                     const float yv = hs * (0.5f * gt * (1.0f + th)); y[2 * i + e] = yv; q += yv * yv; } }
;             q = wave_sum(q);
;             if (rr < MR) { u32x4 w; w.x = cvt_pk(y[0], y[1]); w.y = cvt_pk(y[2], y[3]); w.z = cvt_pk(y[4], y[5]); w.w = cvt_pk(y[6], y[7]);
	v_lshlrev_b32_e32 v8, 16, v52
	v_and_b32_e32 v9, 0xffff0000, v52
	v_lshlrev_b32_e32 v10, 16, v53
	v_and_b32_e32 v11, 0xffff0000, v53
	v_lshlrev_b32_e32 v12, 16, v54
	v_and_b32_e32 v13, 0xffff0000, v54
	v_lshlrev_b32_e32 v14, 16, v55
	v_and_b32_e32 v15, 0xffff0000, v55
	v_mul_f32_e32 v16, 0x3d372713, v8
	v_mul_f32_e32 v17, 0x3d372713, v9
	v_mul_f32_e32 v18, 0x3d372713, v10
	v_mul_f32_e32 v19, 0x3d372713, v11
	v_mul_f32_e32 v20, 0x3d372713, v12
	v_mul_f32_e32 v21, 0x3d372713, v13
	v_mul_f32_e32 v22, 0x3d372713, v14
	v_mul_f32_e32 v23, 0x3d372713, v15
	v_mul_f32_e32 v16, v16, v8
	v_mul_f32_e32 v17, v17, v9
	v_mul_f32_e32 v18, v18, v10
	v_mul_f32_e32 v19, v19, v11
	v_mul_f32_e32 v20, v20, v12
	v_mul_f32_e32 v21, v21, v13
	v_mul_f32_e32 v22, v22, v14
	v_mul_f32_e32 v23, v23, v15
	v_fma_f32 v16, v16, v8, v8
	v_fma_f32 v17, v17, v9, v9
	v_fma_f32 v18, v18, v10, v10
	v_fma_f32 v19, v19, v11, v11
	v_fma_f32 v20, v20, v12, v12
	v_fma_f32 v21, v21, v13, v13
	v_fma_f32 v22, v22, v14, v14
	v_fma_f32 v23, v23, v15, v15
	v_mul_f32_e32 v16, 0x3f4c422a, v16
	v_mul_f32_e32 v17, 0x3f4c422a, v17
	v_mul_f32_e32 v18, 0x3f4c422a, v18
	v_mul_f32_e32 v19, 0x3f4c422a, v19
	v_mul_f32_e32 v20, 0x3f4c422a, v20
	v_mul_f32_e32 v21, 0x3f4c422a, v21
	v_mul_f32_e32 v22, 0x3f4c422a, v22
	v_mul_f32_e32 v23, 0x3f4c422a, v23
	v_mul_f32_e32 v16, 0x4038aa3b, v16
	v_mul_f32_e32 v17, 0x4038aa3b, v17
	v_mul_f32_e32 v18, 0x4038aa3b, v18
	v_mul_f32_e32 v19, 0x4038aa3b, v19
	v_mul_f32_e32 v20, 0x4038aa3b, v20
	v_mul_f32_e32 v21, 0x4038aa3b, v21
	v_mul_f32_e32 v22, 0x4038aa3b, v22
	v_mul_f32_e32 v23, 0x4038aa3b, v23
	v_exp_f32_e32 v16, v16
	v_exp_f32_e32 v17, v17
	v_exp_f32_e32 v18, v18
	v_exp_f32_e32 v19, v19
	v_exp_f32_e32 v20, v20
	v_exp_f32_e32 v21, v21
	v_exp_f32_e32 v22, v22
	v_exp_f32_e32 v23, v23
	v_lshlrev_b32_e32 v24, 16, v44
	v_and_b32_e32 v25, 0xffff0000, v44
	v_lshlrev_b32_e32 v26, 16, v45
	v_and_b32_e32 v27, 0xffff0000, v45
	v_lshlrev_b32_e32 v28, 16, v46
	v_and_b32_e32 v29, 0xffff0000, v46
	v_lshlrev_b32_e32 v30, 16, v47
	v_and_b32_e32 v31, 0xffff0000, v47
	v_add_f32_e32 v16, 1.0, v16
	v_add_f32_e32 v17, 1.0, v17
	v_add_f32_e32 v18, 1.0, v18
	v_add_f32_e32 v19, 1.0, v19
	v_add_f32_e32 v20, 1.0, v20
	v_add_f32_e32 v21, 1.0, v21
	v_add_f32_e32 v22, 1.0, v22
	v_add_f32_e32 v23, 1.0, v23
	v_rcp_f32_e32 v16, v16
	v_rcp_f32_e32 v17, v17
	v_rcp_f32_e32 v18, v18
	v_rcp_f32_e32 v19, v19
	v_rcp_f32_e32 v20, v20
	v_rcp_f32_e32 v21, v21
	v_rcp_f32_e32 v22, v22
	v_rcp_f32_e32 v23, v23
	v_lshlrev_b32_e32 v44, 16, v48
	v_and_b32_e32 v48, 0xffff0000, v48
	v_lshlrev_b32_e32 v45, 16, v49
	v_and_b32_e32 v49, 0xffff0000, v49
	v_lshlrev_b32_e32 v46, 16, v50
	v_and_b32_e32 v50, 0xffff0000, v50
	v_lshlrev_b32_e32 v47, 16, v51
	v_and_b32_e32 v51, 0xffff0000, v51
	v_add_f32_e32 v24, v44, v24
	v_add_f32_e32 v25, v48, v25
	v_add_f32_e32 v26, v45, v26
	v_add_f32_e32 v27, v49, v27
	v_add_f32_e32 v28, v46, v28
	v_add_f32_e32 v29, v50, v29
	v_add_f32_e32 v30, v47, v30
	v_add_f32_e32 v31, v51, v31
	v_fma_f32 v16, v16, -2.0, 1.0
	v_fma_f32 v17, v17, -2.0, 1.0
	v_fma_f32 v18, v18, -2.0, 1.0
	v_fma_f32 v19, v19, -2.0, 1.0
	v_fma_f32 v20, v20, -2.0, 1.0
	v_fma_f32 v21, v21, -2.0, 1.0
	v_fma_f32 v22, v22, -2.0, 1.0
	v_fma_f32 v23, v23, -2.0, 1.0
	v_mul_f32_e32 v8, 0.5, v8
	v_mul_f32_e32 v9, 0.5, v9
	v_mul_f32_e32 v10, 0.5, v10
	v_mul_f32_e32 v11, 0.5, v11
	v_mul_f32_e32 v12, 0.5, v12
	v_mul_f32_e32 v13, 0.5, v13
	v_mul_f32_e32 v14, 0.5, v14
	v_mul_f32_e32 v15, 0.5, v15
	v_add_f32_e32 v16, 1.0, v16
	v_add_f32_e32 v17, 1.0, v17
	v_add_f32_e32 v18, 1.0, v18
	v_add_f32_e32 v19, 1.0, v19
	v_add_f32_e32 v20, 1.0, v20
	v_add_f32_e32 v21, 1.0, v21
	v_add_f32_e32 v22, 1.0, v22
	v_add_f32_e32 v23, 1.0, v23
	v_mul_f32_e32 v8, v8, v16
	v_mul_f32_e32 v9, v9, v17
	v_mul_f32_e32 v10, v10, v18
	v_mul_f32_e32 v11, v11, v19
	v_mul_f32_e32 v12, v12, v20
	v_mul_f32_e32 v13, v13, v21
	v_mul_f32_e32 v14, v14, v22
	v_mul_f32_e32 v15, v15, v23
	v_mul_f32_e32 v24, v24, v8
	v_mul_f32_e32 v25, v25, v9
	v_mul_f32_e32 v26, v26, v10
	v_mul_f32_e32 v27, v27, v11
	v_mul_f32_e32 v28, v28, v12
	v_mul_f32_e32 v29, v29, v13
	v_mul_f32_e32 v30, v30, v14
	v_mul_f32_e32 v31, v31, v15
	v_mul_f32_e32 v48, v25, v25
	v_cvt_pk_bf16_f32 v44, v24, v25
	v_fmac_f32_e32 v48, v24, v24
	v_cvt_pk_bf16_f32 v45, v26, v27
	v_fmac_f32_e32 v48, v26, v26
	v_cvt_pk_bf16_f32 v46, v28, v29
	v_fmac_f32_e32 v48, v27, v27
	v_cvt_pk_bf16_f32 v47, v30, v31
	v_fmac_f32_e32 v48, v28, v28
	v_fmac_f32_e32 v48, v29, v29
	v_fmac_f32_e32 v48, v30, v30
	v_fmac_f32_e32 v48, v31, v31
	s_waitcnt vmcnt(39)
; __device__ __forceinline__ unsigned cvt_pk(float lo, float hi) { unsigned r; asm("v_cvt_pk_bf16_f32 %0, %1, %2" : "=v"(r) : "v"(lo), "v"(hi)); return r; }
; __device__ __forceinline__ float bflo(unsigned w) { return __uint_as_float(w << 16); }
; __device__ __forceinline__ float bfhi(unsigned w) { return __uint_as_float(w & 0xffff0000u); }
; __device__ __forceinline__ void rnn_combine(const Params& p) {
;     ...
;         for (int k = 0; k < 4; ++k) { const int rr = r0 + k * NW;
;             float y[8]; float q = 0.f;
; #pragma unroll
;             for (int i = 0; i < 4; ++i) { const unsigned a = hf[k][i], c = hb[k][i], gg = gw[k][i];
; #pragma unroll
;                 for (int e = 0; e < 2; ++e) { const float hs = (e ? bfhi(a) : bflo(a)) + (e ? bfhi(c) : bflo(c)); const float gt = e ? bfhi(gg) : bflo(gg);
;                     const float u = 0.7978845608028654f * (gt + 0.044715f * gt * gt * gt); const float th = 1.0f - 2.0f * __builtin_amdgcn_rcpf(1.0f + __builtin_amdgcn_exp2f(2.8853900817779268f * u));
;                     const float yv = hs * (0.5f * gt * (1.0f + th)); y[2 * i + e] = yv; q += yv * yv; } }
;             q = wave_sum(q);
;             if (rr < MR) { u32x4 w; w.x = cvt_pk(y[0], y[1]); w.y = cvt_pk(y[2], y[3]); w.z = cvt_pk(y[4], y[5]); w.w = cvt_pk(y[6], y[7]);
	v_lshlrev_b32_e32 v8, 16, v64
	v_and_b32_e32 v9, 0xffff0000, v64
	v_lshlrev_b32_e32 v10, 16, v65
	v_and_b32_e32 v11, 0xffff0000, v65
	v_lshlrev_b32_e32 v12, 16, v66
	v_and_b32_e32 v13, 0xffff0000, v66
	v_lshlrev_b32_e32 v14, 16, v67
	v_and_b32_e32 v15, 0xffff0000, v67
	v_mul_f32_e32 v16, 0x3d372713, v8
	v_mul_f32_e32 v17, 0x3d372713, v9
	v_mul_f32_e32 v18, 0x3d372713, v10
	v_mul_f32_e32 v19, 0x3d372713, v11
	v_mul_f32_e32 v20, 0x3d372713, v12
	v_mul_f32_e32 v21, 0x3d372713, v13
	v_mul_f32_e32 v22, 0x3d372713, v14
	v_mul_f32_e32 v23, 0x3d372713, v15
	v_mul_f32_e32 v16, v16, v8
	v_mul_f32_e32 v17, v17, v9
	v_mul_f32_e32 v18, v18, v10
	v_mul_f32_e32 v19, v19, v11
	v_mul_f32_e32 v20, v20, v12
	v_mul_f32_e32 v21, v21, v13
	v_mul_f32_e32 v22, v22, v14
	v_mul_f32_e32 v23, v23, v15
	v_fma_f32 v16, v16, v8, v8
	v_fma_f32 v17, v17, v9, v9
	v_fma_f32 v18, v18, v10, v10
	v_fma_f32 v19, v19, v11, v11
	v_fma_f32 v20, v20, v12, v12
	v_fma_f32 v21, v21, v13, v13
	v_fma_f32 v22, v22, v14, v14
	v_fma_f32 v23, v23, v15, v15
	v_mul_f32_e32 v16, 0x3f4c422a, v16
	v_mul_f32_e32 v17, 0x3f4c422a, v17
	v_mul_f32_e32 v18, 0x3f4c422a, v18
	v_mul_f32_e32 v19, 0x3f4c422a, v19
	v_mul_f32_e32 v20, 0x3f4c422a, v20
	v_mul_f32_e32 v21, 0x3f4c422a, v21
	v_mul_f32_e32 v22, 0x3f4c422a, v22
	v_mul_f32_e32 v23, 0x3f4c422a, v23
	v_mul_f32_e32 v16, 0x4038aa3b, v16
	v_mul_f32_e32 v17, 0x4038aa3b, v17
	v_mul_f32_e32 v18, 0x4038aa3b, v18
	v_mul_f32_e32 v19, 0x4038aa3b, v19
	v_mul_f32_e32 v20, 0x4038aa3b, v20
	v_mul_f32_e32 v21, 0x4038aa3b, v21
	v_mul_f32_e32 v22, 0x4038aa3b, v22
	v_mul_f32_e32 v23, 0x4038aa3b, v23
	v_exp_f32_e32 v16, v16
	v_exp_f32_e32 v17, v17
	v_exp_f32_e32 v18, v18
	v_exp_f32_e32 v19, v19
	v_exp_f32_e32 v20, v20
	v_exp_f32_e32 v21, v21
	v_exp_f32_e32 v22, v22
	v_exp_f32_e32 v23, v23
	v_lshlrev_b32_e32 v24, 16, v56
	v_and_b32_e32 v25, 0xffff0000, v56
	v_lshlrev_b32_e32 v26, 16, v57
	v_and_b32_e32 v27, 0xffff0000, v57
	v_lshlrev_b32_e32 v28, 16, v58
	v_and_b32_e32 v29, 0xffff0000, v58
	v_lshlrev_b32_e32 v30, 16, v59
	v_and_b32_e32 v31, 0xffff0000, v59
	v_add_f32_e32 v16, 1.0, v16
	v_add_f32_e32 v17, 1.0, v17
	v_add_f32_e32 v18, 1.0, v18
	v_add_f32_e32 v19, 1.0, v19
	v_add_f32_e32 v20, 1.0, v20
	v_add_f32_e32 v21, 1.0, v21
	v_add_f32_e32 v22, 1.0, v22
	v_add_f32_e32 v23, 1.0, v23
	v_rcp_f32_e32 v16, v16
	v_rcp_f32_e32 v17, v17
	v_rcp_f32_e32 v18, v18
	v_rcp_f32_e32 v19, v19
	v_rcp_f32_e32 v20, v20
	v_rcp_f32_e32 v21, v21
	v_rcp_f32_e32 v22, v22
	v_rcp_f32_e32 v23, v23
	v_lshlrev_b32_e32 v56, 16, v60
	v_and_b32_e32 v60, 0xffff0000, v60
	v_lshlrev_b32_e32 v57, 16, v61
	v_and_b32_e32 v61, 0xffff0000, v61
	v_lshlrev_b32_e32 v58, 16, v62
	v_and_b32_e32 v62, 0xffff0000, v62
	v_lshlrev_b32_e32 v59, 16, v63
	v_and_b32_e32 v63, 0xffff0000, v63
	v_add_f32_e32 v24, v56, v24
	v_add_f32_e32 v25, v60, v25
	v_add_f32_e32 v26, v57, v26
	v_add_f32_e32 v27, v61, v27
	v_add_f32_e32 v28, v58, v28
	v_add_f32_e32 v29, v62, v29
	v_add_f32_e32 v30, v59, v30
	v_add_f32_e32 v31, v63, v31
	v_fma_f32 v16, v16, -2.0, 1.0
	v_fma_f32 v17, v17, -2.0, 1.0
	v_fma_f32 v18, v18, -2.0, 1.0
	v_fma_f32 v19, v19, -2.0, 1.0
	v_fma_f32 v20, v20, -2.0, 1.0
	v_fma_f32 v21, v21, -2.0, 1.0
	v_fma_f32 v22, v22, -2.0, 1.0
	v_fma_f32 v23, v23, -2.0, 1.0
	v_mul_f32_e32 v8, 0.5, v8
	v_mul_f32_e32 v9, 0.5, v9
	v_mul_f32_e32 v10, 0.5, v10
	v_mul_f32_e32 v11, 0.5, v11
	v_mul_f32_e32 v12, 0.5, v12
	v_mul_f32_e32 v13, 0.5, v13
	v_mul_f32_e32 v14, 0.5, v14
	v_mul_f32_e32 v15, 0.5, v15
	v_add_f32_e32 v16, 1.0, v16
	v_add_f32_e32 v17, 1.0, v17
	v_add_f32_e32 v18, 1.0, v18
	v_add_f32_e32 v19, 1.0, v19
	v_add_f32_e32 v20, 1.0, v20
	v_add_f32_e32 v21, 1.0, v21
	v_add_f32_e32 v22, 1.0, v22
	v_add_f32_e32 v23, 1.0, v23
	v_mul_f32_e32 v8, v8, v16
	v_mul_f32_e32 v9, v9, v17
	v_mul_f32_e32 v10, v10, v18
	v_mul_f32_e32 v11, v11, v19
	v_mul_f32_e32 v12, v12, v20
	v_mul_f32_e32 v13, v13, v21
	v_mul_f32_e32 v14, v14, v22
	v_mul_f32_e32 v15, v15, v23
	v_mul_f32_e32 v24, v24, v8
	v_mul_f32_e32 v25, v25, v9
	v_mul_f32_e32 v26, v26, v10
	v_mul_f32_e32 v27, v27, v11
	v_mul_f32_e32 v28, v28, v12
	v_mul_f32_e32 v29, v29, v13
	v_mul_f32_e32 v30, v30, v14
	v_mul_f32_e32 v31, v31, v15
	v_mul_f32_e32 v60, v25, v25
	v_cvt_pk_bf16_f32 v56, v24, v25
	v_fmac_f32_e32 v60, v24, v24
	v_cvt_pk_bf16_f32 v57, v26, v27
	v_fmac_f32_e32 v60, v26, v26
	v_cvt_pk_bf16_f32 v58, v28, v29
	v_fmac_f32_e32 v60, v27, v27
	v_cvt_pk_bf16_f32 v59, v30, v31
	v_fmac_f32_e32 v60, v28, v28
	v_fmac_f32_e32 v60, v29, v29
	v_fmac_f32_e32 v60, v30, v30
	v_fmac_f32_e32 v60, v31, v31
	s_waitcnt vmcnt(36)
; __device__ __forceinline__ unsigned cvt_pk(float lo, float hi) { unsigned r; asm("v_cvt_pk_bf16_f32 %0, %1, %2" : "=v"(r) : "v"(lo), "v"(hi)); return r; }
; __device__ __forceinline__ float bflo(unsigned w) { return __uint_as_float(w << 16); }
; __device__ __forceinline__ float bfhi(unsigned w) { return __uint_as_float(w & 0xffff0000u); }
; __device__ __forceinline__ void rnn_combine(const Params& p) {
;     ...
;         for (int k = 0; k < 4; ++k) { const int rr = r0 + k * NW;
;             float y[8]; float q = 0.f;
; #pragma unroll
;             for (int i = 0; i < 4; ++i) { const unsigned a = hf[k][i], c = hb[k][i], gg = gw[k][i];
; #pragma unroll
;                 for (int e = 0; e < 2; ++e) { const float hs = (e ? bfhi(a) : bflo(a)) + (e ? bfhi(c) : bflo(c)); const float gt = e ? bfhi(gg) : bflo(gg);
;                     const float u = 0.7978845608028654f * (gt + 0.044715f * gt * gt * gt); const float th = 1.0f - 2.0f * __builtin_amdgcn_rcpf(1.0f + __builtin_amdgcn_exp2f(2.8853900817779268f * u));
;                     const float yv = hs * (0.5f * gt * (1.0f + th)); y[2 * i + e] = yv; q += yv * yv; } }
;             q = wave_sum(q);
;             if (rr < MR) { u32x4 w; w.x = cvt_pk(y[0], y[1]); w.y = cvt_pk(y[2], y[3]); w.z = cvt_pk(y[4], y[5]); w.w = cvt_pk(y[6], y[7]);
	v_lshlrev_b32_e32 v8, 16, v76
	v_and_b32_e32 v9, 0xffff0000, v76
	v_lshlrev_b32_e32 v10, 16, v77
	v_and_b32_e32 v11, 0xffff0000, v77
	v_lshlrev_b32_e32 v12, 16, v78
	v_and_b32_e32 v13, 0xffff0000, v78
	v_lshlrev_b32_e32 v14, 16, v79
	v_and_b32_e32 v15, 0xffff0000, v79
	v_mul_f32_e32 v16, 0x3d372713, v8
	v_mul_f32_e32 v17, 0x3d372713, v9
	v_mul_f32_e32 v18, 0x3d372713, v10
	v_mul_f32_e32 v19, 0x3d372713, v11
	v_mul_f32_e32 v20, 0x3d372713, v12
	v_mul_f32_e32 v21, 0x3d372713, v13
	v_mul_f32_e32 v22, 0x3d372713, v14
	v_mul_f32_e32 v23, 0x3d372713, v15
	v_mul_f32_e32 v16, v16, v8
	v_mul_f32_e32 v17, v17, v9
	v_mul_f32_e32 v18, v18, v10
	v_mul_f32_e32 v19, v19, v11
	v_mul_f32_e32 v20, v20, v12
	v_mul_f32_e32 v21, v21, v13
	v_mul_f32_e32 v22, v22, v14
	v_mul_f32_e32 v23, v23, v15
	v_fma_f32 v16, v16, v8, v8
	v_fma_f32 v17, v17, v9, v9
	v_fma_f32 v18, v18, v10, v10
	v_fma_f32 v19, v19, v11, v11
	v_fma_f32 v20, v20, v12, v12
	v_fma_f32 v21, v21, v13, v13
	v_fma_f32 v22, v22, v14, v14
	v_fma_f32 v23, v23, v15, v15
	v_mul_f32_e32 v16, 0x3f4c422a, v16
	v_mul_f32_e32 v17, 0x3f4c422a, v17
	v_mul_f32_e32 v18, 0x3f4c422a, v18
	v_mul_f32_e32 v19, 0x3f4c422a, v19
	v_mul_f32_e32 v20, 0x3f4c422a, v20
	v_mul_f32_e32 v21, 0x3f4c422a, v21
	v_mul_f32_e32 v22, 0x3f4c422a, v22
	v_mul_f32_e32 v23, 0x3f4c422a, v23
	v_mul_f32_e32 v16, 0x4038aa3b, v16
	v_mul_f32_e32 v17, 0x4038aa3b, v17
	v_mul_f32_e32 v18, 0x4038aa3b, v18
	v_mul_f32_e32 v19, 0x4038aa3b, v19
	v_mul_f32_e32 v20, 0x4038aa3b, v20
	v_mul_f32_e32 v21, 0x4038aa3b, v21
	v_mul_f32_e32 v22, 0x4038aa3b, v22
	v_mul_f32_e32 v23, 0x4038aa3b, v23
	v_exp_f32_e32 v16, v16
	v_exp_f32_e32 v17, v17
	v_exp_f32_e32 v18, v18
	v_exp_f32_e32 v19, v19
	v_exp_f32_e32 v20, v20
	v_exp_f32_e32 v21, v21
	v_exp_f32_e32 v22, v22
	v_exp_f32_e32 v23, v23
	v_lshlrev_b32_e32 v24, 16, v68
	v_and_b32_e32 v25, 0xffff0000, v68
	v_lshlrev_b32_e32 v26, 16, v69
	v_and_b32_e32 v27, 0xffff0000, v69
	v_lshlrev_b32_e32 v28, 16, v70
	v_and_b32_e32 v29, 0xffff0000, v70
	v_lshlrev_b32_e32 v30, 16, v71
	v_and_b32_e32 v31, 0xffff0000, v71
	v_add_f32_e32 v16, 1.0, v16
	v_add_f32_e32 v17, 1.0, v17
	v_add_f32_e32 v18, 1.0, v18
	v_add_f32_e32 v19, 1.0, v19
	v_add_f32_e32 v20, 1.0, v20
	v_add_f32_e32 v21, 1.0, v21
	v_add_f32_e32 v22, 1.0, v22
	v_add_f32_e32 v23, 1.0, v23
	v_rcp_f32_e32 v16, v16
	v_rcp_f32_e32 v17, v17
	v_rcp_f32_e32 v18, v18
	v_rcp_f32_e32 v19, v19
	v_rcp_f32_e32 v20, v20
	v_rcp_f32_e32 v21, v21
	v_rcp_f32_e32 v22, v22
	v_rcp_f32_e32 v23, v23
	v_lshlrev_b32_e32 v68, 16, v72
	v_and_b32_e32 v72, 0xffff0000, v72
	v_lshlrev_b32_e32 v69, 16, v73
	v_and_b32_e32 v73, 0xffff0000, v73
	v_lshlrev_b32_e32 v70, 16, v74
	v_and_b32_e32 v74, 0xffff0000, v74
	v_lshlrev_b32_e32 v71, 16, v75
	v_and_b32_e32 v75, 0xffff0000, v75
	v_add_f32_e32 v24, v68, v24
	v_add_f32_e32 v25, v72, v25
	v_add_f32_e32 v26, v69, v26
	v_add_f32_e32 v27, v73, v27
	v_add_f32_e32 v28, v70, v28
	v_add_f32_e32 v29, v74, v29
	v_add_f32_e32 v30, v71, v30
	v_add_f32_e32 v31, v75, v31
	v_fma_f32 v16, v16, -2.0, 1.0
	v_fma_f32 v17, v17, -2.0, 1.0
	v_fma_f32 v18, v18, -2.0, 1.0
	v_fma_f32 v19, v19, -2.0, 1.0
	v_fma_f32 v20, v20, -2.0, 1.0
	v_fma_f32 v21, v21, -2.0, 1.0
	v_fma_f32 v22, v22, -2.0, 1.0
	v_fma_f32 v23, v23, -2.0, 1.0
	v_mul_f32_e32 v8, 0.5, v8
	v_mul_f32_e32 v9, 0.5, v9
	v_mul_f32_e32 v10, 0.5, v10
	v_mul_f32_e32 v11, 0.5, v11
	v_mul_f32_e32 v12, 0.5, v12
	v_mul_f32_e32 v13, 0.5, v13
	v_mul_f32_e32 v14, 0.5, v14
	v_mul_f32_e32 v15, 0.5, v15
	v_add_f32_e32 v16, 1.0, v16
	v_add_f32_e32 v17, 1.0, v17
	v_add_f32_e32 v18, 1.0, v18
	v_add_f32_e32 v19, 1.0, v19
	v_add_f32_e32 v20, 1.0, v20
	v_add_f32_e32 v21, 1.0, v21
	v_add_f32_e32 v22, 1.0, v22
	v_add_f32_e32 v23, 1.0, v23
	v_mul_f32_e32 v8, v8, v16
	v_mul_f32_e32 v9, v9, v17
	v_mul_f32_e32 v10, v10, v18
	v_mul_f32_e32 v11, v11, v19
	v_mul_f32_e32 v12, v12, v20
	v_mul_f32_e32 v13, v13, v21
	v_mul_f32_e32 v14, v14, v22
	v_mul_f32_e32 v15, v15, v23
	v_mul_f32_e32 v24, v24, v8
	v_mul_f32_e32 v25, v25, v9
	v_mul_f32_e32 v26, v26, v10
	v_mul_f32_e32 v27, v27, v11
	v_mul_f32_e32 v28, v28, v12
	v_mul_f32_e32 v29, v29, v13
	v_mul_f32_e32 v30, v30, v14
	v_mul_f32_e32 v31, v31, v15
	v_mul_f32_e32 v72, v25, v25
	v_cvt_pk_bf16_f32 v68, v24, v25
	v_fmac_f32_e32 v72, v24, v24
	v_cvt_pk_bf16_f32 v69, v26, v27
	v_fmac_f32_e32 v72, v26, v26
	v_cvt_pk_bf16_f32 v70, v28, v29
	v_fmac_f32_e32 v72, v27, v27
	v_cvt_pk_bf16_f32 v71, v30, v31
	v_fmac_f32_e32 v72, v28, v28
	v_fmac_f32_e32 v72, v29, v29
	v_fmac_f32_e32 v72, v30, v30
	v_fmac_f32_e32 v72, v31, v31
	s_waitcnt vmcnt(33)
; __device__ __forceinline__ unsigned cvt_pk(float lo, float hi) { unsigned r; asm("v_cvt_pk_bf16_f32 %0, %1, %2" : "=v"(r) : "v"(lo), "v"(hi)); return r; }
; __device__ __forceinline__ float bflo(unsigned w) { return __uint_as_float(w << 16); }
; __device__ __forceinline__ float bfhi(unsigned w) { return __uint_as_float(w & 0xffff0000u); }
; __device__ __forceinline__ void rnn_combine(const Params& p) {
;     ...
;         for (int k = 0; k < 4; ++k) { const int rr = r0 + k * NW;
;             float y[8]; float q = 0.f;
; #pragma unroll
;             for (int i = 0; i < 4; ++i) { const unsigned a = hf[k][i], c = hb[k][i], gg = gw[k][i];
; #pragma unroll
;                 for (int e = 0; e < 2; ++e) { const float hs = (e ? bfhi(a) : bflo(a)) + (e ? bfhi(c) : bflo(c)); const float gt = e ? bfhi(gg) : bflo(gg);
;                     const float u = 0.7978845608028654f * (gt + 0.044715f * gt * gt * gt); const float th = 1.0f - 2.0f * __builtin_amdgcn_rcpf(1.0f + __builtin_amdgcn_exp2f(2.8853900817779268f * u));
;                     const float yv = hs * (0.5f * gt * (1.0f + th)); y[2 * i + e] = yv; q += yv * yv; } }
;             q = wave_sum(q);
;             if (rr < MR) { u32x4 w; w.x = cvt_pk(y[0], y[1]); w.y = cvt_pk(y[2], y[3]); w.z = cvt_pk(y[4], y[5]); w.w = cvt_pk(y[6], y[7]);
	v_lshlrev_b32_e32 v8, 16, v88
	v_and_b32_e32 v9, 0xffff0000, v88
	v_lshlrev_b32_e32 v10, 16, v89
	v_and_b32_e32 v11, 0xffff0000, v89
	v_lshlrev_b32_e32 v12, 16, v90
	v_and_b32_e32 v13, 0xffff0000, v90
	v_lshlrev_b32_e32 v14, 16, v91
	v_and_b32_e32 v15, 0xffff0000, v91
	v_mul_f32_e32 v16, 0x3d372713, v8
	v_mul_f32_e32 v17, 0x3d372713, v9
	v_mul_f32_e32 v18, 0x3d372713, v10
	v_mul_f32_e32 v19, 0x3d372713, v11
	v_mul_f32_e32 v20, 0x3d372713, v12
	v_mul_f32_e32 v21, 0x3d372713, v13
	v_mul_f32_e32 v22, 0x3d372713, v14
	v_mul_f32_e32 v23, 0x3d372713, v15
	v_mul_f32_e32 v16, v16, v8
	v_mul_f32_e32 v17, v17, v9
	v_mul_f32_e32 v18, v18, v10
	v_mul_f32_e32 v19, v19, v11
	v_mul_f32_e32 v20, v20, v12
	v_mul_f32_e32 v21, v21, v13
	v_mul_f32_e32 v22, v22, v14
	v_mul_f32_e32 v23, v23, v15
	v_fma_f32 v16, v16, v8, v8
	v_fma_f32 v17, v17, v9, v9
	v_fma_f32 v18, v18, v10, v10
	v_fma_f32 v19, v19, v11, v11
	v_fma_f32 v20, v20, v12, v12
	v_fma_f32 v21, v21, v13, v13
	v_fma_f32 v22, v22, v14, v14
	v_fma_f32 v23, v23, v15, v15
	v_mul_f32_e32 v16, 0x3f4c422a, v16
	v_mul_f32_e32 v17, 0x3f4c422a, v17
	v_mul_f32_e32 v18, 0x3f4c422a, v18
	v_mul_f32_e32 v19, 0x3f4c422a, v19
	v_mul_f32_e32 v20, 0x3f4c422a, v20
	v_mul_f32_e32 v21, 0x3f4c422a, v21
	v_mul_f32_e32 v22, 0x3f4c422a, v22
	v_mul_f32_e32 v23, 0x3f4c422a, v23
	v_mul_f32_e32 v16, 0x4038aa3b, v16
	v_mul_f32_e32 v17, 0x4038aa3b, v17
	v_mul_f32_e32 v18, 0x4038aa3b, v18
	v_mul_f32_e32 v19, 0x4038aa3b, v19
	v_mul_f32_e32 v20, 0x4038aa3b, v20
	v_mul_f32_e32 v21, 0x4038aa3b, v21
	v_mul_f32_e32 v22, 0x4038aa3b, v22
	v_mul_f32_e32 v23, 0x4038aa3b, v23
	v_exp_f32_e32 v16, v16
	v_exp_f32_e32 v17, v17
	v_exp_f32_e32 v18, v18
	v_exp_f32_e32 v19, v19
	v_exp_f32_e32 v20, v20
	v_exp_f32_e32 v21, v21
	v_exp_f32_e32 v22, v22
	v_exp_f32_e32 v23, v23
	v_lshlrev_b32_e32 v24, 16, v80
	v_and_b32_e32 v25, 0xffff0000, v80
	v_lshlrev_b32_e32 v26, 16, v81
	v_and_b32_e32 v27, 0xffff0000, v81
	v_lshlrev_b32_e32 v28, 16, v82
	v_and_b32_e32 v29, 0xffff0000, v82
	v_lshlrev_b32_e32 v30, 16, v83
	v_and_b32_e32 v31, 0xffff0000, v83
	v_add_f32_e32 v16, 1.0, v16
	v_add_f32_e32 v17, 1.0, v17
	v_add_f32_e32 v18, 1.0, v18
	v_add_f32_e32 v19, 1.0, v19
	v_add_f32_e32 v20, 1.0, v20
	v_add_f32_e32 v21, 1.0, v21
	v_add_f32_e32 v22, 1.0, v22
	v_add_f32_e32 v23, 1.0, v23
	v_rcp_f32_e32 v16, v16
	v_rcp_f32_e32 v17, v17
	v_rcp_f32_e32 v18, v18
	v_rcp_f32_e32 v19, v19
	v_rcp_f32_e32 v20, v20
	v_rcp_f32_e32 v21, v21
	v_rcp_f32_e32 v22, v22
	v_rcp_f32_e32 v23, v23
	v_lshlrev_b32_e32 v80, 16, v84
	v_and_b32_e32 v84, 0xffff0000, v84
	v_lshlrev_b32_e32 v81, 16, v85
	v_and_b32_e32 v85, 0xffff0000, v85
	v_lshlrev_b32_e32 v82, 16, v86
	v_and_b32_e32 v86, 0xffff0000, v86
	v_lshlrev_b32_e32 v83, 16, v87
	v_and_b32_e32 v87, 0xffff0000, v87
	v_add_f32_e32 v24, v80, v24
	v_add_f32_e32 v25, v84, v25
	v_add_f32_e32 v26, v81, v26
	v_add_f32_e32 v27, v85, v27
	v_add_f32_e32 v28, v82, v28
	v_add_f32_e32 v29, v86, v29
	v_add_f32_e32 v30, v83, v30
	v_add_f32_e32 v31, v87, v31
	v_fma_f32 v16, v16, -2.0, 1.0
	v_fma_f32 v17, v17, -2.0, 1.0
	v_fma_f32 v18, v18, -2.0, 1.0
	v_fma_f32 v19, v19, -2.0, 1.0
	v_fma_f32 v20, v20, -2.0, 1.0
	v_fma_f32 v21, v21, -2.0, 1.0
	v_fma_f32 v22, v22, -2.0, 1.0
	v_fma_f32 v23, v23, -2.0, 1.0
	v_mul_f32_e32 v8, 0.5, v8
	v_mul_f32_e32 v9, 0.5, v9
	v_mul_f32_e32 v10, 0.5, v10
	v_mul_f32_e32 v11, 0.5, v11
	v_mul_f32_e32 v12, 0.5, v12
	v_mul_f32_e32 v13, 0.5, v13
	v_mul_f32_e32 v14, 0.5, v14
	v_mul_f32_e32 v15, 0.5, v15
	v_add_f32_e32 v16, 1.0, v16
	v_add_f32_e32 v17, 1.0, v17
	v_add_f32_e32 v18, 1.0, v18
	v_add_f32_e32 v19, 1.0, v19
	v_add_f32_e32 v20, 1.0, v20
	v_add_f32_e32 v21, 1.0, v21
	v_add_f32_e32 v22, 1.0, v22
	v_add_f32_e32 v23, 1.0, v23
	v_mul_f32_e32 v8, v8, v16
	v_mul_f32_e32 v9, v9, v17
	v_mul_f32_e32 v10, v10, v18
	v_mul_f32_e32 v11, v11, v19
	v_mul_f32_e32 v12, v12, v20
	v_mul_f32_e32 v13, v13, v21
	v_mul_f32_e32 v14, v14, v22
	v_mul_f32_e32 v15, v15, v23
	v_mul_f32_e32 v24, v24, v8
	v_mul_f32_e32 v25, v25, v9
	v_mul_f32_e32 v26, v26, v10
	v_mul_f32_e32 v27, v27, v11
	v_mul_f32_e32 v28, v28, v12
	v_mul_f32_e32 v29, v29, v13
	v_mul_f32_e32 v30, v30, v14
	v_mul_f32_e32 v31, v31, v15
	v_mul_f32_e32 v84, v25, v25
	v_cvt_pk_bf16_f32 v80, v24, v25
	v_fmac_f32_e32 v84, v24, v24
	v_cvt_pk_bf16_f32 v81, v26, v27
	v_fmac_f32_e32 v84, v26, v26
	v_cvt_pk_bf16_f32 v82, v28, v29
	v_fmac_f32_e32 v84, v27, v27
	v_cvt_pk_bf16_f32 v83, v30, v31
	v_fmac_f32_e32 v84, v28, v28
	v_fmac_f32_e32 v84, v29, v29
	v_fmac_f32_e32 v84, v30, v30
	v_fmac_f32_e32 v84, v31, v31
	s_waitcnt vmcnt(30)
; __device__ __forceinline__ unsigned cvt_pk(float lo, float hi) { unsigned r; asm("v_cvt_pk_bf16_f32 %0, %1, %2" : "=v"(r) : "v"(lo), "v"(hi)); return r; }
; __device__ __forceinline__ float bflo(unsigned w) { return __uint_as_float(w << 16); }
; __device__ __forceinline__ float bfhi(unsigned w) { return __uint_as_float(w & 0xffff0000u); }
; __device__ __forceinline__ void rnn_combine(const Params& p) {
;     ...
;         for (int k = 0; k < 4; ++k) { const int rr = r0 + k * NW;
;             float y[8]; float q = 0.f;
; #pragma unroll
;             for (int i = 0; i < 4; ++i) { const unsigned a = hf[k][i], c = hb[k][i], gg = gw[k][i];
; #pragma unroll
;                 for (int e = 0; e < 2; ++e) { const float hs = (e ? bfhi(a) : bflo(a)) + (e ? bfhi(c) : bflo(c)); const float gt = e ? bfhi(gg) : bflo(gg);
;                     const float u = 0.7978845608028654f * (gt + 0.044715f * gt * gt * gt); const float th = 1.0f - 2.0f * __builtin_amdgcn_rcpf(1.0f + __builtin_amdgcn_exp2f(2.8853900817779268f * u));
;                     const float yv = hs * (0.5f * gt * (1.0f + th)); y[2 * i + e] = yv; q += yv * yv; } }
;             q = wave_sum(q);
;             if (rr < MR) { u32x4 w; w.x = cvt_pk(y[0], y[1]); w.y = cvt_pk(y[2], y[3]); w.z = cvt_pk(y[4], y[5]); w.w = cvt_pk(y[6], y[7]);
	v_lshlrev_b32_e32 v8, 16, v100
	v_and_b32_e32 v9, 0xffff0000, v100
	v_lshlrev_b32_e32 v10, 16, v101
	v_and_b32_e32 v11, 0xffff0000, v101
	v_lshlrev_b32_e32 v12, 16, v102
	v_and_b32_e32 v13, 0xffff0000, v102
	v_lshlrev_b32_e32 v14, 16, v103
	v_and_b32_e32 v15, 0xffff0000, v103
	v_mul_f32_e32 v16, 0x3d372713, v8
	v_mul_f32_e32 v17, 0x3d372713, v9
	v_mul_f32_e32 v18, 0x3d372713, v10
	v_mul_f32_e32 v19, 0x3d372713, v11
	v_mul_f32_e32 v20, 0x3d372713, v12
	v_mul_f32_e32 v21, 0x3d372713, v13
	v_mul_f32_e32 v22, 0x3d372713, v14
	v_mul_f32_e32 v23, 0x3d372713, v15
	v_mul_f32_e32 v16, v16, v8
	v_mul_f32_e32 v17, v17, v9
	v_mul_f32_e32 v18, v18, v10
	v_mul_f32_e32 v19, v19, v11
	v_mul_f32_e32 v20, v20, v12
	v_mul_f32_e32 v21, v21, v13
	v_mul_f32_e32 v22, v22, v14
	v_mul_f32_e32 v23, v23, v15
	v_fma_f32 v16, v16, v8, v8
	v_fma_f32 v17, v17, v9, v9
	v_fma_f32 v18, v18, v10, v10
	v_fma_f32 v19, v19, v11, v11
	v_fma_f32 v20, v20, v12, v12
	v_fma_f32 v21, v21, v13, v13
	v_fma_f32 v22, v22, v14, v14
	v_fma_f32 v23, v23, v15, v15
	v_mul_f32_e32 v16, 0x3f4c422a, v16
	v_mul_f32_e32 v17, 0x3f4c422a, v17
	v_mul_f32_e32 v18, 0x3f4c422a, v18
	v_mul_f32_e32 v19, 0x3f4c422a, v19
	v_mul_f32_e32 v20, 0x3f4c422a, v20
	v_mul_f32_e32 v21, 0x3f4c422a, v21
	v_mul_f32_e32 v22, 0x3f4c422a, v22
	v_mul_f32_e32 v23, 0x3f4c422a, v23
	v_mul_f32_e32 v16, 0x4038aa3b, v16
	v_mul_f32_e32 v17, 0x4038aa3b, v17
	v_mul_f32_e32 v18, 0x4038aa3b, v18
	v_mul_f32_e32 v19, 0x4038aa3b, v19
	v_mul_f32_e32 v20, 0x4038aa3b, v20
	v_mul_f32_e32 v21, 0x4038aa3b, v21
	v_mul_f32_e32 v22, 0x4038aa3b, v22
	v_mul_f32_e32 v23, 0x4038aa3b, v23
	v_exp_f32_e32 v16, v16
	v_exp_f32_e32 v17, v17
	v_exp_f32_e32 v18, v18
	v_exp_f32_e32 v19, v19
	v_exp_f32_e32 v20, v20
	v_exp_f32_e32 v21, v21
	v_exp_f32_e32 v22, v22
	v_exp_f32_e32 v23, v23
	v_lshlrev_b32_e32 v24, 16, v92
	v_and_b32_e32 v25, 0xffff0000, v92
	v_lshlrev_b32_e32 v26, 16, v93
	v_and_b32_e32 v27, 0xffff0000, v93
	v_lshlrev_b32_e32 v28, 16, v94
	v_and_b32_e32 v29, 0xffff0000, v94
	v_lshlrev_b32_e32 v30, 16, v95
	v_and_b32_e32 v31, 0xffff0000, v95
	v_add_f32_e32 v16, 1.0, v16
	v_add_f32_e32 v17, 1.0, v17
	v_add_f32_e32 v18, 1.0, v18
	v_add_f32_e32 v19, 1.0, v19
	v_add_f32_e32 v20, 1.0, v20
	v_add_f32_e32 v21, 1.0, v21
	v_add_f32_e32 v22, 1.0, v22
	v_add_f32_e32 v23, 1.0, v23
	v_rcp_f32_e32 v16, v16
	v_rcp_f32_e32 v17, v17
	v_rcp_f32_e32 v18, v18
	v_rcp_f32_e32 v19, v19
	v_rcp_f32_e32 v20, v20
	v_rcp_f32_e32 v21, v21
	v_rcp_f32_e32 v22, v22
	v_rcp_f32_e32 v23, v23
	v_lshlrev_b32_e32 v92, 16, v96
	v_and_b32_e32 v96, 0xffff0000, v96
	v_lshlrev_b32_e32 v93, 16, v97
	v_and_b32_e32 v97, 0xffff0000, v97
	v_lshlrev_b32_e32 v94, 16, v98
	v_and_b32_e32 v98, 0xffff0000, v98
	v_lshlrev_b32_e32 v95, 16, v99
	v_and_b32_e32 v99, 0xffff0000, v99
	v_add_f32_e32 v24, v92, v24
	v_add_f32_e32 v25, v96, v25
	v_add_f32_e32 v26, v93, v26
	v_add_f32_e32 v27, v97, v27
	v_add_f32_e32 v28, v94, v28
	v_add_f32_e32 v29, v98, v29
	v_add_f32_e32 v30, v95, v30
	v_add_f32_e32 v31, v99, v31
	v_fma_f32 v16, v16, -2.0, 1.0
	v_fma_f32 v17, v17, -2.0, 1.0
	v_fma_f32 v18, v18, -2.0, 1.0
	v_fma_f32 v19, v19, -2.0, 1.0
	v_fma_f32 v20, v20, -2.0, 1.0
	v_fma_f32 v21, v21, -2.0, 1.0
	v_fma_f32 v22, v22, -2.0, 1.0
	v_fma_f32 v23, v23, -2.0, 1.0
	v_mul_f32_e32 v8, 0.5, v8
	v_mul_f32_e32 v9, 0.5, v9
	v_mul_f32_e32 v10, 0.5, v10
	v_mul_f32_e32 v11, 0.5, v11
	v_mul_f32_e32 v12, 0.5, v12
	v_mul_f32_e32 v13, 0.5, v13
	v_mul_f32_e32 v14, 0.5, v14
	v_mul_f32_e32 v15, 0.5, v15
	v_add_f32_e32 v16, 1.0, v16
	v_add_f32_e32 v17, 1.0, v17
	v_add_f32_e32 v18, 1.0, v18
	v_add_f32_e32 v19, 1.0, v19
	v_add_f32_e32 v20, 1.0, v20
	v_add_f32_e32 v21, 1.0, v21
	v_add_f32_e32 v22, 1.0, v22
	v_add_f32_e32 v23, 1.0, v23
	v_mul_f32_e32 v8, v8, v16
	v_mul_f32_e32 v9, v9, v17
	v_mul_f32_e32 v10, v10, v18
	v_mul_f32_e32 v11, v11, v19
	v_mul_f32_e32 v12, v12, v20
	v_mul_f32_e32 v13, v13, v21
	v_mul_f32_e32 v14, v14, v22
	v_mul_f32_e32 v15, v15, v23
	v_mul_f32_e32 v24, v24, v8
	v_mul_f32_e32 v25, v25, v9
	v_mul_f32_e32 v26, v26, v10
	v_mul_f32_e32 v27, v27, v11
	v_mul_f32_e32 v28, v28, v12
	v_mul_f32_e32 v29, v29, v13
	v_mul_f32_e32 v30, v30, v14
	v_mul_f32_e32 v31, v31, v15
	v_mul_f32_e32 v96, v25, v25
	v_cvt_pk_bf16_f32 v92, v24, v25
	v_fmac_f32_e32 v96, v24, v24
	v_cvt_pk_bf16_f32 v93, v26, v27
	v_fmac_f32_e32 v96, v26, v26
	v_cvt_pk_bf16_f32 v94, v28, v29
	v_fmac_f32_e32 v96, v27, v27
	v_cvt_pk_bf16_f32 v95, v30, v31
	v_fmac_f32_e32 v96, v28, v28
	v_fmac_f32_e32 v96, v29, v29
	v_fmac_f32_e32 v96, v30, v30
	v_fmac_f32_e32 v96, v31, v31
	s_waitcnt vmcnt(27)
; __device__ __forceinline__ unsigned cvt_pk(float lo, float hi) { unsigned r; asm("v_cvt_pk_bf16_f32 %0, %1, %2" : "=v"(r) : "v"(lo), "v"(hi)); return r; }
; __device__ __forceinline__ float bflo(unsigned w) { return __uint_as_float(w << 16); }
; __device__ __forceinline__ float bfhi(unsigned w) { return __uint_as_float(w & 0xffff0000u); }
; __device__ __forceinline__ void rnn_combine(const Params& p) {
;     ...
;         for (int k = 0; k < 4; ++k) { const int rr = r0 + k * NW;
;             float y[8]; float q = 0.f;
; #pragma unroll
;             for (int i = 0; i < 4; ++i) { const unsigned a = hf[k][i], c = hb[k][i], gg = gw[k][i];
; #pragma unroll
;                 for (int e = 0; e < 2; ++e) { const float hs = (e ? bfhi(a) : bflo(a)) + (e ? bfhi(c) : bflo(c)); const float gt = e ? bfhi(gg) : bflo(gg);
;                     const float u = 0.7978845608028654f * (gt + 0.044715f * gt * gt * gt); const float th = 1.0f - 2.0f * __builtin_amdgcn_rcpf(1.0f + __builtin_amdgcn_exp2f(2.8853900817779268f * u));
;                     const float yv = hs * (0.5f * gt * (1.0f + th)); y[2 * i + e] = yv; q += yv * yv; } }
;             q = wave_sum(q);
;             if (rr < MR) { u32x4 w; w.x = cvt_pk(y[0], y[1]); w.y = cvt_pk(y[2], y[3]); w.z = cvt_pk(y[4], y[5]); w.w = cvt_pk(y[6], y[7]);
	v_lshlrev_b32_e32 v8, 16, v112
	v_and_b32_e32 v9, 0xffff0000, v112
	v_lshlrev_b32_e32 v10, 16, v113
	v_and_b32_e32 v11, 0xffff0000, v113
	v_lshlrev_b32_e32 v12, 16, v114
	v_and_b32_e32 v13, 0xffff0000, v114
	v_lshlrev_b32_e32 v14, 16, v115
	v_and_b32_e32 v15, 0xffff0000, v115
	v_mul_f32_e32 v16, 0x3d372713, v8
	v_mul_f32_e32 v17, 0x3d372713, v9
	v_mul_f32_e32 v18, 0x3d372713, v10
	v_mul_f32_e32 v19, 0x3d372713, v11
	v_mul_f32_e32 v20, 0x3d372713, v12
	v_mul_f32_e32 v21, 0x3d372713, v13
	v_mul_f32_e32 v22, 0x3d372713, v14
	v_mul_f32_e32 v23, 0x3d372713, v15
	v_mul_f32_e32 v16, v16, v8
	v_mul_f32_e32 v17, v17, v9
	v_mul_f32_e32 v18, v18, v10
	v_mul_f32_e32 v19, v19, v11
	v_mul_f32_e32 v20, v20, v12
	v_mul_f32_e32 v21, v21, v13
	v_mul_f32_e32 v22, v22, v14
	v_mul_f32_e32 v23, v23, v15
	v_fma_f32 v16, v16, v8, v8
	v_fma_f32 v17, v17, v9, v9
	v_fma_f32 v18, v18, v10, v10
	v_fma_f32 v19, v19, v11, v11
	v_fma_f32 v20, v20, v12, v12
	v_fma_f32 v21, v21, v13, v13
	v_fma_f32 v22, v22, v14, v14
	v_fma_f32 v23, v23, v15, v15
	v_mul_f32_e32 v16, 0x3f4c422a, v16
	v_mul_f32_e32 v17, 0x3f4c422a, v17
	v_mul_f32_e32 v18, 0x3f4c422a, v18
	v_mul_f32_e32 v19, 0x3f4c422a, v19
	v_mul_f32_e32 v20, 0x3f4c422a, v20
	v_mul_f32_e32 v21, 0x3f4c422a, v21
	v_mul_f32_e32 v22, 0x3f4c422a, v22
	v_mul_f32_e32 v23, 0x3f4c422a, v23
	v_mul_f32_e32 v16, 0x4038aa3b, v16
	v_mul_f32_e32 v17, 0x4038aa3b, v17
	v_mul_f32_e32 v18, 0x4038aa3b, v18
	v_mul_f32_e32 v19, 0x4038aa3b, v19
	v_mul_f32_e32 v20, 0x4038aa3b, v20
	v_mul_f32_e32 v21, 0x4038aa3b, v21
	v_mul_f32_e32 v22, 0x4038aa3b, v22
	v_mul_f32_e32 v23, 0x4038aa3b, v23
	v_exp_f32_e32 v16, v16
	v_exp_f32_e32 v17, v17
	v_exp_f32_e32 v18, v18
	v_exp_f32_e32 v19, v19
	v_exp_f32_e32 v20, v20
	v_exp_f32_e32 v21, v21
	v_exp_f32_e32 v22, v22
	v_exp_f32_e32 v23, v23
	v_lshlrev_b32_e32 v24, 16, v104
	v_and_b32_e32 v25, 0xffff0000, v104
	v_lshlrev_b32_e32 v26, 16, v105
	v_and_b32_e32 v27, 0xffff0000, v105
	v_lshlrev_b32_e32 v28, 16, v106
	v_and_b32_e32 v29, 0xffff0000, v106
	v_lshlrev_b32_e32 v30, 16, v107
	v_and_b32_e32 v31, 0xffff0000, v107
	v_add_f32_e32 v16, 1.0, v16
	v_add_f32_e32 v17, 1.0, v17
	v_add_f32_e32 v18, 1.0, v18
	v_add_f32_e32 v19, 1.0, v19
	v_add_f32_e32 v20, 1.0, v20
	v_add_f32_e32 v21, 1.0, v21
	v_add_f32_e32 v22, 1.0, v22
	v_add_f32_e32 v23, 1.0, v23
	v_rcp_f32_e32 v16, v16
	v_rcp_f32_e32 v17, v17
	v_rcp_f32_e32 v18, v18
	v_rcp_f32_e32 v19, v19
	v_rcp_f32_e32 v20, v20
	v_rcp_f32_e32 v21, v21
	v_rcp_f32_e32 v22, v22
	v_rcp_f32_e32 v23, v23
	v_lshlrev_b32_e32 v104, 16, v108
	v_and_b32_e32 v108, 0xffff0000, v108
	v_lshlrev_b32_e32 v105, 16, v109
	v_and_b32_e32 v109, 0xffff0000, v109
	v_lshlrev_b32_e32 v106, 16, v110
	v_and_b32_e32 v110, 0xffff0000, v110
	v_lshlrev_b32_e32 v107, 16, v111
	v_and_b32_e32 v111, 0xffff0000, v111
	v_add_f32_e32 v24, v104, v24
	v_add_f32_e32 v25, v108, v25
	v_add_f32_e32 v26, v105, v26
	v_add_f32_e32 v27, v109, v27
	v_add_f32_e32 v28, v106, v28
	v_add_f32_e32 v29, v110, v29
	v_add_f32_e32 v30, v107, v30
	v_add_f32_e32 v31, v111, v31
	v_fma_f32 v16, v16, -2.0, 1.0
	v_fma_f32 v17, v17, -2.0, 1.0
	v_fma_f32 v18, v18, -2.0, 1.0
	v_fma_f32 v19, v19, -2.0, 1.0
	v_fma_f32 v20, v20, -2.0, 1.0
	v_fma_f32 v21, v21, -2.0, 1.0
	v_fma_f32 v22, v22, -2.0, 1.0
	v_fma_f32 v23, v23, -2.0, 1.0
	v_mul_f32_e32 v8, 0.5, v8
	v_mul_f32_e32 v9, 0.5, v9
	v_mul_f32_e32 v10, 0.5, v10
	v_mul_f32_e32 v11, 0.5, v11
	v_mul_f32_e32 v12, 0.5, v12
	v_mul_f32_e32 v13, 0.5, v13
	v_mul_f32_e32 v14, 0.5, v14
	v_mul_f32_e32 v15, 0.5, v15
	v_add_f32_e32 v16, 1.0, v16
	v_add_f32_e32 v17, 1.0, v17
	v_add_f32_e32 v18, 1.0, v18
	v_add_f32_e32 v19, 1.0, v19
	v_add_f32_e32 v20, 1.0, v20
	v_add_f32_e32 v21, 1.0, v21
	v_add_f32_e32 v22, 1.0, v22
	v_add_f32_e32 v23, 1.0, v23
	v_mul_f32_e32 v8, v8, v16
	v_mul_f32_e32 v9, v9, v17
	v_mul_f32_e32 v10, v10, v18
	v_mul_f32_e32 v11, v11, v19
	v_mul_f32_e32 v12, v12, v20
	v_mul_f32_e32 v13, v13, v21
	v_mul_f32_e32 v14, v14, v22
	v_mul_f32_e32 v15, v15, v23
	v_mul_f32_e32 v24, v24, v8
	v_mul_f32_e32 v25, v25, v9
	v_mul_f32_e32 v26, v26, v10
	v_mul_f32_e32 v27, v27, v11
	v_mul_f32_e32 v28, v28, v12
	v_mul_f32_e32 v29, v29, v13
	v_mul_f32_e32 v30, v30, v14
	v_mul_f32_e32 v31, v31, v15
	v_mul_f32_e32 v108, v25, v25
	v_cvt_pk_bf16_f32 v104, v24, v25
	v_fmac_f32_e32 v108, v24, v24
	v_cvt_pk_bf16_f32 v105, v26, v27
	v_fmac_f32_e32 v108, v26, v26
	v_cvt_pk_bf16_f32 v106, v28, v29
	v_fmac_f32_e32 v108, v27, v27
	v_cvt_pk_bf16_f32 v107, v30, v31
	v_fmac_f32_e32 v108, v28, v28
	v_fmac_f32_e32 v108, v29, v29
	v_fmac_f32_e32 v108, v30, v30
	v_fmac_f32_e32 v108, v31, v31
	s_waitcnt vmcnt(24)
; __device__ __forceinline__ unsigned cvt_pk(float lo, float hi) { unsigned r; asm("v_cvt_pk_bf16_f32 %0, %1, %2" : "=v"(r) : "v"(lo), "v"(hi)); return r; }
; __device__ __forceinline__ float bflo(unsigned w) { return __uint_as_float(w << 16); }
; __device__ __forceinline__ float bfhi(unsigned w) { return __uint_as_float(w & 0xffff0000u); }
; __device__ __forceinline__ void rnn_combine(const Params& p) {
;     ...
;         for (int k = 0; k < 4; ++k) { const int rr = r0 + k * NW;
;             float y[8]; float q = 0.f;
; #pragma unroll
;             for (int i = 0; i < 4; ++i) { const unsigned a = hf[k][i], c = hb[k][i], gg = gw[k][i];
; #pragma unroll
;                 for (int e = 0; e < 2; ++e) { const float hs = (e ? bfhi(a) : bflo(a)) + (e ? bfhi(c) : bflo(c)); const float gt = e ? bfhi(gg) : bflo(gg);
;                     const float u = 0.7978845608028654f * (gt + 0.044715f * gt * gt * gt); const float th = 1.0f - 2.0f * __builtin_amdgcn_rcpf(1.0f + __builtin_amdgcn_exp2f(2.8853900817779268f * u));
;                     const float yv = hs * (0.5f * gt * (1.0f + th)); y[2 * i + e] = yv; q += yv * yv; } }
;             q = wave_sum(q);
;             if (rr < MR) { u32x4 w; w.x = cvt_pk(y[0], y[1]); w.y = cvt_pk(y[2], y[3]); w.z = cvt_pk(y[4], y[5]); w.w = cvt_pk(y[6], y[7]);
	v_lshlrev_b32_e32 v8, 16, v124
	v_and_b32_e32 v9, 0xffff0000, v124
	v_lshlrev_b32_e32 v10, 16, v125
	v_and_b32_e32 v11, 0xffff0000, v125
	v_lshlrev_b32_e32 v12, 16, v126
	v_and_b32_e32 v13, 0xffff0000, v126
	v_lshlrev_b32_e32 v14, 16, v127
	v_and_b32_e32 v15, 0xffff0000, v127
	v_mul_f32_e32 v16, 0x3d372713, v8
	v_mul_f32_e32 v17, 0x3d372713, v9
	v_mul_f32_e32 v18, 0x3d372713, v10
	v_mul_f32_e32 v19, 0x3d372713, v11
	v_mul_f32_e32 v20, 0x3d372713, v12
	v_mul_f32_e32 v21, 0x3d372713, v13
	v_mul_f32_e32 v22, 0x3d372713, v14
	v_mul_f32_e32 v23, 0x3d372713, v15
	v_mul_f32_e32 v16, v16, v8
	v_mul_f32_e32 v17, v17, v9
	v_mul_f32_e32 v18, v18, v10
	v_mul_f32_e32 v19, v19, v11
	v_mul_f32_e32 v20, v20, v12
	v_mul_f32_e32 v21, v21, v13
	v_mul_f32_e32 v22, v22, v14
	v_mul_f32_e32 v23, v23, v15
	v_fma_f32 v16, v16, v8, v8
	v_fma_f32 v17, v17, v9, v9
	v_fma_f32 v18, v18, v10, v10
	v_fma_f32 v19, v19, v11, v11
	v_fma_f32 v20, v20, v12, v12
	v_fma_f32 v21, v21, v13, v13
	v_fma_f32 v22, v22, v14, v14
	v_fma_f32 v23, v23, v15, v15
	v_mul_f32_e32 v16, 0x3f4c422a, v16
	v_mul_f32_e32 v17, 0x3f4c422a, v17
	v_mul_f32_e32 v18, 0x3f4c422a, v18
	v_mul_f32_e32 v19, 0x3f4c422a, v19
	v_mul_f32_e32 v20, 0x3f4c422a, v20
	v_mul_f32_e32 v21, 0x3f4c422a, v21
	v_mul_f32_e32 v22, 0x3f4c422a, v22
	v_mul_f32_e32 v23, 0x3f4c422a, v23
	v_mul_f32_e32 v16, 0x4038aa3b, v16
	v_mul_f32_e32 v17, 0x4038aa3b, v17
	v_mul_f32_e32 v18, 0x4038aa3b, v18
	v_mul_f32_e32 v19, 0x4038aa3b, v19
	v_mul_f32_e32 v20, 0x4038aa3b, v20
	v_mul_f32_e32 v21, 0x4038aa3b, v21
	v_mul_f32_e32 v22, 0x4038aa3b, v22
	v_mul_f32_e32 v23, 0x4038aa3b, v23
	v_exp_f32_e32 v16, v16
	v_exp_f32_e32 v17, v17
	v_exp_f32_e32 v18, v18
	v_exp_f32_e32 v19, v19
	v_exp_f32_e32 v20, v20
	v_exp_f32_e32 v21, v21
	v_exp_f32_e32 v22, v22
	v_exp_f32_e32 v23, v23
	v_lshlrev_b32_e32 v24, 16, v116
	v_and_b32_e32 v25, 0xffff0000, v116
	v_lshlrev_b32_e32 v26, 16, v117
	v_and_b32_e32 v27, 0xffff0000, v117
	v_lshlrev_b32_e32 v28, 16, v118
	v_and_b32_e32 v29, 0xffff0000, v118
	v_lshlrev_b32_e32 v30, 16, v119
	v_and_b32_e32 v31, 0xffff0000, v119
	v_add_f32_e32 v16, 1.0, v16
	v_add_f32_e32 v17, 1.0, v17
	v_add_f32_e32 v18, 1.0, v18
	v_add_f32_e32 v19, 1.0, v19
	v_add_f32_e32 v20, 1.0, v20
	v_add_f32_e32 v21, 1.0, v21
	v_add_f32_e32 v22, 1.0, v22
	v_add_f32_e32 v23, 1.0, v23
	v_rcp_f32_e32 v16, v16
	v_rcp_f32_e32 v17, v17
	v_rcp_f32_e32 v18, v18
	v_rcp_f32_e32 v19, v19
	v_rcp_f32_e32 v20, v20
	v_rcp_f32_e32 v21, v21
	v_rcp_f32_e32 v22, v22
	v_rcp_f32_e32 v23, v23
	v_lshlrev_b32_e32 v116, 16, v120
	v_and_b32_e32 v120, 0xffff0000, v120
	v_lshlrev_b32_e32 v117, 16, v121
	v_and_b32_e32 v121, 0xffff0000, v121
	v_lshlrev_b32_e32 v118, 16, v122
	v_and_b32_e32 v122, 0xffff0000, v122
	v_lshlrev_b32_e32 v119, 16, v123
	v_and_b32_e32 v123, 0xffff0000, v123
	v_add_f32_e32 v24, v116, v24
	v_add_f32_e32 v25, v120, v25
	v_add_f32_e32 v26, v117, v26
	v_add_f32_e32 v27, v121, v27
	v_add_f32_e32 v28, v118, v28
	v_add_f32_e32 v29, v122, v29
	v_add_f32_e32 v30, v119, v30
	v_add_f32_e32 v31, v123, v31
	v_fma_f32 v16, v16, -2.0, 1.0
	v_fma_f32 v17, v17, -2.0, 1.0
	v_fma_f32 v18, v18, -2.0, 1.0
	v_fma_f32 v19, v19, -2.0, 1.0
	v_fma_f32 v20, v20, -2.0, 1.0
	v_fma_f32 v21, v21, -2.0, 1.0
	v_fma_f32 v22, v22, -2.0, 1.0
	v_fma_f32 v23, v23, -2.0, 1.0
	v_mul_f32_e32 v8, 0.5, v8
	v_mul_f32_e32 v9, 0.5, v9
	v_mul_f32_e32 v10, 0.5, v10
	v_mul_f32_e32 v11, 0.5, v11
	v_mul_f32_e32 v12, 0.5, v12
	v_mul_f32_e32 v13, 0.5, v13
	v_mul_f32_e32 v14, 0.5, v14
	v_mul_f32_e32 v15, 0.5, v15
	v_add_f32_e32 v16, 1.0, v16
	v_add_f32_e32 v17, 1.0, v17
	v_add_f32_e32 v18, 1.0, v18
	v_add_f32_e32 v19, 1.0, v19
	v_add_f32_e32 v20, 1.0, v20
	v_add_f32_e32 v21, 1.0, v21
	v_add_f32_e32 v22, 1.0, v22
	v_add_f32_e32 v23, 1.0, v23
	v_mul_f32_e32 v8, v8, v16
	v_mul_f32_e32 v9, v9, v17
	v_mul_f32_e32 v10, v10, v18
	v_mul_f32_e32 v11, v11, v19
	v_mul_f32_e32 v12, v12, v20
	v_mul_f32_e32 v13, v13, v21
	v_mul_f32_e32 v14, v14, v22
	v_mul_f32_e32 v15, v15, v23
	v_mul_f32_e32 v24, v24, v8
	v_mul_f32_e32 v25, v25, v9
	v_mul_f32_e32 v26, v26, v10
	v_mul_f32_e32 v27, v27, v11
	v_mul_f32_e32 v28, v28, v12
	v_mul_f32_e32 v29, v29, v13
	v_mul_f32_e32 v30, v30, v14
	v_mul_f32_e32 v31, v31, v15
	v_mul_f32_e32 v120, v25, v25
	v_cvt_pk_bf16_f32 v116, v24, v25
	v_fmac_f32_e32 v120, v24, v24
	v_cvt_pk_bf16_f32 v117, v26, v27
	v_fmac_f32_e32 v120, v26, v26
	v_cvt_pk_bf16_f32 v118, v28, v29
	v_fmac_f32_e32 v120, v27, v27
	v_cvt_pk_bf16_f32 v119, v30, v31
	v_fmac_f32_e32 v120, v28, v28
	v_fmac_f32_e32 v120, v29, v29
	v_fmac_f32_e32 v120, v30, v30
	v_fmac_f32_e32 v120, v31, v31
	s_waitcnt vmcnt(21)
; __device__ __forceinline__ unsigned cvt_pk(float lo, float hi) { unsigned r; asm("v_cvt_pk_bf16_f32 %0, %1, %2" : "=v"(r) : "v"(lo), "v"(hi)); return r; }
; __device__ __forceinline__ float bflo(unsigned w) { return __uint_as_float(w << 16); }
; __device__ __forceinline__ float bfhi(unsigned w) { return __uint_as_float(w & 0xffff0000u); }
; __device__ __forceinline__ void rnn_combine(const Params& p) {
;     ...
;         for (int k = 0; k < 4; ++k) { const int rr = r0 + k * NW;
;             float y[8]; float q = 0.f;
; #pragma unroll
;             for (int i = 0; i < 4; ++i) { const unsigned a = hf[k][i], c = hb[k][i], gg = gw[k][i];
; #pragma unroll
;                 for (int e = 0; e < 2; ++e) { const float hs = (e ? bfhi(a) : bflo(a)) + (e ? bfhi(c) : bflo(c)); const float gt = e ? bfhi(gg) : bflo(gg);
;                     const float u = 0.7978845608028654f * (gt + 0.044715f * gt * gt * gt); const float th = 1.0f - 2.0f * __builtin_amdgcn_rcpf(1.0f + __builtin_amdgcn_exp2f(2.8853900817779268f * u));
;                     const float yv = hs * (0.5f * gt * (1.0f + th)); y[2 * i + e] = yv; q += yv * yv; } }
;             q = wave_sum(q);
;             if (rr < MR) { u32x4 w; w.x = cvt_pk(y[0], y[1]); w.y = cvt_pk(y[2], y[3]); w.z = cvt_pk(y[4], y[5]); w.w = cvt_pk(y[6], y[7]);
	v_lshlrev_b32_e32 v8, 16, v136
	v_and_b32_e32 v9, 0xffff0000, v136
	v_lshlrev_b32_e32 v10, 16, v137
	v_and_b32_e32 v11, 0xffff0000, v137
	v_lshlrev_b32_e32 v12, 16, v138
	v_and_b32_e32 v13, 0xffff0000, v138
	v_lshlrev_b32_e32 v14, 16, v139
	v_and_b32_e32 v15, 0xffff0000, v139
	v_mul_f32_e32 v16, 0x3d372713, v8
	v_mul_f32_e32 v17, 0x3d372713, v9
	v_mul_f32_e32 v18, 0x3d372713, v10
	v_mul_f32_e32 v19, 0x3d372713, v11
	v_mul_f32_e32 v20, 0x3d372713, v12
	v_mul_f32_e32 v21, 0x3d372713, v13
	v_mul_f32_e32 v22, 0x3d372713, v14
	v_mul_f32_e32 v23, 0x3d372713, v15
	v_mul_f32_e32 v16, v16, v8
	v_mul_f32_e32 v17, v17, v9
	v_mul_f32_e32 v18, v18, v10
	v_mul_f32_e32 v19, v19, v11
	v_mul_f32_e32 v20, v20, v12
	v_mul_f32_e32 v21, v21, v13
	v_mul_f32_e32 v22, v22, v14
	v_mul_f32_e32 v23, v23, v15
	v_fma_f32 v16, v16, v8, v8
	v_fma_f32 v17, v17, v9, v9
	v_fma_f32 v18, v18, v10, v10
	v_fma_f32 v19, v19, v11, v11
	v_fma_f32 v20, v20, v12, v12
	v_fma_f32 v21, v21, v13, v13
	v_fma_f32 v22, v22, v14, v14
	v_fma_f32 v23, v23, v15, v15
	v_mul_f32_e32 v16, 0x3f4c422a, v16
	v_mul_f32_e32 v17, 0x3f4c422a, v17
	v_mul_f32_e32 v18, 0x3f4c422a, v18
	v_mul_f32_e32 v19, 0x3f4c422a, v19
	v_mul_f32_e32 v20, 0x3f4c422a, v20
	v_mul_f32_e32 v21, 0x3f4c422a, v21
	v_mul_f32_e32 v22, 0x3f4c422a, v22
	v_mul_f32_e32 v23, 0x3f4c422a, v23
	v_mul_f32_e32 v16, 0x4038aa3b, v16
	v_mul_f32_e32 v17, 0x4038aa3b, v17
	v_mul_f32_e32 v18, 0x4038aa3b, v18
	v_mul_f32_e32 v19, 0x4038aa3b, v19
	v_mul_f32_e32 v20, 0x4038aa3b, v20
	v_mul_f32_e32 v21, 0x4038aa3b, v21
	v_mul_f32_e32 v22, 0x4038aa3b, v22
	v_mul_f32_e32 v23, 0x4038aa3b, v23
	v_exp_f32_e32 v16, v16
	v_exp_f32_e32 v17, v17
	v_exp_f32_e32 v18, v18
	v_exp_f32_e32 v19, v19
	v_exp_f32_e32 v20, v20
	v_exp_f32_e32 v21, v21
	v_exp_f32_e32 v22, v22
	v_exp_f32_e32 v23, v23
	v_lshlrev_b32_e32 v24, 16, v128
	v_and_b32_e32 v25, 0xffff0000, v128
	v_lshlrev_b32_e32 v26, 16, v129
	v_and_b32_e32 v27, 0xffff0000, v129
	v_lshlrev_b32_e32 v28, 16, v130
	v_and_b32_e32 v29, 0xffff0000, v130
	v_lshlrev_b32_e32 v30, 16, v131
	v_and_b32_e32 v31, 0xffff0000, v131
	v_add_f32_e32 v16, 1.0, v16
	v_add_f32_e32 v17, 1.0, v17
	v_add_f32_e32 v18, 1.0, v18
	v_add_f32_e32 v19, 1.0, v19
	v_add_f32_e32 v20, 1.0, v20
	v_add_f32_e32 v21, 1.0, v21
	v_add_f32_e32 v22, 1.0, v22
	v_add_f32_e32 v23, 1.0, v23
	v_rcp_f32_e32 v16, v16
	v_rcp_f32_e32 v17, v17
	v_rcp_f32_e32 v18, v18
	v_rcp_f32_e32 v19, v19
	v_rcp_f32_e32 v20, v20
	v_rcp_f32_e32 v21, v21
	v_rcp_f32_e32 v22, v22
	v_rcp_f32_e32 v23, v23
	v_lshlrev_b32_e32 v128, 16, v132
	v_and_b32_e32 v132, 0xffff0000, v132
	v_lshlrev_b32_e32 v129, 16, v133
	v_and_b32_e32 v133, 0xffff0000, v133
	v_lshlrev_b32_e32 v130, 16, v134
	v_and_b32_e32 v134, 0xffff0000, v134
	v_lshlrev_b32_e32 v131, 16, v135
	v_and_b32_e32 v135, 0xffff0000, v135
	v_add_f32_e32 v24, v128, v24
	v_add_f32_e32 v25, v132, v25
	v_add_f32_e32 v26, v129, v26
	v_add_f32_e32 v27, v133, v27
	v_add_f32_e32 v28, v130, v28
	v_add_f32_e32 v29, v134, v29
	v_add_f32_e32 v30, v131, v30
	v_add_f32_e32 v31, v135, v31
	v_fma_f32 v16, v16, -2.0, 1.0
	v_fma_f32 v17, v17, -2.0, 1.0
	v_fma_f32 v18, v18, -2.0, 1.0
	v_fma_f32 v19, v19, -2.0, 1.0
	v_fma_f32 v20, v20, -2.0, 1.0
	v_fma_f32 v21, v21, -2.0, 1.0
	v_fma_f32 v22, v22, -2.0, 1.0
	v_fma_f32 v23, v23, -2.0, 1.0
	v_mul_f32_e32 v8, 0.5, v8
	v_mul_f32_e32 v9, 0.5, v9
	v_mul_f32_e32 v10, 0.5, v10
	v_mul_f32_e32 v11, 0.5, v11
	v_mul_f32_e32 v12, 0.5, v12
	v_mul_f32_e32 v13, 0.5, v13
	v_mul_f32_e32 v14, 0.5, v14
	v_mul_f32_e32 v15, 0.5, v15
	v_add_f32_e32 v16, 1.0, v16
	v_add_f32_e32 v17, 1.0, v17
	v_add_f32_e32 v18, 1.0, v18
	v_add_f32_e32 v19, 1.0, v19
	v_add_f32_e32 v20, 1.0, v20
	v_add_f32_e32 v21, 1.0, v21
	v_add_f32_e32 v22, 1.0, v22
	v_add_f32_e32 v23, 1.0, v23
	v_mul_f32_e32 v8, v8, v16
	v_mul_f32_e32 v9, v9, v17
	v_mul_f32_e32 v10, v10, v18
	v_mul_f32_e32 v11, v11, v19
	v_mul_f32_e32 v12, v12, v20
	v_mul_f32_e32 v13, v13, v21
	v_mul_f32_e32 v14, v14, v22
	v_mul_f32_e32 v15, v15, v23
	v_mul_f32_e32 v24, v24, v8
	v_mul_f32_e32 v25, v25, v9
	v_mul_f32_e32 v26, v26, v10
	v_mul_f32_e32 v27, v27, v11
	v_mul_f32_e32 v28, v28, v12
	v_mul_f32_e32 v29, v29, v13
	v_mul_f32_e32 v30, v30, v14
	v_mul_f32_e32 v31, v31, v15
	v_mul_f32_e32 v132, v25, v25
	v_cvt_pk_bf16_f32 v128, v24, v25
	v_fmac_f32_e32 v132, v24, v24
	v_cvt_pk_bf16_f32 v129, v26, v27
	v_fmac_f32_e32 v132, v26, v26
	v_cvt_pk_bf16_f32 v130, v28, v29
	v_fmac_f32_e32 v132, v27, v27
	v_cvt_pk_bf16_f32 v131, v30, v31
	v_fmac_f32_e32 v132, v28, v28
	v_fmac_f32_e32 v132, v29, v29
	v_fmac_f32_e32 v132, v30, v30
	v_fmac_f32_e32 v132, v31, v31
	s_waitcnt vmcnt(18)
; __device__ __forceinline__ unsigned cvt_pk(float lo, float hi) { unsigned r; asm("v_cvt_pk_bf16_f32 %0, %1, %2" : "=v"(r) : "v"(lo), "v"(hi)); return r; }
; __device__ __forceinline__ float bflo(unsigned w) { return __uint_as_float(w << 16); }
; __device__ __forceinline__ float bfhi(unsigned w) { return __uint_as_float(w & 0xffff0000u); }
; __device__ __forceinline__ void rnn_combine(const Params& p) {
;     ...
;         for (int k = 0; k < 4; ++k) { const int rr = r0 + k * NW;
;             float y[8]; float q = 0.f;
; #pragma unroll
;             for (int i = 0; i < 4; ++i) { const unsigned a = hf[k][i], c = hb[k][i], gg = gw[k][i];
; #pragma unroll
;                 for (int e = 0; e < 2; ++e) { const float hs = (e ? bfhi(a) : bflo(a)) + (e ? bfhi(c) : bflo(c)); const float gt = e ? bfhi(gg) : bflo(gg);
;                     const float u = 0.7978845608028654f * (gt + 0.044715f * gt * gt * gt); const float th = 1.0f - 2.0f * __builtin_amdgcn_rcpf(1.0f + __builtin_amdgcn_exp2f(2.8853900817779268f * u));
;                     const float yv = hs * (0.5f * gt * (1.0f + th)); y[2 * i + e] = yv; q += yv * yv; } }
;             q = wave_sum(q);
;             if (rr < MR) { u32x4 w; w.x = cvt_pk(y[0], y[1]); w.y = cvt_pk(y[2], y[3]); w.z = cvt_pk(y[4], y[5]); w.w = cvt_pk(y[6], y[7]);
	v_lshlrev_b32_e32 v8, 16, v148
	v_and_b32_e32 v9, 0xffff0000, v148
	v_lshlrev_b32_e32 v10, 16, v149
	v_and_b32_e32 v11, 0xffff0000, v149
	v_lshlrev_b32_e32 v12, 16, v150
	v_and_b32_e32 v13, 0xffff0000, v150
	v_lshlrev_b32_e32 v14, 16, v151
	v_and_b32_e32 v15, 0xffff0000, v151
	v_mul_f32_e32 v16, 0x3d372713, v8
	v_mul_f32_e32 v17, 0x3d372713, v9
	v_mul_f32_e32 v18, 0x3d372713, v10
	v_mul_f32_e32 v19, 0x3d372713, v11
	v_mul_f32_e32 v20, 0x3d372713, v12
	v_mul_f32_e32 v21, 0x3d372713, v13
	v_mul_f32_e32 v22, 0x3d372713, v14
	v_mul_f32_e32 v23, 0x3d372713, v15
	v_mul_f32_e32 v16, v16, v8
	v_mul_f32_e32 v17, v17, v9
	v_mul_f32_e32 v18, v18, v10
	v_mul_f32_e32 v19, v19, v11
	v_mul_f32_e32 v20, v20, v12
	v_mul_f32_e32 v21, v21, v13
	v_mul_f32_e32 v22, v22, v14
	v_mul_f32_e32 v23, v23, v15
	v_fma_f32 v16, v16, v8, v8
	v_fma_f32 v17, v17, v9, v9
	v_fma_f32 v18, v18, v10, v10
	v_fma_f32 v19, v19, v11, v11
	v_fma_f32 v20, v20, v12, v12
	v_fma_f32 v21, v21, v13, v13
	v_fma_f32 v22, v22, v14, v14
	v_fma_f32 v23, v23, v15, v15
	v_mul_f32_e32 v16, 0x3f4c422a, v16
	v_mul_f32_e32 v17, 0x3f4c422a, v17
	v_mul_f32_e32 v18, 0x3f4c422a, v18
	v_mul_f32_e32 v19, 0x3f4c422a, v19
	v_mul_f32_e32 v20, 0x3f4c422a, v20
	v_mul_f32_e32 v21, 0x3f4c422a, v21
	v_mul_f32_e32 v22, 0x3f4c422a, v22
	v_mul_f32_e32 v23, 0x3f4c422a, v23
	v_mul_f32_e32 v16, 0x4038aa3b, v16
	v_mul_f32_e32 v17, 0x4038aa3b, v17
	v_mul_f32_e32 v18, 0x4038aa3b, v18
	v_mul_f32_e32 v19, 0x4038aa3b, v19
	v_mul_f32_e32 v20, 0x4038aa3b, v20
	v_mul_f32_e32 v21, 0x4038aa3b, v21
	v_mul_f32_e32 v22, 0x4038aa3b, v22
	v_mul_f32_e32 v23, 0x4038aa3b, v23
	v_exp_f32_e32 v16, v16
	v_exp_f32_e32 v17, v17
	v_exp_f32_e32 v18, v18
	v_exp_f32_e32 v19, v19
	v_exp_f32_e32 v20, v20
	v_exp_f32_e32 v21, v21
	v_exp_f32_e32 v22, v22
	v_exp_f32_e32 v23, v23
	v_lshlrev_b32_e32 v24, 16, v140
	v_and_b32_e32 v25, 0xffff0000, v140
	v_lshlrev_b32_e32 v26, 16, v141
	v_and_b32_e32 v27, 0xffff0000, v141
	v_lshlrev_b32_e32 v28, 16, v142
	v_and_b32_e32 v29, 0xffff0000, v142
	v_lshlrev_b32_e32 v30, 16, v143
	v_and_b32_e32 v31, 0xffff0000, v143
	v_add_f32_e32 v16, 1.0, v16
	v_add_f32_e32 v17, 1.0, v17
	v_add_f32_e32 v18, 1.0, v18
	v_add_f32_e32 v19, 1.0, v19
	v_add_f32_e32 v20, 1.0, v20
	v_add_f32_e32 v21, 1.0, v21
	v_add_f32_e32 v22, 1.0, v22
	v_add_f32_e32 v23, 1.0, v23
	v_rcp_f32_e32 v16, v16
	v_rcp_f32_e32 v17, v17
	v_rcp_f32_e32 v18, v18
	v_rcp_f32_e32 v19, v19
	v_rcp_f32_e32 v20, v20
	v_rcp_f32_e32 v21, v21
	v_rcp_f32_e32 v22, v22
	v_rcp_f32_e32 v23, v23
	v_lshlrev_b32_e32 v140, 16, v144
	v_and_b32_e32 v144, 0xffff0000, v144
	v_lshlrev_b32_e32 v141, 16, v145
	v_and_b32_e32 v145, 0xffff0000, v145
	v_lshlrev_b32_e32 v142, 16, v146
	v_and_b32_e32 v146, 0xffff0000, v146
	v_lshlrev_b32_e32 v143, 16, v147
	v_and_b32_e32 v147, 0xffff0000, v147
	v_add_f32_e32 v24, v140, v24
	v_add_f32_e32 v25, v144, v25
	v_add_f32_e32 v26, v141, v26
	v_add_f32_e32 v27, v145, v27
	v_add_f32_e32 v28, v142, v28
	v_add_f32_e32 v29, v146, v29
	v_add_f32_e32 v30, v143, v30
	v_add_f32_e32 v31, v147, v31
	v_fma_f32 v16, v16, -2.0, 1.0
	v_fma_f32 v17, v17, -2.0, 1.0
	v_fma_f32 v18, v18, -2.0, 1.0
	v_fma_f32 v19, v19, -2.0, 1.0
	v_fma_f32 v20, v20, -2.0, 1.0
	v_fma_f32 v21, v21, -2.0, 1.0
	v_fma_f32 v22, v22, -2.0, 1.0
	v_fma_f32 v23, v23, -2.0, 1.0
	v_mul_f32_e32 v8, 0.5, v8
	v_mul_f32_e32 v9, 0.5, v9
	v_mul_f32_e32 v10, 0.5, v10
	v_mul_f32_e32 v11, 0.5, v11
	v_mul_f32_e32 v12, 0.5, v12
	v_mul_f32_e32 v13, 0.5, v13
	v_mul_f32_e32 v14, 0.5, v14
	v_mul_f32_e32 v15, 0.5, v15
	v_add_f32_e32 v16, 1.0, v16
	v_add_f32_e32 v17, 1.0, v17
	v_add_f32_e32 v18, 1.0, v18
	v_add_f32_e32 v19, 1.0, v19
	v_add_f32_e32 v20, 1.0, v20
	v_add_f32_e32 v21, 1.0, v21
	v_add_f32_e32 v22, 1.0, v22
	v_add_f32_e32 v23, 1.0, v23
	v_mul_f32_e32 v8, v8, v16
	v_mul_f32_e32 v9, v9, v17
	v_mul_f32_e32 v10, v10, v18
	v_mul_f32_e32 v11, v11, v19
	v_mul_f32_e32 v12, v12, v20
	v_mul_f32_e32 v13, v13, v21
	v_mul_f32_e32 v14, v14, v22
	v_mul_f32_e32 v15, v15, v23
	v_mul_f32_e32 v24, v24, v8
	v_mul_f32_e32 v25, v25, v9
	v_mul_f32_e32 v26, v26, v10
	v_mul_f32_e32 v27, v27, v11
	v_mul_f32_e32 v28, v28, v12
	v_mul_f32_e32 v29, v29, v13
	v_mul_f32_e32 v30, v30, v14
	v_mul_f32_e32 v31, v31, v15
	v_mul_f32_e32 v144, v25, v25
	v_cvt_pk_bf16_f32 v140, v24, v25
	v_fmac_f32_e32 v144, v24, v24
	v_cvt_pk_bf16_f32 v141, v26, v27
	v_fmac_f32_e32 v144, v26, v26
	v_cvt_pk_bf16_f32 v142, v28, v29
	v_fmac_f32_e32 v144, v27, v27
	v_cvt_pk_bf16_f32 v143, v30, v31
	v_fmac_f32_e32 v144, v28, v28
	v_fmac_f32_e32 v144, v29, v29
	v_fmac_f32_e32 v144, v30, v30
	v_fmac_f32_e32 v144, v31, v31
	s_waitcnt vmcnt(15)
; __device__ __forceinline__ unsigned cvt_pk(float lo, float hi) { unsigned r; asm("v_cvt_pk_bf16_f32 %0, %1, %2" : "=v"(r) : "v"(lo), "v"(hi)); return r; }
; __device__ __forceinline__ float bflo(unsigned w) { return __uint_as_float(w << 16); }
; __device__ __forceinline__ float bfhi(unsigned w) { return __uint_as_float(w & 0xffff0000u); }
; __device__ __forceinline__ void rnn_combine(const Params& p) {
;     ...
;         for (int k = 0; k < 4; ++k) { const int rr = r0 + k * NW;
;             float y[8]; float q = 0.f;
; #pragma unroll
;             for (int i = 0; i < 4; ++i) { const unsigned a = hf[k][i], c = hb[k][i], gg = gw[k][i];
; #pragma unroll
;                 for (int e = 0; e < 2; ++e) { const float hs = (e ? bfhi(a) : bflo(a)) + (e ? bfhi(c) : bflo(c)); const float gt = e ? bfhi(gg) : bflo(gg);
;                     const float u = 0.7978845608028654f * (gt + 0.044715f * gt * gt * gt); const float th = 1.0f - 2.0f * __builtin_amdgcn_rcpf(1.0f + __builtin_amdgcn_exp2f(2.8853900817779268f * u));
;                     const float yv = hs * (0.5f * gt * (1.0f + th)); y[2 * i + e] = yv; q += yv * yv; } }
;             q = wave_sum(q);
;             if (rr < MR) { u32x4 w; w.x = cvt_pk(y[0], y[1]); w.y = cvt_pk(y[2], y[3]); w.z = cvt_pk(y[4], y[5]); w.w = cvt_pk(y[6], y[7]);
	v_lshlrev_b32_e32 v8, 16, v172
	v_and_b32_e32 v9, 0xffff0000, v172
	v_lshlrev_b32_e32 v10, 16, v173
	v_and_b32_e32 v11, 0xffff0000, v173
	v_lshlrev_b32_e32 v12, 16, v174
	v_and_b32_e32 v13, 0xffff0000, v174
	v_lshlrev_b32_e32 v14, 16, v175
	v_and_b32_e32 v15, 0xffff0000, v175
	v_mul_f32_e32 v16, 0x3d372713, v8
	v_mul_f32_e32 v17, 0x3d372713, v9
	v_mul_f32_e32 v18, 0x3d372713, v10
	v_mul_f32_e32 v19, 0x3d372713, v11
	v_mul_f32_e32 v20, 0x3d372713, v12
	v_mul_f32_e32 v21, 0x3d372713, v13
	v_mul_f32_e32 v22, 0x3d372713, v14
	v_mul_f32_e32 v23, 0x3d372713, v15
	v_mul_f32_e32 v16, v16, v8
	v_mul_f32_e32 v17, v17, v9
	v_mul_f32_e32 v18, v18, v10
	v_mul_f32_e32 v19, v19, v11
	v_mul_f32_e32 v20, v20, v12
	v_mul_f32_e32 v21, v21, v13
	v_mul_f32_e32 v22, v22, v14
	v_mul_f32_e32 v23, v23, v15
	v_fma_f32 v16, v16, v8, v8
	v_fma_f32 v17, v17, v9, v9
	v_fma_f32 v18, v18, v10, v10
	v_fma_f32 v19, v19, v11, v11
	v_fma_f32 v20, v20, v12, v12
	v_fma_f32 v21, v21, v13, v13
	v_fma_f32 v22, v22, v14, v14
	v_fma_f32 v23, v23, v15, v15
	v_mul_f32_e32 v16, 0x3f4c422a, v16
	v_mul_f32_e32 v17, 0x3f4c422a, v17
	v_mul_f32_e32 v18, 0x3f4c422a, v18
	v_mul_f32_e32 v19, 0x3f4c422a, v19
	v_mul_f32_e32 v20, 0x3f4c422a, v20
	v_mul_f32_e32 v21, 0x3f4c422a, v21
	v_mul_f32_e32 v22, 0x3f4c422a, v22
	v_mul_f32_e32 v23, 0x3f4c422a, v23
	v_mul_f32_e32 v16, 0x4038aa3b, v16
	v_mul_f32_e32 v17, 0x4038aa3b, v17
	v_mul_f32_e32 v18, 0x4038aa3b, v18
	v_mul_f32_e32 v19, 0x4038aa3b, v19
	v_mul_f32_e32 v20, 0x4038aa3b, v20
	v_mul_f32_e32 v21, 0x4038aa3b, v21
	v_mul_f32_e32 v22, 0x4038aa3b, v22
	v_mul_f32_e32 v23, 0x4038aa3b, v23
	v_exp_f32_e32 v16, v16
	v_exp_f32_e32 v17, v17
	v_exp_f32_e32 v18, v18
	v_exp_f32_e32 v19, v19
	v_exp_f32_e32 v20, v20
	v_exp_f32_e32 v21, v21
	v_exp_f32_e32 v22, v22
	v_exp_f32_e32 v23, v23
	v_lshlrev_b32_e32 v24, 16, v164
	v_and_b32_e32 v25, 0xffff0000, v164
	v_lshlrev_b32_e32 v26, 16, v165
	v_and_b32_e32 v27, 0xffff0000, v165
	v_lshlrev_b32_e32 v28, 16, v166
	v_and_b32_e32 v29, 0xffff0000, v166
	v_lshlrev_b32_e32 v30, 16, v167
	v_and_b32_e32 v31, 0xffff0000, v167
	v_add_f32_e32 v16, 1.0, v16
	v_add_f32_e32 v17, 1.0, v17
	v_add_f32_e32 v18, 1.0, v18
	v_add_f32_e32 v19, 1.0, v19
	v_add_f32_e32 v20, 1.0, v20
	v_add_f32_e32 v21, 1.0, v21
	v_add_f32_e32 v22, 1.0, v22
	v_add_f32_e32 v23, 1.0, v23
	v_rcp_f32_e32 v16, v16
	v_rcp_f32_e32 v17, v17
	v_rcp_f32_e32 v18, v18
	v_rcp_f32_e32 v19, v19
	v_rcp_f32_e32 v20, v20
	v_rcp_f32_e32 v21, v21
	v_rcp_f32_e32 v22, v22
	v_rcp_f32_e32 v23, v23
	v_lshlrev_b32_e32 v164, 16, v168
	v_and_b32_e32 v168, 0xffff0000, v168
	v_lshlrev_b32_e32 v165, 16, v169
	v_and_b32_e32 v169, 0xffff0000, v169
	v_lshlrev_b32_e32 v166, 16, v170
	v_and_b32_e32 v170, 0xffff0000, v170
	v_lshlrev_b32_e32 v167, 16, v171
	v_and_b32_e32 v171, 0xffff0000, v171
	v_add_f32_e32 v24, v164, v24
	v_add_f32_e32 v25, v168, v25
	v_add_f32_e32 v26, v165, v26
	v_add_f32_e32 v27, v169, v27
	v_add_f32_e32 v28, v166, v28
	v_add_f32_e32 v29, v170, v29
	v_add_f32_e32 v30, v167, v30
	v_add_f32_e32 v31, v171, v31
	v_fma_f32 v16, v16, -2.0, 1.0
	v_fma_f32 v17, v17, -2.0, 1.0
	v_fma_f32 v18, v18, -2.0, 1.0
	v_fma_f32 v19, v19, -2.0, 1.0
	v_fma_f32 v20, v20, -2.0, 1.0
	v_fma_f32 v21, v21, -2.0, 1.0
	v_fma_f32 v22, v22, -2.0, 1.0
	v_fma_f32 v23, v23, -2.0, 1.0
	v_mul_f32_e32 v8, 0.5, v8
	v_mul_f32_e32 v9, 0.5, v9
	v_mul_f32_e32 v10, 0.5, v10
	v_mul_f32_e32 v11, 0.5, v11
	v_mul_f32_e32 v12, 0.5, v12
	v_mul_f32_e32 v13, 0.5, v13
	v_mul_f32_e32 v14, 0.5, v14
	v_mul_f32_e32 v15, 0.5, v15
	v_add_f32_e32 v16, 1.0, v16
	v_add_f32_e32 v17, 1.0, v17
	v_add_f32_e32 v18, 1.0, v18
	v_add_f32_e32 v19, 1.0, v19
	v_add_f32_e32 v20, 1.0, v20
	v_add_f32_e32 v21, 1.0, v21
	v_add_f32_e32 v22, 1.0, v22
	v_add_f32_e32 v23, 1.0, v23
	v_mul_f32_e32 v8, v8, v16
	v_mul_f32_e32 v9, v9, v17
	v_mul_f32_e32 v10, v10, v18
	v_mul_f32_e32 v11, v11, v19
	v_mul_f32_e32 v12, v12, v20
	v_mul_f32_e32 v13, v13, v21
	v_mul_f32_e32 v14, v14, v22
	v_mul_f32_e32 v15, v15, v23
	v_mul_f32_e32 v24, v24, v8
	v_mul_f32_e32 v25, v25, v9
	v_mul_f32_e32 v26, v26, v10
	v_mul_f32_e32 v27, v27, v11
	v_mul_f32_e32 v28, v28, v12
	v_mul_f32_e32 v29, v29, v13
	v_mul_f32_e32 v30, v30, v14
	v_mul_f32_e32 v31, v31, v15
	v_mul_f32_e32 v168, v25, v25
	v_cvt_pk_bf16_f32 v164, v24, v25
	v_fmac_f32_e32 v168, v24, v24
	v_cvt_pk_bf16_f32 v165, v26, v27
	v_fmac_f32_e32 v168, v26, v26
	v_cvt_pk_bf16_f32 v166, v28, v29
	v_fmac_f32_e32 v168, v27, v27
	v_cvt_pk_bf16_f32 v167, v30, v31
	v_fmac_f32_e32 v168, v28, v28
	v_fmac_f32_e32 v168, v29, v29
	v_fmac_f32_e32 v168, v30, v30
	v_fmac_f32_e32 v168, v31, v31
	s_waitcnt vmcnt(12)
; __device__ __forceinline__ unsigned cvt_pk(float lo, float hi) { unsigned r; asm("v_cvt_pk_bf16_f32 %0, %1, %2" : "=v"(r) : "v"(lo), "v"(hi)); return r; }
; __device__ __forceinline__ float bflo(unsigned w) { return __uint_as_float(w << 16); }
; __device__ __forceinline__ float bfhi(unsigned w) { return __uint_as_float(w & 0xffff0000u); }
; __device__ __forceinline__ void rnn_combine(const Params& p) {
;     ...
;         for (int k = 0; k < 4; ++k) { const int rr = r0 + k * NW;
;             float y[8]; float q = 0.f;
; #pragma unroll
;             for (int i = 0; i < 4; ++i) { const unsigned a = hf[k][i], c = hb[k][i], gg = gw[k][i];
; #pragma unroll
;                 for (int e = 0; e < 2; ++e) { const float hs = (e ? bfhi(a) : bflo(a)) + (e ? bfhi(c) : bflo(c)); const float gt = e ? bfhi(gg) : bflo(gg);
;                     const float u = 0.7978845608028654f * (gt + 0.044715f * gt * gt * gt); const float th = 1.0f - 2.0f * __builtin_amdgcn_rcpf(1.0f + __builtin_amdgcn_exp2f(2.8853900817779268f * u));
;                     const float yv = hs * (0.5f * gt * (1.0f + th)); y[2 * i + e] = yv; q += yv * yv; } }
;             q = wave_sum(q);
;             if (rr < MR) { u32x4 w; w.x = cvt_pk(y[0], y[1]); w.y = cvt_pk(y[2], y[3]); w.z = cvt_pk(y[4], y[5]); w.w = cvt_pk(y[6], y[7]);
	v_lshlrev_b32_e32 v8, 16, v184
	v_and_b32_e32 v9, 0xffff0000, v184
	v_lshlrev_b32_e32 v10, 16, v185
	v_and_b32_e32 v11, 0xffff0000, v185
	v_lshlrev_b32_e32 v12, 16, v186
	v_and_b32_e32 v13, 0xffff0000, v186
	v_lshlrev_b32_e32 v14, 16, v187
	v_and_b32_e32 v15, 0xffff0000, v187
	v_mul_f32_e32 v16, 0x3d372713, v8
	v_mul_f32_e32 v17, 0x3d372713, v9
	v_mul_f32_e32 v18, 0x3d372713, v10
	v_mul_f32_e32 v19, 0x3d372713, v11
	v_mul_f32_e32 v20, 0x3d372713, v12
	v_mul_f32_e32 v21, 0x3d372713, v13
	v_mul_f32_e32 v22, 0x3d372713, v14
	v_mul_f32_e32 v23, 0x3d372713, v15
	v_mul_f32_e32 v16, v16, v8
	v_mul_f32_e32 v17, v17, v9
	v_mul_f32_e32 v18, v18, v10
	v_mul_f32_e32 v19, v19, v11
	v_mul_f32_e32 v20, v20, v12
	v_mul_f32_e32 v21, v21, v13
	v_mul_f32_e32 v22, v22, v14
	v_mul_f32_e32 v23, v23, v15
	v_fma_f32 v16, v16, v8, v8
	v_fma_f32 v17, v17, v9, v9
	v_fma_f32 v18, v18, v10, v10
	v_fma_f32 v19, v19, v11, v11
	v_fma_f32 v20, v20, v12, v12
	v_fma_f32 v21, v21, v13, v13
	v_fma_f32 v22, v22, v14, v14
	v_fma_f32 v23, v23, v15, v15
	v_mul_f32_e32 v16, 0x3f4c422a, v16
	v_mul_f32_e32 v17, 0x3f4c422a, v17
	v_mul_f32_e32 v18, 0x3f4c422a, v18
	v_mul_f32_e32 v19, 0x3f4c422a, v19
	v_mul_f32_e32 v20, 0x3f4c422a, v20
	v_mul_f32_e32 v21, 0x3f4c422a, v21
	v_mul_f32_e32 v22, 0x3f4c422a, v22
	v_mul_f32_e32 v23, 0x3f4c422a, v23
	v_mul_f32_e32 v16, 0x4038aa3b, v16
	v_mul_f32_e32 v17, 0x4038aa3b, v17
	v_mul_f32_e32 v18, 0x4038aa3b, v18
	v_mul_f32_e32 v19, 0x4038aa3b, v19
	v_mul_f32_e32 v20, 0x4038aa3b, v20
	v_mul_f32_e32 v21, 0x4038aa3b, v21
	v_mul_f32_e32 v22, 0x4038aa3b, v22
	v_mul_f32_e32 v23, 0x4038aa3b, v23
	v_exp_f32_e32 v16, v16
	v_exp_f32_e32 v17, v17
	v_exp_f32_e32 v18, v18
	v_exp_f32_e32 v19, v19
	v_exp_f32_e32 v20, v20
	v_exp_f32_e32 v21, v21
	v_exp_f32_e32 v22, v22
	v_exp_f32_e32 v23, v23
	v_lshlrev_b32_e32 v24, 16, v176
	v_and_b32_e32 v25, 0xffff0000, v176
	v_lshlrev_b32_e32 v26, 16, v177
	v_and_b32_e32 v27, 0xffff0000, v177
	v_lshlrev_b32_e32 v28, 16, v178
	v_and_b32_e32 v29, 0xffff0000, v178
	v_lshlrev_b32_e32 v30, 16, v179
	v_and_b32_e32 v31, 0xffff0000, v179
	v_add_f32_e32 v16, 1.0, v16
	v_add_f32_e32 v17, 1.0, v17
	v_add_f32_e32 v18, 1.0, v18
	v_add_f32_e32 v19, 1.0, v19
	v_add_f32_e32 v20, 1.0, v20
	v_add_f32_e32 v21, 1.0, v21
	v_add_f32_e32 v22, 1.0, v22
	v_add_f32_e32 v23, 1.0, v23
	v_rcp_f32_e32 v16, v16
	v_rcp_f32_e32 v17, v17
	v_rcp_f32_e32 v18, v18
	v_rcp_f32_e32 v19, v19
	v_rcp_f32_e32 v20, v20
	v_rcp_f32_e32 v21, v21
	v_rcp_f32_e32 v22, v22
	v_rcp_f32_e32 v23, v23
	v_lshlrev_b32_e32 v176, 16, v180
	v_and_b32_e32 v180, 0xffff0000, v180
	v_lshlrev_b32_e32 v177, 16, v181
	v_and_b32_e32 v181, 0xffff0000, v181
	v_lshlrev_b32_e32 v178, 16, v182
	v_and_b32_e32 v182, 0xffff0000, v182
	v_lshlrev_b32_e32 v179, 16, v183
	v_and_b32_e32 v183, 0xffff0000, v183
	v_add_f32_e32 v24, v176, v24
	v_add_f32_e32 v25, v180, v25
	v_add_f32_e32 v26, v177, v26
	v_add_f32_e32 v27, v181, v27
	v_add_f32_e32 v28, v178, v28
	v_add_f32_e32 v29, v182, v29
	v_add_f32_e32 v30, v179, v30
	v_add_f32_e32 v31, v183, v31
	v_fma_f32 v16, v16, -2.0, 1.0
	v_fma_f32 v17, v17, -2.0, 1.0
	v_fma_f32 v18, v18, -2.0, 1.0
	v_fma_f32 v19, v19, -2.0, 1.0
	v_fma_f32 v20, v20, -2.0, 1.0
	v_fma_f32 v21, v21, -2.0, 1.0
	v_fma_f32 v22, v22, -2.0, 1.0
	v_fma_f32 v23, v23, -2.0, 1.0
	v_mul_f32_e32 v8, 0.5, v8
	v_mul_f32_e32 v9, 0.5, v9
	v_mul_f32_e32 v10, 0.5, v10
	v_mul_f32_e32 v11, 0.5, v11
	v_mul_f32_e32 v12, 0.5, v12
	v_mul_f32_e32 v13, 0.5, v13
	v_mul_f32_e32 v14, 0.5, v14
	v_mul_f32_e32 v15, 0.5, v15
	v_add_f32_e32 v16, 1.0, v16
	v_add_f32_e32 v17, 1.0, v17
	v_add_f32_e32 v18, 1.0, v18
	v_add_f32_e32 v19, 1.0, v19
	v_add_f32_e32 v20, 1.0, v20
	v_add_f32_e32 v21, 1.0, v21
	v_add_f32_e32 v22, 1.0, v22
	v_add_f32_e32 v23, 1.0, v23
	v_mul_f32_e32 v8, v8, v16
	v_mul_f32_e32 v9, v9, v17
	v_mul_f32_e32 v10, v10, v18
	v_mul_f32_e32 v11, v11, v19
	v_mul_f32_e32 v12, v12, v20
	v_mul_f32_e32 v13, v13, v21
	v_mul_f32_e32 v14, v14, v22
	v_mul_f32_e32 v15, v15, v23
	v_mul_f32_e32 v24, v24, v8
	v_mul_f32_e32 v25, v25, v9
	v_mul_f32_e32 v26, v26, v10
	v_mul_f32_e32 v27, v27, v11
	v_mul_f32_e32 v28, v28, v12
	v_mul_f32_e32 v29, v29, v13
	v_mul_f32_e32 v30, v30, v14
	v_mul_f32_e32 v31, v31, v15
	v_mul_f32_e32 v180, v25, v25
	v_cvt_pk_bf16_f32 v176, v24, v25
	v_fmac_f32_e32 v180, v24, v24
	v_cvt_pk_bf16_f32 v177, v26, v27
	v_fmac_f32_e32 v180, v26, v26
	v_cvt_pk_bf16_f32 v178, v28, v29
	v_fmac_f32_e32 v180, v27, v27
	v_cvt_pk_bf16_f32 v179, v30, v31
	v_fmac_f32_e32 v180, v28, v28
	v_fmac_f32_e32 v180, v29, v29
	v_fmac_f32_e32 v180, v30, v30
	v_fmac_f32_e32 v180, v31, v31
	s_waitcnt vmcnt(9)
; __device__ __forceinline__ unsigned cvt_pk(float lo, float hi) { unsigned r; asm("v_cvt_pk_bf16_f32 %0, %1, %2" : "=v"(r) : "v"(lo), "v"(hi)); return r; }
; __device__ __forceinline__ float bflo(unsigned w) { return __uint_as_float(w << 16); }
; __device__ __forceinline__ float bfhi(unsigned w) { return __uint_as_float(w & 0xffff0000u); }
; __device__ __forceinline__ void rnn_combine(const Params& p) {
;     ...
;         for (int k = 0; k < 4; ++k) { const int rr = r0 + k * NW;
;             float y[8]; float q = 0.f;
; #pragma unroll
;             for (int i = 0; i < 4; ++i) { const unsigned a = hf[k][i], c = hb[k][i], gg = gw[k][i];
; #pragma unroll
;                 for (int e = 0; e < 2; ++e) { const float hs = (e ? bfhi(a) : bflo(a)) + (e ? bfhi(c) : bflo(c)); const float gt = e ? bfhi(gg) : bflo(gg);
;                     const float u = 0.7978845608028654f * (gt + 0.044715f * gt * gt * gt); const float th = 1.0f - 2.0f * __builtin_amdgcn_rcpf(1.0f + __builtin_amdgcn_exp2f(2.8853900817779268f * u));
;                     const float yv = hs * (0.5f * gt * (1.0f + th)); y[2 * i + e] = yv; q += yv * yv; } }
;             q = wave_sum(q);
;             if (rr < MR) { u32x4 w; w.x = cvt_pk(y[0], y[1]); w.y = cvt_pk(y[2], y[3]); w.z = cvt_pk(y[4], y[5]); w.w = cvt_pk(y[6], y[7]);
	v_lshlrev_b32_e32 v8, 16, v196
	v_and_b32_e32 v9, 0xffff0000, v196
	v_lshlrev_b32_e32 v10, 16, v197
	v_and_b32_e32 v11, 0xffff0000, v197
	v_lshlrev_b32_e32 v12, 16, v198
	v_and_b32_e32 v13, 0xffff0000, v198
	v_lshlrev_b32_e32 v14, 16, v199
	v_and_b32_e32 v15, 0xffff0000, v199
	v_mul_f32_e32 v16, 0x3d372713, v8
	v_mul_f32_e32 v17, 0x3d372713, v9
	v_mul_f32_e32 v18, 0x3d372713, v10
	v_mul_f32_e32 v19, 0x3d372713, v11
	v_mul_f32_e32 v20, 0x3d372713, v12
	v_mul_f32_e32 v21, 0x3d372713, v13
	v_mul_f32_e32 v22, 0x3d372713, v14
	v_mul_f32_e32 v23, 0x3d372713, v15
	v_mul_f32_e32 v16, v16, v8
	v_mul_f32_e32 v17, v17, v9
	v_mul_f32_e32 v18, v18, v10
	v_mul_f32_e32 v19, v19, v11
	v_mul_f32_e32 v20, v20, v12
	v_mul_f32_e32 v21, v21, v13
	v_mul_f32_e32 v22, v22, v14
	v_mul_f32_e32 v23, v23, v15
	v_fma_f32 v16, v16, v8, v8
	v_fma_f32 v17, v17, v9, v9
	v_fma_f32 v18, v18, v10, v10
	v_fma_f32 v19, v19, v11, v11
	v_fma_f32 v20, v20, v12, v12
	v_fma_f32 v21, v21, v13, v13
	v_fma_f32 v22, v22, v14, v14
	v_fma_f32 v23, v23, v15, v15
	v_mul_f32_e32 v16, 0x3f4c422a, v16
	v_mul_f32_e32 v17, 0x3f4c422a, v17
	v_mul_f32_e32 v18, 0x3f4c422a, v18
	v_mul_f32_e32 v19, 0x3f4c422a, v19
	v_mul_f32_e32 v20, 0x3f4c422a, v20
	v_mul_f32_e32 v21, 0x3f4c422a, v21
	v_mul_f32_e32 v22, 0x3f4c422a, v22
	v_mul_f32_e32 v23, 0x3f4c422a, v23
	v_mul_f32_e32 v16, 0x4038aa3b, v16
	v_mul_f32_e32 v17, 0x4038aa3b, v17
	v_mul_f32_e32 v18, 0x4038aa3b, v18
	v_mul_f32_e32 v19, 0x4038aa3b, v19
	v_mul_f32_e32 v20, 0x4038aa3b, v20
	v_mul_f32_e32 v21, 0x4038aa3b, v21
	v_mul_f32_e32 v22, 0x4038aa3b, v22
	v_mul_f32_e32 v23, 0x4038aa3b, v23
	v_exp_f32_e32 v16, v16
	v_exp_f32_e32 v17, v17
	v_exp_f32_e32 v18, v18
	v_exp_f32_e32 v19, v19
	v_exp_f32_e32 v20, v20
	v_exp_f32_e32 v21, v21
	v_exp_f32_e32 v22, v22
	v_exp_f32_e32 v23, v23
	v_lshlrev_b32_e32 v24, 16, v188
	v_and_b32_e32 v25, 0xffff0000, v188
	v_lshlrev_b32_e32 v26, 16, v189
	v_and_b32_e32 v27, 0xffff0000, v189
	v_lshlrev_b32_e32 v28, 16, v190
	v_and_b32_e32 v29, 0xffff0000, v190
	v_lshlrev_b32_e32 v30, 16, v191
	v_and_b32_e32 v31, 0xffff0000, v191
	v_add_f32_e32 v16, 1.0, v16
	v_add_f32_e32 v17, 1.0, v17
	v_add_f32_e32 v18, 1.0, v18
	v_add_f32_e32 v19, 1.0, v19
	v_add_f32_e32 v20, 1.0, v20
	v_add_f32_e32 v21, 1.0, v21
	v_add_f32_e32 v22, 1.0, v22
	v_add_f32_e32 v23, 1.0, v23
	v_rcp_f32_e32 v16, v16
	v_rcp_f32_e32 v17, v17
	v_rcp_f32_e32 v18, v18
	v_rcp_f32_e32 v19, v19
	v_rcp_f32_e32 v20, v20
	v_rcp_f32_e32 v21, v21
	v_rcp_f32_e32 v22, v22
	v_rcp_f32_e32 v23, v23
	v_lshlrev_b32_e32 v188, 16, v192
	v_and_b32_e32 v192, 0xffff0000, v192
	v_lshlrev_b32_e32 v189, 16, v193
	v_and_b32_e32 v193, 0xffff0000, v193
	v_lshlrev_b32_e32 v190, 16, v194
	v_and_b32_e32 v194, 0xffff0000, v194
	v_lshlrev_b32_e32 v191, 16, v195
	v_and_b32_e32 v195, 0xffff0000, v195
	v_add_f32_e32 v24, v188, v24
	v_add_f32_e32 v25, v192, v25
	v_add_f32_e32 v26, v189, v26
	v_add_f32_e32 v27, v193, v27
	v_add_f32_e32 v28, v190, v28
	v_add_f32_e32 v29, v194, v29
	v_add_f32_e32 v30, v191, v30
	v_add_f32_e32 v31, v195, v31
	v_fma_f32 v16, v16, -2.0, 1.0
	v_fma_f32 v17, v17, -2.0, 1.0
	v_fma_f32 v18, v18, -2.0, 1.0
	v_fma_f32 v19, v19, -2.0, 1.0
	v_fma_f32 v20, v20, -2.0, 1.0
	v_fma_f32 v21, v21, -2.0, 1.0
	v_fma_f32 v22, v22, -2.0, 1.0
	v_fma_f32 v23, v23, -2.0, 1.0
	v_mul_f32_e32 v8, 0.5, v8
	v_mul_f32_e32 v9, 0.5, v9
	v_mul_f32_e32 v10, 0.5, v10
	v_mul_f32_e32 v11, 0.5, v11
	v_mul_f32_e32 v12, 0.5, v12
	v_mul_f32_e32 v13, 0.5, v13
	v_mul_f32_e32 v14, 0.5, v14
	v_mul_f32_e32 v15, 0.5, v15
	v_add_f32_e32 v16, 1.0, v16
	v_add_f32_e32 v17, 1.0, v17
	v_add_f32_e32 v18, 1.0, v18
	v_add_f32_e32 v19, 1.0, v19
	v_add_f32_e32 v20, 1.0, v20
	v_add_f32_e32 v21, 1.0, v21
	v_add_f32_e32 v22, 1.0, v22
	v_add_f32_e32 v23, 1.0, v23
	v_mul_f32_e32 v8, v8, v16
	v_mul_f32_e32 v9, v9, v17
	v_mul_f32_e32 v10, v10, v18
	v_mul_f32_e32 v11, v11, v19
	v_mul_f32_e32 v12, v12, v20
	v_mul_f32_e32 v13, v13, v21
	v_mul_f32_e32 v14, v14, v22
	v_mul_f32_e32 v15, v15, v23
	v_mul_f32_e32 v24, v24, v8
	v_mul_f32_e32 v25, v25, v9
	v_mul_f32_e32 v26, v26, v10
	v_mul_f32_e32 v27, v27, v11
	v_mul_f32_e32 v28, v28, v12
	v_mul_f32_e32 v29, v29, v13
	v_mul_f32_e32 v30, v30, v14
	v_mul_f32_e32 v31, v31, v15
	v_mul_f32_e32 v192, v25, v25
	v_cvt_pk_bf16_f32 v188, v24, v25
	v_fmac_f32_e32 v192, v24, v24
	v_cvt_pk_bf16_f32 v189, v26, v27
	v_fmac_f32_e32 v192, v26, v26
	v_cvt_pk_bf16_f32 v190, v28, v29
	v_fmac_f32_e32 v192, v27, v27
	v_cvt_pk_bf16_f32 v191, v30, v31
	v_fmac_f32_e32 v192, v28, v28
	v_fmac_f32_e32 v192, v29, v29
	v_fmac_f32_e32 v192, v30, v30
	v_fmac_f32_e32 v192, v31, v31
	s_waitcnt vmcnt(6)
; __device__ __forceinline__ unsigned cvt_pk(float lo, float hi) { unsigned r; asm("v_cvt_pk_bf16_f32 %0, %1, %2" : "=v"(r) : "v"(lo), "v"(hi)); return r; }
; __device__ __forceinline__ float bflo(unsigned w) { return __uint_as_float(w << 16); }
; __device__ __forceinline__ float bfhi(unsigned w) { return __uint_as_float(w & 0xffff0000u); }
; __device__ __forceinline__ void rnn_combine(const Params& p) {
;     ...
;         for (int k = 0; k < 4; ++k) { const int rr = r0 + k * NW;
;             float y[8]; float q = 0.f;
; #pragma unroll
;             for (int i = 0; i < 4; ++i) { const unsigned a = hf[k][i], c = hb[k][i], gg = gw[k][i];
; #pragma unroll
;                 for (int e = 0; e < 2; ++e) { const float hs = (e ? bfhi(a) : bflo(a)) + (e ? bfhi(c) : bflo(c)); const float gt = e ? bfhi(gg) : bflo(gg);
;                     const float u = 0.7978845608028654f * (gt + 0.044715f * gt * gt * gt); const float th = 1.0f - 2.0f * __builtin_amdgcn_rcpf(1.0f + __builtin_amdgcn_exp2f(2.8853900817779268f * u));
;                     const float yv = hs * (0.5f * gt * (1.0f + th)); y[2 * i + e] = yv; q += yv * yv; } }
;             q = wave_sum(q);
;             if (rr < MR) { u32x4 w; w.x = cvt_pk(y[0], y[1]); w.y = cvt_pk(y[2], y[3]); w.z = cvt_pk(y[4], y[5]); w.w = cvt_pk(y[6], y[7]);
	v_lshlrev_b32_e32 v8, 16, v208
	v_and_b32_e32 v9, 0xffff0000, v208
	v_lshlrev_b32_e32 v10, 16, v209
	v_and_b32_e32 v11, 0xffff0000, v209
	v_lshlrev_b32_e32 v12, 16, v210
	v_and_b32_e32 v13, 0xffff0000, v210
	v_lshlrev_b32_e32 v14, 16, v211
	v_and_b32_e32 v15, 0xffff0000, v211
	v_mul_f32_e32 v16, 0x3d372713, v8
	v_mul_f32_e32 v17, 0x3d372713, v9
	v_mul_f32_e32 v18, 0x3d372713, v10
	v_mul_f32_e32 v19, 0x3d372713, v11
	v_mul_f32_e32 v20, 0x3d372713, v12
	v_mul_f32_e32 v21, 0x3d372713, v13
	v_mul_f32_e32 v22, 0x3d372713, v14
	v_mul_f32_e32 v23, 0x3d372713, v15
	v_mul_f32_e32 v16, v16, v8
	v_mul_f32_e32 v17, v17, v9
	v_mul_f32_e32 v18, v18, v10
	v_mul_f32_e32 v19, v19, v11
	v_mul_f32_e32 v20, v20, v12
	v_mul_f32_e32 v21, v21, v13
	v_mul_f32_e32 v22, v22, v14
	v_mul_f32_e32 v23, v23, v15
	v_fma_f32 v16, v16, v8, v8
	v_fma_f32 v17, v17, v9, v9
	v_fma_f32 v18, v18, v10, v10
	v_fma_f32 v19, v19, v11, v11
	v_fma_f32 v20, v20, v12, v12
	v_fma_f32 v21, v21, v13, v13
	v_fma_f32 v22, v22, v14, v14
	v_fma_f32 v23, v23, v15, v15
	v_mul_f32_e32 v16, 0x3f4c422a, v16
	v_mul_f32_e32 v17, 0x3f4c422a, v17
	v_mul_f32_e32 v18, 0x3f4c422a, v18
	v_mul_f32_e32 v19, 0x3f4c422a, v19
	v_mul_f32_e32 v20, 0x3f4c422a, v20
	v_mul_f32_e32 v21, 0x3f4c422a, v21
	v_mul_f32_e32 v22, 0x3f4c422a, v22
	v_mul_f32_e32 v23, 0x3f4c422a, v23
	v_mul_f32_e32 v16, 0x4038aa3b, v16
	v_mul_f32_e32 v17, 0x4038aa3b, v17
	v_mul_f32_e32 v18, 0x4038aa3b, v18
	v_mul_f32_e32 v19, 0x4038aa3b, v19
	v_mul_f32_e32 v20, 0x4038aa3b, v20
	v_mul_f32_e32 v21, 0x4038aa3b, v21
	v_mul_f32_e32 v22, 0x4038aa3b, v22
	v_mul_f32_e32 v23, 0x4038aa3b, v23
	v_exp_f32_e32 v16, v16
	v_exp_f32_e32 v17, v17
	v_exp_f32_e32 v18, v18
	v_exp_f32_e32 v19, v19
	v_exp_f32_e32 v20, v20
	v_exp_f32_e32 v21, v21
	v_exp_f32_e32 v22, v22
	v_exp_f32_e32 v23, v23
	v_lshlrev_b32_e32 v24, 16, v200
	v_and_b32_e32 v25, 0xffff0000, v200
	v_lshlrev_b32_e32 v26, 16, v201
	v_and_b32_e32 v27, 0xffff0000, v201
	v_lshlrev_b32_e32 v28, 16, v202
	v_and_b32_e32 v29, 0xffff0000, v202
	v_lshlrev_b32_e32 v30, 16, v203
	v_and_b32_e32 v31, 0xffff0000, v203
	v_add_f32_e32 v16, 1.0, v16
	v_add_f32_e32 v17, 1.0, v17
	v_add_f32_e32 v18, 1.0, v18
	v_add_f32_e32 v19, 1.0, v19
	v_add_f32_e32 v20, 1.0, v20
	v_add_f32_e32 v21, 1.0, v21
	v_add_f32_e32 v22, 1.0, v22
	v_add_f32_e32 v23, 1.0, v23
	v_rcp_f32_e32 v16, v16
	v_rcp_f32_e32 v17, v17
	v_rcp_f32_e32 v18, v18
	v_rcp_f32_e32 v19, v19
	v_rcp_f32_e32 v20, v20
	v_rcp_f32_e32 v21, v21
	v_rcp_f32_e32 v22, v22
	v_rcp_f32_e32 v23, v23
	v_lshlrev_b32_e32 v200, 16, v204
	v_and_b32_e32 v204, 0xffff0000, v204
	v_lshlrev_b32_e32 v201, 16, v205
	v_and_b32_e32 v205, 0xffff0000, v205
	v_lshlrev_b32_e32 v202, 16, v206
	v_and_b32_e32 v206, 0xffff0000, v206
	v_lshlrev_b32_e32 v203, 16, v207
	v_and_b32_e32 v207, 0xffff0000, v207
	v_add_f32_e32 v24, v200, v24
	v_add_f32_e32 v25, v204, v25
	v_add_f32_e32 v26, v201, v26
	v_add_f32_e32 v27, v205, v27
	v_add_f32_e32 v28, v202, v28
	v_add_f32_e32 v29, v206, v29
	v_add_f32_e32 v30, v203, v30
	v_add_f32_e32 v31, v207, v31
	v_fma_f32 v16, v16, -2.0, 1.0
	v_fma_f32 v17, v17, -2.0, 1.0
	v_fma_f32 v18, v18, -2.0, 1.0
	v_fma_f32 v19, v19, -2.0, 1.0
	v_fma_f32 v20, v20, -2.0, 1.0
	v_fma_f32 v21, v21, -2.0, 1.0
	v_fma_f32 v22, v22, -2.0, 1.0
	v_fma_f32 v23, v23, -2.0, 1.0
	v_mul_f32_e32 v8, 0.5, v8
	v_mul_f32_e32 v9, 0.5, v9
	v_mul_f32_e32 v10, 0.5, v10
	v_mul_f32_e32 v11, 0.5, v11
	v_mul_f32_e32 v12, 0.5, v12
	v_mul_f32_e32 v13, 0.5, v13
	v_mul_f32_e32 v14, 0.5, v14
	v_mul_f32_e32 v15, 0.5, v15
	v_add_f32_e32 v16, 1.0, v16
	v_add_f32_e32 v17, 1.0, v17
	v_add_f32_e32 v18, 1.0, v18
	v_add_f32_e32 v19, 1.0, v19
	v_add_f32_e32 v20, 1.0, v20
	v_add_f32_e32 v21, 1.0, v21
	v_add_f32_e32 v22, 1.0, v22
	v_add_f32_e32 v23, 1.0, v23
	v_mul_f32_e32 v8, v8, v16
	v_mul_f32_e32 v9, v9, v17
	v_mul_f32_e32 v10, v10, v18
	v_mul_f32_e32 v11, v11, v19
	v_mul_f32_e32 v12, v12, v20
	v_mul_f32_e32 v13, v13, v21
	v_mul_f32_e32 v14, v14, v22
	v_mul_f32_e32 v15, v15, v23
	v_mul_f32_e32 v24, v24, v8
	v_mul_f32_e32 v25, v25, v9
	v_mul_f32_e32 v26, v26, v10
	v_mul_f32_e32 v27, v27, v11
	v_mul_f32_e32 v28, v28, v12
	v_mul_f32_e32 v29, v29, v13
	v_mul_f32_e32 v30, v30, v14
	v_mul_f32_e32 v31, v31, v15
	v_mul_f32_e32 v204, v25, v25
	v_cvt_pk_bf16_f32 v200, v24, v25
	v_fmac_f32_e32 v204, v24, v24
	v_cvt_pk_bf16_f32 v201, v26, v27
	v_fmac_f32_e32 v204, v26, v26
	v_cvt_pk_bf16_f32 v202, v28, v29
	v_fmac_f32_e32 v204, v27, v27
	v_cvt_pk_bf16_f32 v203, v30, v31
	v_fmac_f32_e32 v204, v28, v28
	v_fmac_f32_e32 v204, v29, v29
	v_fmac_f32_e32 v204, v30, v30
	v_fmac_f32_e32 v204, v31, v31
	s_waitcnt vmcnt(3)
; __device__ __forceinline__ unsigned cvt_pk(float lo, float hi) { unsigned r; asm("v_cvt_pk_bf16_f32 %0, %1, %2" : "=v"(r) : "v"(lo), "v"(hi)); return r; }
; __device__ __forceinline__ float bflo(unsigned w) { return __uint_as_float(w << 16); }
; __device__ __forceinline__ float bfhi(unsigned w) { return __uint_as_float(w & 0xffff0000u); }
; __device__ __forceinline__ void rnn_combine(const Params& p) {
;     ...
;         for (int k = 0; k < 4; ++k) { const int rr = r0 + k * NW;
;             float y[8]; float q = 0.f;
; #pragma unroll
;             for (int i = 0; i < 4; ++i) { const unsigned a = hf[k][i], c = hb[k][i], gg = gw[k][i];
; #pragma unroll
;                 for (int e = 0; e < 2; ++e) { const float hs = (e ? bfhi(a) : bflo(a)) + (e ? bfhi(c) : bflo(c)); const float gt = e ? bfhi(gg) : bflo(gg);
;                     const float u = 0.7978845608028654f * (gt + 0.044715f * gt * gt * gt); const float th = 1.0f - 2.0f * __builtin_amdgcn_rcpf(1.0f + __builtin_amdgcn_exp2f(2.8853900817779268f * u));
;                     const float yv = hs * (0.5f * gt * (1.0f + th)); y[2 * i + e] = yv; q += yv * yv; } }
;             q = wave_sum(q);
;             if (rr < MR) { u32x4 w; w.x = cvt_pk(y[0], y[1]); w.y = cvt_pk(y[2], y[3]); w.z = cvt_pk(y[4], y[5]); w.w = cvt_pk(y[6], y[7]);
	v_lshlrev_b32_e32 v8, 16, v220
	v_and_b32_e32 v9, 0xffff0000, v220
	v_lshlrev_b32_e32 v10, 16, v221
	v_and_b32_e32 v11, 0xffff0000, v221
	v_lshlrev_b32_e32 v12, 16, v222
	v_and_b32_e32 v13, 0xffff0000, v222
	v_lshlrev_b32_e32 v14, 16, v223
	v_and_b32_e32 v15, 0xffff0000, v223
	v_mul_f32_e32 v16, 0x3d372713, v8
	v_mul_f32_e32 v17, 0x3d372713, v9
	v_mul_f32_e32 v18, 0x3d372713, v10
	v_mul_f32_e32 v19, 0x3d372713, v11
	v_mul_f32_e32 v20, 0x3d372713, v12
	v_mul_f32_e32 v21, 0x3d372713, v13
	v_mul_f32_e32 v22, 0x3d372713, v14
	v_mul_f32_e32 v23, 0x3d372713, v15
	v_mul_f32_e32 v16, v16, v8
	v_mul_f32_e32 v17, v17, v9
	v_mul_f32_e32 v18, v18, v10
	v_mul_f32_e32 v19, v19, v11
	v_mul_f32_e32 v20, v20, v12
	v_mul_f32_e32 v21, v21, v13
	v_mul_f32_e32 v22, v22, v14
	v_mul_f32_e32 v23, v23, v15
	v_fma_f32 v16, v16, v8, v8
	v_fma_f32 v17, v17, v9, v9
	v_fma_f32 v18, v18, v10, v10
	v_fma_f32 v19, v19, v11, v11
	v_fma_f32 v20, v20, v12, v12
	v_fma_f32 v21, v21, v13, v13
	v_fma_f32 v22, v22, v14, v14
	v_fma_f32 v23, v23, v15, v15
	v_mul_f32_e32 v16, 0x3f4c422a, v16
	v_mul_f32_e32 v17, 0x3f4c422a, v17
	v_mul_f32_e32 v18, 0x3f4c422a, v18
	v_mul_f32_e32 v19, 0x3f4c422a, v19
	v_mul_f32_e32 v20, 0x3f4c422a, v20
	v_mul_f32_e32 v21, 0x3f4c422a, v21
	v_mul_f32_e32 v22, 0x3f4c422a, v22
	v_mul_f32_e32 v23, 0x3f4c422a, v23
	v_mul_f32_e32 v16, 0x4038aa3b, v16
	v_mul_f32_e32 v17, 0x4038aa3b, v17
	v_mul_f32_e32 v18, 0x4038aa3b, v18
	v_mul_f32_e32 v19, 0x4038aa3b, v19
	v_mul_f32_e32 v20, 0x4038aa3b, v20
	v_mul_f32_e32 v21, 0x4038aa3b, v21
	v_mul_f32_e32 v22, 0x4038aa3b, v22
	v_mul_f32_e32 v23, 0x4038aa3b, v23
	v_exp_f32_e32 v16, v16
	v_exp_f32_e32 v17, v17
	v_exp_f32_e32 v18, v18
	v_exp_f32_e32 v19, v19
	v_exp_f32_e32 v20, v20
	v_exp_f32_e32 v21, v21
	v_exp_f32_e32 v22, v22
	v_exp_f32_e32 v23, v23
	v_lshlrev_b32_e32 v24, 16, v212
	v_and_b32_e32 v25, 0xffff0000, v212
	v_lshlrev_b32_e32 v26, 16, v213
	v_and_b32_e32 v27, 0xffff0000, v213
	v_lshlrev_b32_e32 v28, 16, v214
	v_and_b32_e32 v29, 0xffff0000, v214
	v_lshlrev_b32_e32 v30, 16, v215
	v_and_b32_e32 v31, 0xffff0000, v215
	v_add_f32_e32 v16, 1.0, v16
	v_add_f32_e32 v17, 1.0, v17
	v_add_f32_e32 v18, 1.0, v18
	v_add_f32_e32 v19, 1.0, v19
	v_add_f32_e32 v20, 1.0, v20
	v_add_f32_e32 v21, 1.0, v21
	v_add_f32_e32 v22, 1.0, v22
	v_add_f32_e32 v23, 1.0, v23
	v_rcp_f32_e32 v16, v16
	v_rcp_f32_e32 v17, v17
	v_rcp_f32_e32 v18, v18
	v_rcp_f32_e32 v19, v19
	v_rcp_f32_e32 v20, v20
	v_rcp_f32_e32 v21, v21
	v_rcp_f32_e32 v22, v22
	v_rcp_f32_e32 v23, v23
	v_lshlrev_b32_e32 v212, 16, v216
	v_and_b32_e32 v216, 0xffff0000, v216
	v_lshlrev_b32_e32 v213, 16, v217
	v_and_b32_e32 v217, 0xffff0000, v217
	v_lshlrev_b32_e32 v214, 16, v218
	v_and_b32_e32 v218, 0xffff0000, v218
	v_lshlrev_b32_e32 v215, 16, v219
	v_and_b32_e32 v219, 0xffff0000, v219
	v_add_f32_e32 v24, v212, v24
	v_add_f32_e32 v25, v216, v25
	v_add_f32_e32 v26, v213, v26
	v_add_f32_e32 v27, v217, v27
	v_add_f32_e32 v28, v214, v28
	v_add_f32_e32 v29, v218, v29
	v_add_f32_e32 v30, v215, v30
	v_add_f32_e32 v31, v219, v31
	v_fma_f32 v16, v16, -2.0, 1.0
	v_fma_f32 v17, v17, -2.0, 1.0
	v_fma_f32 v18, v18, -2.0, 1.0
	v_fma_f32 v19, v19, -2.0, 1.0
	v_fma_f32 v20, v20, -2.0, 1.0
	v_fma_f32 v21, v21, -2.0, 1.0
	v_fma_f32 v22, v22, -2.0, 1.0
	v_fma_f32 v23, v23, -2.0, 1.0
	v_mul_f32_e32 v8, 0.5, v8
	v_mul_f32_e32 v9, 0.5, v9
	v_mul_f32_e32 v10, 0.5, v10
	v_mul_f32_e32 v11, 0.5, v11
	v_mul_f32_e32 v12, 0.5, v12
	v_mul_f32_e32 v13, 0.5, v13
	v_mul_f32_e32 v14, 0.5, v14
	v_mul_f32_e32 v15, 0.5, v15
	v_add_f32_e32 v16, 1.0, v16
	v_add_f32_e32 v17, 1.0, v17
	v_add_f32_e32 v18, 1.0, v18
	v_add_f32_e32 v19, 1.0, v19
	v_add_f32_e32 v20, 1.0, v20
	v_add_f32_e32 v21, 1.0, v21
	v_add_f32_e32 v22, 1.0, v22
	v_add_f32_e32 v23, 1.0, v23
	v_mul_f32_e32 v8, v8, v16
	v_mul_f32_e32 v9, v9, v17
	v_mul_f32_e32 v10, v10, v18
	v_mul_f32_e32 v11, v11, v19
	v_mul_f32_e32 v12, v12, v20
	v_mul_f32_e32 v13, v13, v21
	v_mul_f32_e32 v14, v14, v22
	v_mul_f32_e32 v15, v15, v23
	v_mul_f32_e32 v24, v24, v8
	v_mul_f32_e32 v25, v25, v9
	v_mul_f32_e32 v26, v26, v10
	v_mul_f32_e32 v27, v27, v11
	v_mul_f32_e32 v28, v28, v12
	v_mul_f32_e32 v29, v29, v13
	v_mul_f32_e32 v30, v30, v14
	v_mul_f32_e32 v31, v31, v15
	v_mul_f32_e32 v216, v25, v25
	v_cvt_pk_bf16_f32 v212, v24, v25
	v_fmac_f32_e32 v216, v24, v24
	v_cvt_pk_bf16_f32 v213, v26, v27
	v_fmac_f32_e32 v216, v26, v26
	v_cvt_pk_bf16_f32 v214, v28, v29
	v_fmac_f32_e32 v216, v27, v27
	v_cvt_pk_bf16_f32 v215, v30, v31
	v_fmac_f32_e32 v216, v28, v28
	v_fmac_f32_e32 v216, v29, v29
	v_fmac_f32_e32 v216, v30, v30
	v_fmac_f32_e32 v216, v31, v31
	s_waitcnt vmcnt(0)
; __device__ __forceinline__ unsigned cvt_pk(float lo, float hi) { unsigned r; asm("v_cvt_pk_bf16_f32 %0, %1, %2" : "=v"(r) : "v"(lo), "v"(hi)); return r; }
; __device__ __forceinline__ float bflo(unsigned w) { return __uint_as_float(w << 16); }
; __device__ __forceinline__ float bfhi(unsigned w) { return __uint_as_float(w & 0xffff0000u); }
; __device__ __forceinline__ float wave_sum(float v) {
; #pragma unroll
;     for (int o = 1; o < 64; o <<= 1) v += __shfl_xor(v, o);
;     return v;
; __device__ __forceinline__ void rnn_combine(const Params& p) {
;     ...
;         for (int k = 0; k < 4; ++k) { const int rr = r0 + k * NW;
;             float y[8]; float q = 0.f;
; #pragma unroll
;             for (int i = 0; i < 4; ++i) { const unsigned a = hf[k][i], c = hb[k][i], gg = gw[k][i];
; #pragma unroll
;                 for (int e = 0; e < 2; ++e) { const float hs = (e ? bfhi(a) : bflo(a)) + (e ? bfhi(c) : bflo(c)); const float gt = e ? bfhi(gg) : bflo(gg);
;                     const float u = 0.7978845608028654f * (gt + 0.044715f * gt * gt * gt); const float th = 1.0f - 2.0f * __builtin_amdgcn_rcpf(1.0f + __builtin_amdgcn_exp2f(2.8853900817779268f * u));
;                     const float yv = hs * (0.5f * gt * (1.0f + th)); y[2 * i + e] = yv; q += yv * yv; } }
;             q = wave_sum(q);
;             if (rr < MR) { u32x4 w; w.x = cvt_pk(y[0], y[1]); w.y = cvt_pk(y[2], y[3]); w.z = cvt_pk(y[4], y[5]); w.w = cvt_pk(y[6], y[7]);
;                 *(u32x4*)(MIX + (size_t)rr * DM + 512 + 8 * lane) = w;
;                 if (lane == 0) ss_b[rr] = q; } }
	v_lshlrev_b32_e32 v8, 16, v232
	v_and_b32_e32 v9, 0xffff0000, v232
	v_lshlrev_b32_e32 v10, 16, v233
	v_and_b32_e32 v11, 0xffff0000, v233
	v_lshlrev_b32_e32 v12, 16, v234
	v_and_b32_e32 v13, 0xffff0000, v234
	v_lshlrev_b32_e32 v14, 16, v235
	v_and_b32_e32 v15, 0xffff0000, v235
	v_mul_f32_e32 v16, 0x3d372713, v8
	v_mul_f32_e32 v17, 0x3d372713, v9
	v_mul_f32_e32 v18, 0x3d372713, v10
	v_mul_f32_e32 v19, 0x3d372713, v11
	v_mul_f32_e32 v20, 0x3d372713, v12
	v_mul_f32_e32 v21, 0x3d372713, v13
	v_mul_f32_e32 v22, 0x3d372713, v14
	v_mul_f32_e32 v23, 0x3d372713, v15
	v_mul_f32_e32 v16, v16, v8
	v_mul_f32_e32 v17, v17, v9
	v_mul_f32_e32 v18, v18, v10
	v_mul_f32_e32 v19, v19, v11
	v_mul_f32_e32 v20, v20, v12
	v_mul_f32_e32 v21, v21, v13
	v_mul_f32_e32 v22, v22, v14
	v_mul_f32_e32 v23, v23, v15
	v_fma_f32 v16, v16, v8, v8
	v_fma_f32 v17, v17, v9, v9
	v_fma_f32 v18, v18, v10, v10
	v_fma_f32 v19, v19, v11, v11
	v_fma_f32 v20, v20, v12, v12
	v_fma_f32 v21, v21, v13, v13
	v_fma_f32 v22, v22, v14, v14
	v_fma_f32 v23, v23, v15, v15
	v_mul_f32_e32 v16, 0x3f4c422a, v16
	v_mul_f32_e32 v17, 0x3f4c422a, v17
	v_mul_f32_e32 v18, 0x3f4c422a, v18
	v_mul_f32_e32 v19, 0x3f4c422a, v19
	v_mul_f32_e32 v20, 0x3f4c422a, v20
	v_mul_f32_e32 v21, 0x3f4c422a, v21
	v_mul_f32_e32 v22, 0x3f4c422a, v22
	v_mul_f32_e32 v23, 0x3f4c422a, v23
	v_mul_f32_e32 v16, 0x4038aa3b, v16
	v_mul_f32_e32 v17, 0x4038aa3b, v17
	v_mul_f32_e32 v18, 0x4038aa3b, v18
	v_mul_f32_e32 v19, 0x4038aa3b, v19
	v_mul_f32_e32 v20, 0x4038aa3b, v20
	v_mul_f32_e32 v21, 0x4038aa3b, v21
	v_mul_f32_e32 v22, 0x4038aa3b, v22
	v_mul_f32_e32 v23, 0x4038aa3b, v23
	v_exp_f32_e32 v16, v16
	v_exp_f32_e32 v17, v17
	v_exp_f32_e32 v18, v18
	v_exp_f32_e32 v19, v19
	v_exp_f32_e32 v20, v20
	v_exp_f32_e32 v21, v21
	v_exp_f32_e32 v22, v22
	v_exp_f32_e32 v23, v23
	v_lshlrev_b32_e32 v24, 16, v224
	v_and_b32_e32 v25, 0xffff0000, v224
	v_lshlrev_b32_e32 v26, 16, v225
	v_and_b32_e32 v27, 0xffff0000, v225
	v_lshlrev_b32_e32 v28, 16, v226
	v_and_b32_e32 v29, 0xffff0000, v226
	v_lshlrev_b32_e32 v30, 16, v227
	v_and_b32_e32 v31, 0xffff0000, v227
	v_add_f32_e32 v16, 1.0, v16
	v_add_f32_e32 v17, 1.0, v17
	v_add_f32_e32 v18, 1.0, v18
	v_add_f32_e32 v19, 1.0, v19
	v_add_f32_e32 v20, 1.0, v20
	v_add_f32_e32 v21, 1.0, v21
	v_add_f32_e32 v22, 1.0, v22
	v_add_f32_e32 v23, 1.0, v23
	v_rcp_f32_e32 v16, v16
	v_rcp_f32_e32 v17, v17
	v_rcp_f32_e32 v18, v18
	v_rcp_f32_e32 v19, v19
	v_rcp_f32_e32 v20, v20
	v_rcp_f32_e32 v21, v21
	v_rcp_f32_e32 v22, v22
	v_rcp_f32_e32 v23, v23
	v_lshlrev_b32_e32 v224, 16, v228
	v_and_b32_e32 v228, 0xffff0000, v228
	v_lshlrev_b32_e32 v225, 16, v229
	v_and_b32_e32 v229, 0xffff0000, v229
	v_lshlrev_b32_e32 v226, 16, v230
	v_and_b32_e32 v230, 0xffff0000, v230
	v_lshlrev_b32_e32 v227, 16, v231
	v_and_b32_e32 v231, 0xffff0000, v231
	v_add_f32_e32 v24, v224, v24
	v_add_f32_e32 v25, v228, v25
	v_add_f32_e32 v26, v225, v26
	v_add_f32_e32 v27, v229, v27
	v_add_f32_e32 v28, v226, v28
	v_add_f32_e32 v29, v230, v29
	v_add_f32_e32 v30, v227, v30
	v_add_f32_e32 v31, v231, v31
	v_fma_f32 v16, v16, -2.0, 1.0
	v_fma_f32 v17, v17, -2.0, 1.0
	v_fma_f32 v18, v18, -2.0, 1.0
	v_fma_f32 v19, v19, -2.0, 1.0
	v_fma_f32 v20, v20, -2.0, 1.0
	v_fma_f32 v21, v21, -2.0, 1.0
	v_fma_f32 v22, v22, -2.0, 1.0
	v_fma_f32 v23, v23, -2.0, 1.0
	v_mul_f32_e32 v8, 0.5, v8
	v_mul_f32_e32 v9, 0.5, v9
	v_mul_f32_e32 v10, 0.5, v10
	v_mul_f32_e32 v11, 0.5, v11
	v_mul_f32_e32 v12, 0.5, v12
	v_mul_f32_e32 v13, 0.5, v13
	v_mul_f32_e32 v14, 0.5, v14
	v_mul_f32_e32 v15, 0.5, v15
	v_add_f32_e32 v16, 1.0, v16
	v_add_f32_e32 v17, 1.0, v17
	v_add_f32_e32 v18, 1.0, v18
	v_add_f32_e32 v19, 1.0, v19
	v_add_f32_e32 v20, 1.0, v20
	v_add_f32_e32 v21, 1.0, v21
	v_add_f32_e32 v22, 1.0, v22
	v_add_f32_e32 v23, 1.0, v23
	v_mul_f32_e32 v8, v8, v16
	v_mul_f32_e32 v9, v9, v17
	v_mul_f32_e32 v10, v10, v18
	v_mul_f32_e32 v11, v11, v19
	v_mul_f32_e32 v12, v12, v20
	v_mul_f32_e32 v13, v13, v21
	v_mul_f32_e32 v14, v14, v22
	v_mul_f32_e32 v15, v15, v23
	v_mul_f32_e32 v24, v24, v8
	v_mul_f32_e32 v25, v25, v9
	v_mul_f32_e32 v26, v26, v10
	v_mul_f32_e32 v27, v27, v11
	v_mul_f32_e32 v28, v28, v12
	v_mul_f32_e32 v29, v29, v13
	v_mul_f32_e32 v30, v30, v14
	v_mul_f32_e32 v31, v31, v15
	v_mul_f32_e32 v228, v25, v25
	v_cvt_pk_bf16_f32 v224, v24, v25
	v_fmac_f32_e32 v228, v24, v24
	v_cvt_pk_bf16_f32 v225, v26, v27
	v_fmac_f32_e32 v228, v26, v26
	v_cvt_pk_bf16_f32 v226, v28, v29
	v_fmac_f32_e32 v228, v27, v27
	v_cvt_pk_bf16_f32 v227, v30, v31
	v_fmac_f32_e32 v228, v28, v28
	v_fmac_f32_e32 v228, v29, v29
	v_fmac_f32_e32 v228, v30, v30
	v_fmac_f32_e32 v228, v31, v31
	s_lshl_b32 s2, s0, 11
	s_add_u32 s4, s22, s2
	s_addc_u32 s5, s23, 0
	s_add_u32 s4, s4, 0x15800400
	s_addc_u32 s5, s5, 0
	global_store_dwordx4 v7, v[32:35], s[4:5]
	s_add_u32 s4, s4, 0x400000
	s_addc_u32 s5, s5, 0
	global_store_dwordx4 v7, v[44:47], s[4:5]
	s_add_u32 s4, s4, 0x400000
	s_addc_u32 s5, s5, 0
	global_store_dwordx4 v7, v[56:59], s[4:5]
	s_add_u32 s4, s4, 0x400000
	s_addc_u32 s5, s5, 0
	global_store_dwordx4 v7, v[68:71], s[4:5]
	s_add_u32 s4, s4, 0x400000
	s_addc_u32 s5, s5, 0
	global_store_dwordx4 v7, v[80:83], s[4:5]
	s_add_u32 s4, s4, 0x400000
	s_addc_u32 s5, s5, 0
	global_store_dwordx4 v7, v[92:95], s[4:5]
	s_add_u32 s4, s4, 0x400000
	s_addc_u32 s5, s5, 0
	global_store_dwordx4 v7, v[104:107], s[4:5]
	s_add_u32 s4, s4, 0x400000
	s_addc_u32 s5, s5, 0
	global_store_dwordx4 v7, v[116:119], s[4:5]
	s_add_u32 s4, s4, 0x400000
	s_addc_u32 s5, s5, 0
	global_store_dwordx4 v7, v[128:131], s[4:5]
	s_add_u32 s4, s4, 0x400000
	s_addc_u32 s5, s5, 0
	global_store_dwordx4 v7, v[140:143], s[4:5]
	s_add_u32 s4, s4, 0x400000
	s_addc_u32 s5, s5, 0
	global_store_dwordx4 v7, v[164:167], s[4:5]
	s_add_u32 s4, s4, 0x400000
	s_addc_u32 s5, s5, 0
	global_store_dwordx4 v7, v[176:179], s[4:5]
	s_add_u32 s4, s4, 0x400000
	s_addc_u32 s5, s5, 0
	global_store_dwordx4 v7, v[188:191], s[4:5]
	s_add_u32 s4, s4, 0x400000
	s_addc_u32 s5, s5, 0
	global_store_dwordx4 v7, v[200:203], s[4:5]
	s_add_u32 s4, s4, 0x400000
	s_addc_u32 s5, s5, 0
	global_store_dwordx4 v7, v[212:215], s[4:5]
	s_add_u32 s4, s4, 0x400000
	s_addc_u32 s5, s5, 0
	global_store_dwordx4 v7, v[224:227], s[4:5]
	ds_bpermute_b32 v37, v1, v36
	ds_bpermute_b32 v49, v1, v48
	ds_bpermute_b32 v61, v1, v60
	ds_bpermute_b32 v73, v1, v72
	ds_bpermute_b32 v85, v1, v84
	ds_bpermute_b32 v97, v1, v96
	ds_bpermute_b32 v109, v1, v108
	ds_bpermute_b32 v121, v1, v120
	s_waitcnt lgkmcnt(0)
; __device__ __forceinline__ float wave_sum(float v) {
; #pragma unroll
;     for (int o = 1; o < 64; o <<= 1) v += __shfl_xor(v, o);
;     return v;
; __device__ __forceinline__ void rnn_combine(const Params& p) {
;     ...
;             q = wave_sum(q);
	v_add_f32_e32 v36, v36, v37
	v_add_f32_e32 v48, v48, v49
	v_add_f32_e32 v60, v60, v61
	v_add_f32_e32 v72, v72, v73
	v_add_f32_e32 v84, v84, v85
	v_add_f32_e32 v96, v96, v97
	v_add_f32_e32 v108, v108, v109
	v_add_f32_e32 v120, v120, v121
	ds_bpermute_b32 v133, v1, v132
	ds_bpermute_b32 v145, v1, v144
	ds_bpermute_b32 v169, v1, v168
	ds_bpermute_b32 v181, v1, v180
	ds_bpermute_b32 v193, v1, v192
	ds_bpermute_b32 v205, v1, v204
	ds_bpermute_b32 v217, v1, v216
	ds_bpermute_b32 v229, v1, v228
	s_waitcnt lgkmcnt(0)
	v_add_f32_e32 v132, v132, v133
	v_add_f32_e32 v144, v144, v145
	v_add_f32_e32 v168, v168, v169
	v_add_f32_e32 v180, v180, v181
	v_add_f32_e32 v192, v192, v193
	v_add_f32_e32 v204, v204, v205
	v_add_f32_e32 v216, v216, v217
	v_add_f32_e32 v228, v228, v229
	ds_bpermute_b32 v37, v2, v36
	ds_bpermute_b32 v49, v2, v48
	ds_bpermute_b32 v61, v2, v60
	ds_bpermute_b32 v73, v2, v72
	ds_bpermute_b32 v85, v2, v84
	ds_bpermute_b32 v97, v2, v96
	ds_bpermute_b32 v109, v2, v108
	ds_bpermute_b32 v121, v2, v120
	s_waitcnt lgkmcnt(0)
	v_add_f32_e32 v36, v36, v37
	v_add_f32_e32 v48, v48, v49
	v_add_f32_e32 v60, v60, v61
	v_add_f32_e32 v72, v72, v73
	v_add_f32_e32 v84, v84, v85
	v_add_f32_e32 v96, v96, v97
	v_add_f32_e32 v108, v108, v109
	v_add_f32_e32 v120, v120, v121
	ds_bpermute_b32 v133, v2, v132
	ds_bpermute_b32 v145, v2, v144
	ds_bpermute_b32 v169, v2, v168
	ds_bpermute_b32 v181, v2, v180
	ds_bpermute_b32 v193, v2, v192
	ds_bpermute_b32 v205, v2, v204
	ds_bpermute_b32 v217, v2, v216
	ds_bpermute_b32 v229, v2, v228
	s_waitcnt lgkmcnt(0)
	v_add_f32_e32 v132, v132, v133
	v_add_f32_e32 v144, v144, v145
	v_add_f32_e32 v168, v168, v169
	v_add_f32_e32 v180, v180, v181
	v_add_f32_e32 v192, v192, v193
	v_add_f32_e32 v204, v204, v205
	v_add_f32_e32 v216, v216, v217
	v_add_f32_e32 v228, v228, v229
	ds_bpermute_b32 v37, v3, v36
	ds_bpermute_b32 v49, v3, v48
	ds_bpermute_b32 v61, v3, v60
	ds_bpermute_b32 v73, v3, v72
	ds_bpermute_b32 v85, v3, v84
	ds_bpermute_b32 v97, v3, v96
	ds_bpermute_b32 v109, v3, v108
	ds_bpermute_b32 v121, v3, v120
	s_waitcnt lgkmcnt(0)
	v_add_f32_e32 v36, v36, v37
	v_add_f32_e32 v48, v48, v49
	v_add_f32_e32 v60, v60, v61
	v_add_f32_e32 v72, v72, v73
	v_add_f32_e32 v84, v84, v85
	v_add_f32_e32 v96, v96, v97
	v_add_f32_e32 v108, v108, v109
	v_add_f32_e32 v120, v120, v121
	ds_bpermute_b32 v133, v3, v132
	ds_bpermute_b32 v145, v3, v144
	ds_bpermute_b32 v169, v3, v168
	ds_bpermute_b32 v181, v3, v180
	ds_bpermute_b32 v193, v3, v192
	ds_bpermute_b32 v205, v3, v204
	ds_bpermute_b32 v217, v3, v216
	ds_bpermute_b32 v229, v3, v228
	s_waitcnt lgkmcnt(0)
	v_add_f32_e32 v132, v132, v133
	v_add_f32_e32 v144, v144, v145
	v_add_f32_e32 v168, v168, v169
	v_add_f32_e32 v180, v180, v181
	v_add_f32_e32 v192, v192, v193
	v_add_f32_e32 v204, v204, v205
	v_add_f32_e32 v216, v216, v217
	v_add_f32_e32 v228, v228, v229
	ds_bpermute_b32 v37, v4, v36
	ds_bpermute_b32 v49, v4, v48
	ds_bpermute_b32 v61, v4, v60
	ds_bpermute_b32 v73, v4, v72
	ds_bpermute_b32 v85, v4, v84
	ds_bpermute_b32 v97, v4, v96
	ds_bpermute_b32 v109, v4, v108
	ds_bpermute_b32 v121, v4, v120
	s_waitcnt lgkmcnt(0)
	v_add_f32_e32 v36, v36, v37
	v_add_f32_e32 v48, v48, v49
	v_add_f32_e32 v60, v60, v61
	v_add_f32_e32 v72, v72, v73
	v_add_f32_e32 v84, v84, v85
	v_add_f32_e32 v96, v96, v97
	v_add_f32_e32 v108, v108, v109
	v_add_f32_e32 v120, v120, v121
	ds_bpermute_b32 v133, v4, v132
	ds_bpermute_b32 v145, v4, v144
	ds_bpermute_b32 v169, v4, v168
	ds_bpermute_b32 v181, v4, v180
	ds_bpermute_b32 v193, v4, v192
	ds_bpermute_b32 v205, v4, v204
	ds_bpermute_b32 v217, v4, v216
	ds_bpermute_b32 v229, v4, v228
	s_waitcnt lgkmcnt(0)
	v_add_f32_e32 v132, v132, v133
	v_add_f32_e32 v144, v144, v145
	v_add_f32_e32 v168, v168, v169
	v_add_f32_e32 v180, v180, v181
	v_add_f32_e32 v192, v192, v193
	v_add_f32_e32 v204, v204, v205
	v_add_f32_e32 v216, v216, v217
	v_add_f32_e32 v228, v228, v229
	ds_bpermute_b32 v37, v5, v36
	ds_bpermute_b32 v49, v5, v48
	ds_bpermute_b32 v61, v5, v60
	ds_bpermute_b32 v73, v5, v72
	ds_bpermute_b32 v85, v5, v84
	ds_bpermute_b32 v97, v5, v96
	ds_bpermute_b32 v109, v5, v108
	ds_bpermute_b32 v121, v5, v120
	s_waitcnt lgkmcnt(0)
	v_add_f32_e32 v36, v36, v37
	v_add_f32_e32 v48, v48, v49
	v_add_f32_e32 v60, v60, v61
	v_add_f32_e32 v72, v72, v73
	v_add_f32_e32 v84, v84, v85
	v_add_f32_e32 v96, v96, v97
	v_add_f32_e32 v108, v108, v109
	v_add_f32_e32 v120, v120, v121
	ds_bpermute_b32 v133, v5, v132
	ds_bpermute_b32 v145, v5, v144
	ds_bpermute_b32 v169, v5, v168
	ds_bpermute_b32 v181, v5, v180
	ds_bpermute_b32 v193, v5, v192
	ds_bpermute_b32 v205, v5, v204
	ds_bpermute_b32 v217, v5, v216
	ds_bpermute_b32 v229, v5, v228
	s_waitcnt lgkmcnt(0)
; __device__ __forceinline__ unsigned cvt_pk(float lo, float hi) { unsigned r; asm("v_cvt_pk_bf16_f32 %0, %1, %2" : "=v"(r) : "v"(lo), "v"(hi)); return r; }
; __device__ __forceinline__ float wave_sum(float v) {
; #pragma unroll
;     for (int o = 1; o < 64; o <<= 1) v += __shfl_xor(v, o);
;     return v;
; __device__ __forceinline__ void rnn_combine(const Params& p) {
;     const int tid = threadIdx.x, lane = tid & 63, wave = tid >> 6;
;     unsigned char* ws = p.ws;
;     const bf16_t* P = (const bf16_t*)(ws + WS_P); const bf16_t* H0 = (const bf16_t*)(ws + WS_H); const bf16_t* H1 = H0 + (size_t)MT * 512;
;     bf16_t* MIX = (bf16_t*)(ws + WS_MIX); float* ss_b = (float*)(ws + WS_SS) + 2 * MT + MR;
;     const int NW = gridDim.x * 8;
;     for (int r0 = blockIdx.x * 8 + wave; r0 < MR; r0 += 4 * NW) {
;         u32x4 hf[4], hb[4], gw[4];
; #pragma unroll
;         for (int k = 0; k < 4; ++k) { const int rr = (r0 + k * NW < MR) ? r0 + k * NW : r0; const int b = rr / SEQ, sidx = rr % SEQ; const size_t src = (size_t)b * TT + sidx + NMETA;
;             hf[k] = *(const u32x4*)(H0 + src * 512 + 8 * lane); hb[k] = *(const u32x4*)(H1 + src * 512 + 8 * lane); gw[k] = *(const u32x4*)(P + src * INP + C_GATE + 8 * lane); }
;     ...
;             q = wave_sum(q);
;             if (rr < MR) { u32x4 w; w.x = cvt_pk(y[0], y[1]); w.y = cvt_pk(y[2], y[3]); w.z = cvt_pk(y[4], y[5]); w.w = cvt_pk(y[6], y[7]);
;                 *(u32x4*)(MIX + (size_t)rr * DM + 512 + 8 * lane) = w;
;                 if (lane == 0) ss_b[rr] = q; } }
	v_add_f32_e32 v132, v132, v133
	v_add_f32_e32 v144, v144, v145
	v_add_f32_e32 v168, v168, v169
	v_add_f32_e32 v180, v180, v181
	v_add_f32_e32 v192, v192, v193
	v_add_f32_e32 v204, v204, v205
	v_add_f32_e32 v216, v216, v217
	v_add_f32_e32 v228, v228, v229
	ds_bpermute_b32 v37, v6, v36
	ds_bpermute_b32 v49, v6, v48
	ds_bpermute_b32 v61, v6, v60
	ds_bpermute_b32 v73, v6, v72
	ds_bpermute_b32 v85, v6, v84
	ds_bpermute_b32 v97, v6, v96
	ds_bpermute_b32 v109, v6, v108
	ds_bpermute_b32 v121, v6, v120
	s_waitcnt lgkmcnt(0)
	v_add_f32_e32 v36, v36, v37
	v_add_f32_e32 v48, v48, v49
	v_add_f32_e32 v60, v60, v61
	v_add_f32_e32 v72, v72, v73
	v_add_f32_e32 v84, v84, v85
	v_add_f32_e32 v96, v96, v97
	v_add_f32_e32 v108, v108, v109
	v_add_f32_e32 v120, v120, v121
	ds_bpermute_b32 v133, v6, v132
	ds_bpermute_b32 v145, v6, v144
	ds_bpermute_b32 v169, v6, v168
	ds_bpermute_b32 v181, v6, v180
	ds_bpermute_b32 v193, v6, v192
	ds_bpermute_b32 v205, v6, v204
	ds_bpermute_b32 v217, v6, v216
	ds_bpermute_b32 v229, v6, v228
	s_waitcnt lgkmcnt(0)
	v_add_f32_e32 v132, v132, v133
	v_add_f32_e32 v144, v144, v145
	v_add_f32_e32 v168, v168, v169
	v_add_f32_e32 v180, v180, v181
	v_add_f32_e32 v192, v192, v193
	v_add_f32_e32 v204, v204, v205
	v_add_f32_e32 v216, v216, v217
	v_add_f32_e32 v228, v228, v229
	s_lshl_b32 s2, s0, 2
	s_add_u32 s4, s22, s2
	s_addc_u32 s5, s23, 0
	s_add_u32 s4, s4, 0x60800
	s_addc_u32 s5, s5, 0
	v_mov_b32_e32 v0, 0
	s_mov_b64 s[8:9], exec
	s_mov_b64 exec, 1
	global_store_dword v0, v36, s[4:5]
	s_add_u32 s4, s4, 0x2000
	s_addc_u32 s5, s5, 0
	global_store_dword v0, v48, s[4:5]
	s_add_u32 s4, s4, 0x2000
	s_addc_u32 s5, s5, 0
	global_store_dword v0, v60, s[4:5]
	s_add_u32 s4, s4, 0x2000
	s_addc_u32 s5, s5, 0
	global_store_dword v0, v72, s[4:5]
	s_add_u32 s4, s4, 0x2000
	s_addc_u32 s5, s5, 0
	global_store_dword v0, v84, s[4:5]
	s_add_u32 s4, s4, 0x2000
	s_addc_u32 s5, s5, 0
	global_store_dword v0, v96, s[4:5]
	s_add_u32 s4, s4, 0x2000
	s_addc_u32 s5, s5, 0
	global_store_dword v0, v108, s[4:5]
	s_add_u32 s4, s4, 0x2000
	s_addc_u32 s5, s5, 0
	global_store_dword v0, v120, s[4:5]
	s_add_u32 s4, s4, 0x2000
	s_addc_u32 s5, s5, 0
	global_store_dword v0, v132, s[4:5]
	s_add_u32 s4, s4, 0x2000
	s_addc_u32 s5, s5, 0
	global_store_dword v0, v144, s[4:5]
	s_add_u32 s4, s4, 0x2000
	s_addc_u32 s5, s5, 0
	global_store_dword v0, v168, s[4:5]
	s_add_u32 s4, s4, 0x2000
	s_addc_u32 s5, s5, 0
	global_store_dword v0, v180, s[4:5]
	s_add_u32 s4, s4, 0x2000
	s_addc_u32 s5, s5, 0
	global_store_dword v0, v192, s[4:5]
	s_add_u32 s4, s4, 0x2000
	s_addc_u32 s5, s5, 0
	global_store_dword v0, v204, s[4:5]
	s_add_u32 s4, s4, 0x2000
	s_addc_u32 s5, s5, 0
	global_store_dword v0, v216, s[4:5]
	s_add_u32 s4, s4, 0x2000
	s_addc_u32 s5, s5, 0
	global_store_dword v0, v228, s[4:5]
	s_mov_b64 exec, s[8:9]
	s_branch .Lcomb_done_a
.Lcomb_orig_a:
	v_lshl_add_u32 v54, s18, 3, v162
	s_mov_b32 s6, 0x8000
	v_cmp_gt_i32_e32 vcc, s6, v54
	s_and_saveexec_b64 s[14:15], vcc
	s_cbranch_execz .LBB0_711
	s_waitcnt lgkmcnt(0)
	v_and_b32_e32 v1, 63, v163
	v_mov_b32_e32 v49, 0
	v_lshlrev_b32_e32 v48, 4, v1
	v_lshl_add_u64 v[2:3], s[22:23], 0, v[48:49]
	s_mov_b64 s[0:1], 0x19800000
	v_lshl_add_u64 v[50:51], v[2:3], 0, s[0:1]
	s_mov_b64 s[0:1], 0x1b840000
	v_lshl_add_u64 v[52:53], v[2:3], 0, s[0:1]
	v_mbcnt_lo_u32_b32 v2, -1, 0
	v_mbcnt_hi_u32_b32 v2, -1, v2
	v_and_b32_e32 v3, 64, v2
	v_add_u32_e32 v3, 64, v3
	v_xor_b32_e32 v4, 1, v2
	v_cmp_lt_i32_e32 vcc, v4, v3
	s_add_u32 s16, s22, 0x60800
	v_lshlrev_b32_e32 v0, 3, v1
	v_cndmask_b32_e32 v4, v2, v4, vcc
	v_lshlrev_b32_e32 v60, 2, v4
	v_xor_b32_e32 v4, 2, v2
	v_cmp_lt_i32_e32 vcc, v4, v3
	s_addc_u32 s17, s23, 0
	s_lshl_b32 s7, s28, 3
	v_cndmask_b32_e32 v4, v2, v4, vcc
	v_lshlrev_b32_e32 v61, 2, v4
	v_xor_b32_e32 v4, 4, v2
	v_cmp_lt_i32_e32 vcc, v4, v3
	v_cmp_eq_u32_e64 s[0:1], 0, v1
	s_lshl_b32 s19, s28, 4
	v_cndmask_b32_e32 v4, v2, v4, vcc
	v_lshlrev_b32_e32 v62, 2, v4
	v_xor_b32_e32 v4, 8, v2
	v_cmp_lt_i32_e32 vcc, v4, v3
	s_mul_i32 s33, s28, 24
	s_mov_b64 s[30:31], 0
	v_cndmask_b32_e32 v4, v2, v4, vcc
	v_lshlrev_b32_e32 v63, 2, v4
	v_xor_b32_e32 v4, 16, v2
	v_cmp_lt_i32_e32 vcc, v4, v3
	s_movk_i32 s38, 0xe00
	v_mov_b64_e32 v[56:57], s[22:23]
	v_cndmask_b32_e32 v4, v2, v4, vcc
	v_lshlrev_b32_e32 v64, 2, v4
	v_xor_b32_e32 v4, 32, v2
	v_cmp_lt_i32_e32 vcc, v4, v3
	v_lshlrev_b32_e32 v48, 1, v0
	s_mov_b32 s39, 0x6400000
	v_cndmask_b32_e32 v2, v2, v4, vcc
	v_lshlrev_b32_e32 v65, 2, v2
	s_movk_i32 s40, 0x7fff
	s_branch .LBB0_700

; #define LAS __attribute__((address_space(3)))
; __device__ __forceinline__ void attn_unit(const Params& p, LAS unsigned char* lds, int bh, int qb) {
;     int tid_ = threadIdx.x; asm volatile("" : "+v"(tid_));
;     const int tid = tid_, lane = tid & 63, wid = tid >> 6, l31 = lane & 31, hi = lane >> 5;
;     unsigned char* ws = p.ws;
;     const bf16_t* Qg = (const bf16_t*)(ws + WS_Q) + ((size_t)bh * SEQ + qb * 256 + wid * 32 + l31) * QKH;
;     const bf16_t* Kg = (const bf16_t*)(ws + WS_K) + (size_t)bh * TKP * QKH;
;     const bf16_t* Vg = (const bf16_t*)(ws + WS_VT) + (size_t)bh * 64 * TKP;
;     constexpr int KST = 208, VST = 144, KBUF = 64 * KST;
;     bf16x8 qr[6];
; #pragma unroll
;     for (int ks = 0; ks < 6; ++ks) qr[ks] = *(const bf16x8*)(Qg + 16 * ks + 8 * hi);
;     bool fast;
;     { float gq = fabsf(p.in[8][lane]), gk = fabsf(p.in[9][lane]);
;       if (lane < 32) { gq = fmaxf(gq, fabsf(p.in[8][64 + lane])); gk = fmaxf(gk, fabsf(p.in[9][64 + lane])); }
; #pragma unroll
;       for (int o = 1; o < 64; o <<= 1) { gq = fmaxf(gq, __shfl_xor(gq, o)); gk = fmaxf(gk, __shfl_xor(gk, o)); }
;       fast = __builtin_amdgcn_readfirstlane((14.2f * gq * gk < 40.0f) ? 1 : 0) != 0; }
;     const int kr0 = tid / 12, kc0 = tid % 12, i1 = tid + 512, kr1 = i1 / 12, kc1 = i1 % 12, vd = tid >> 3, vc = tid & 7;
;     const bool two = tid < 256;
;     const int pi = (l31 & 0x13) | ((l31 & 4) << 1) | ((l31 & 8) >> 1);
;     constexpr int VOFF = 2 * KBUF, VBUF = 64 * VST;
; __global__ void __launch_bounds__(512, 2) hymba_fwd(Params p) {
;     ...
;     if (IN(3)) { constexpr int NA = BATCH * NH * 8;
;         const bool comb_first = ((vcu >> 3) & 1) == 0;
;         if (comb_first) rnn_combine(p);
;         for (int u = vcu; u < NA; u += G) attn_unit(p, lds, u >> 3, u & 7);
.Lcomb_done_a:
.LBB0_712:
	s_cmpk_gt_i32 s92, 0x3ff
	s_cbranch_scc1 .LBB0_761
	s_add_u32 s0, s22, 0xd500000
	s_addc_u32 s1, s23, 0
	s_add_u32 s81, s22, 0x10500000
	s_addc_u32 s85, s23, 0
	s_add_u32 s33, s22, 0x13700000
	s_addc_u32 s93, s23, 0
	s_add_u32 s90, s22, 0x15800000
	v_mbcnt_lo_u32_b32 v0, -1, 0
	s_addc_u32 s91, s23, 0
	v_mbcnt_hi_u32_b32 v154, -1, v0
	s_add_u32 s94, s22, 0x40800
	s_brev_b32 s56, 1
	v_and_b32_e32 v0, 64, v154
	s_addc_u32 s95, s23, 0
	s_mov_b32 s17, 0
	v_mov_b32_e32 v133, 0
	s_movk_i32 s96, 0xc0
	v_mov_b64_e32 v[134:135], s[0:1]
	s_mov_b32 s72, 0x42200000
	s_mov_b32 s73, 0x2aaaaaab
	s_movk_i32 s74, 0xff
	s_movk_i32 s75, 0x100
	s_movk_i32 s76, 0x60
	s_movk_i32 s77, 0xd0
	s_movk_i32 s78, 0x90
	s_mov_b32 s79, 0x41000000
	s_mov_b64 s[30:31], 0x4000
	s_mov_b64 s[34:35], 0x6000
	s_mov_b32 s57, s56
	s_mov_b32 s58, s56
	s_mov_b32 s59, s56
	s_mov_b32 s60, s56
	s_mov_b32 s61, s56
	s_mov_b32 s62, s56
	s_mov_b32 s63, s56
	s_mov_b32 s64, s56
	s_mov_b32 s65, s56
	s_mov_b32 s66, s56
	s_mov_b32 s67, s56
	s_mov_b32 s68, s56
	s_mov_b32 s69, s56
	s_mov_b32 s70, s56
	s_mov_b32 s71, s56
	s_movk_i32 s80, 0x1200
	v_add_u32_e32 v155, 64, v0
	v_xor_b32_e32 v156, 1, v154
	v_xor_b32_e32 v157, 2, v154
	v_xor_b32_e32 v158, 4, v154
	v_xor_b32_e32 v159, 8, v154
	v_xor_b32_e32 v160, 16, v154
	v_xor_b32_e32 v161, 32, v154
	v_bfrev_b32_e32 v0, 1
	s_branch .LBB0_715

; __device__ __forceinline__ void rnn_combine(const Params& p) {
;     const int tid = threadIdx.x, lane = tid & 63, wave = tid >> 6;
;     unsigned char* ws = p.ws;
;     const bf16_t* P = (const bf16_t*)(ws + WS_P); const bf16_t* H0 = (const bf16_t*)(ws + WS_H); const bf16_t* H1 = H0 + (size_t)MT * 512;
;     bf16_t* MIX = (bf16_t*)(ws + WS_MIX); float* ss_b = (float*)(ws + WS_SS) + 2 * MT + MR;
;     const int NW = gridDim.x * 8;
;     for (int r0 = blockIdx.x * 8 + wave; r0 < MR; r0 += 4 * NW) {
;         u32x4 hf[4], hb[4], gw[4];
; #pragma unroll
;         for (int k = 0; k < 4; ++k) { const int rr = (r0 + k * NW < MR) ? r0 + k * NW : r0; const int b = rr / SEQ, sidx = rr % SEQ; const size_t src = (size_t)b * TT + sidx + NMETA;
;             hf[k] = *(const u32x4*)(H0 + src * 512 + 8 * lane); hb[k] = *(const u32x4*)(H1 + src * 512 + 8 * lane); gw[k] = *(const u32x4*)(P + src * INP + C_GATE + 8 * lane); }
; #pragma unroll
.LBB0_761:
	s_and_b64 vcc, exec, s[88:89]
	s_cbranch_vccz .LBB0_777
	s_cmpk_lg_i32 s28, 0x100
	s_cbranch_scc1 .Lcomb_orig_b
	v_readfirstlane_b32 s0, v162
	v_and_b32_e32 v0, 63, v163
	s_lshl_b32 s1, s18, 3
	v_lshlrev_b32_e32 v7, 4, v0
	s_add_i32 s0, s0, s1
	v_xor_b32_e32 v1, 1, v0
	v_xor_b32_e32 v2, 2, v0
	v_xor_b32_e32 v3, 4, v0
	v_xor_b32_e32 v4, 8, v0
	v_xor_b32_e32 v5, 16, v0
	v_xor_b32_e32 v6, 32, v0
	v_lshlrev_b32_e32 v1, 2, v1
	v_lshlrev_b32_e32 v2, 2, v2
	v_lshlrev_b32_e32 v3, 2, v3
	v_lshlrev_b32_e32 v4, 2, v4
	v_lshlrev_b32_e32 v5, 2, v5
	v_lshlrev_b32_e32 v6, 2, v6
	s_add_i32 s1, s0, 16
	s_lshl_b32 s2, s1, 10
	s_add_u32 s4, s22, s2
	s_addc_u32 s5, s23, 0
	s_add_u32 s4, s4, 0x19800000
	s_addc_u32 s5, s5, 0
	s_add_u32 s8, s4, 0x2040000
	s_addc_u32 s9, s5, 0
	s_mul_i32 s2, s1, 0xe00
	s_add_u32 s6, s22, s2
	s_addc_u32 s7, s23, 0
	s_add_u32 s6, s6, 0x6400940
	s_addc_u32 s7, s7, 0
	global_load_dwordx4 v[32:35], v7, s[4:5]
	global_load_dwordx4 v[36:39], v7, s[8:9]
	global_load_dwordx4 v[40:43], v7, s[6:7]
	s_add_u32 s4, s4, 0x204000
	s_addc_u32 s5, s5, 0
	s_add_u32 s8, s8, 0x204000
	s_addc_u32 s9, s9, 0
	s_add_u32 s6, s6, 0x70e000
	s_addc_u32 s7, s7, 0
	global_load_dwordx4 v[44:47], v7, s[4:5]
	global_load_dwordx4 v[48:51], v7, s[8:9]
	global_load_dwordx4 v[52:55], v7, s[6:7]
	s_add_u32 s4, s4, 0x204000
	s_addc_u32 s5, s5, 0
	s_add_u32 s8, s8, 0x204000
	s_addc_u32 s9, s9, 0
	s_add_u32 s6, s6, 0x70e000
	s_addc_u32 s7, s7, 0
	global_load_dwordx4 v[56:59], v7, s[4:5]
	global_load_dwordx4 v[60:63], v7, s[8:9]
	global_load_dwordx4 v[64:67], v7, s[6:7]
	s_add_u32 s4, s4, 0x204000
	s_addc_u32 s5, s5, 0
	s_add_u32 s8, s8, 0x204000
	s_addc_u32 s9, s9, 0
	s_add_u32 s6, s6, 0x70e000
	s_addc_u32 s7, s7, 0
	global_load_dwordx4 v[68:71], v7, s[4:5]
	global_load_dwordx4 v[72:75], v7, s[8:9]
	global_load_dwordx4 v[76:79], v7, s[6:7]
	s_add_u32 s4, s4, 0x204000
	s_addc_u32 s5, s5, 0
	s_add_u32 s8, s8, 0x204000
	s_addc_u32 s9, s9, 0
	s_add_u32 s6, s6, 0x70e000
	s_addc_u32 s7, s7, 0
	global_load_dwordx4 v[80:83], v7, s[4:5]
	global_load_dwordx4 v[84:87], v7, s[8:9]
	global_load_dwordx4 v[88:91], v7, s[6:7]
	s_add_u32 s4, s4, 0x204000
	s_addc_u32 s5, s5, 0
	s_add_u32 s8, s8, 0x204000
	s_addc_u32 s9, s9, 0
	s_add_u32 s6, s6, 0x70e000
	s_addc_u32 s7, s7, 0
	global_load_dwordx4 v[92:95], v7, s[4:5]
	global_load_dwordx4 v[96:99], v7, s[8:9]
	global_load_dwordx4 v[100:103], v7, s[6:7]
	s_add_u32 s4, s4, 0x204000
	s_addc_u32 s5, s5, 0
	s_add_u32 s8, s8, 0x204000
	s_addc_u32 s9, s9, 0
	s_add_u32 s6, s6, 0x70e000
	s_addc_u32 s7, s7, 0
	global_load_dwordx4 v[104:107], v7, s[4:5]
	global_load_dwordx4 v[108:111], v7, s[8:9]
	global_load_dwordx4 v[112:115], v7, s[6:7]
	s_add_u32 s4, s4, 0x204000
	s_addc_u32 s5, s5, 0
	s_add_u32 s8, s8, 0x204000
	s_addc_u32 s9, s9, 0
	s_add_u32 s6, s6, 0x70e000
	s_addc_u32 s7, s7, 0
	global_load_dwordx4 v[116:119], v7, s[4:5]
	global_load_dwordx4 v[120:123], v7, s[8:9]
	global_load_dwordx4 v[124:127], v7, s[6:7]
	s_add_u32 s4, s4, 0x204000
	s_addc_u32 s5, s5, 0
	s_add_u32 s8, s8, 0x204000
	s_addc_u32 s9, s9, 0
	s_add_u32 s6, s6, 0x70e000
	s_addc_u32 s7, s7, 0
	global_load_dwordx4 v[128:131], v7, s[4:5]
	global_load_dwordx4 v[132:135], v7, s[8:9]
	global_load_dwordx4 v[136:139], v7, s[6:7]
	s_add_u32 s4, s4, 0x204000
	s_addc_u32 s5, s5, 0
	s_add_u32 s8, s8, 0x204000
	s_addc_u32 s9, s9, 0
	s_add_u32 s6, s6, 0x70e000
	s_addc_u32 s7, s7, 0
	global_load_dwordx4 v[140:143], v7, s[4:5]
	global_load_dwordx4 v[144:147], v7, s[8:9]
	global_load_dwordx4 v[148:151], v7, s[6:7]
	s_add_u32 s4, s4, 0x204000
	s_addc_u32 s5, s5, 0
	s_add_u32 s8, s8, 0x204000
	s_addc_u32 s9, s9, 0
	s_add_u32 s6, s6, 0x70e000
	s_addc_u32 s7, s7, 0
	global_load_dwordx4 v[164:167], v7, s[4:5]
	global_load_dwordx4 v[168:171], v7, s[8:9]
	global_load_dwordx4 v[172:175], v7, s[6:7]
	s_add_u32 s4, s4, 0x204000
	s_addc_u32 s5, s5, 0
	s_add_u32 s8, s8, 0x204000
	s_addc_u32 s9, s9, 0
	s_add_u32 s6, s6, 0x70e000
	s_addc_u32 s7, s7, 0
	global_load_dwordx4 v[176:179], v7, s[4:5]
	global_load_dwordx4 v[180:183], v7, s[8:9]
	global_load_dwordx4 v[184:187], v7, s[6:7]
	s_add_u32 s4, s4, 0x204000
	s_addc_u32 s5, s5, 0
	s_add_u32 s8, s8, 0x204000
	s_addc_u32 s9, s9, 0
	s_add_u32 s6, s6, 0x70e000
	s_addc_u32 s7, s7, 0
	global_load_dwordx4 v[188:191], v7, s[4:5]
	global_load_dwordx4 v[192:195], v7, s[8:9]
	global_load_dwordx4 v[196:199], v7, s[6:7]
	s_add_u32 s4, s4, 0x204000
	s_addc_u32 s5, s5, 0
	s_add_u32 s8, s8, 0x204000
	s_addc_u32 s9, s9, 0
	s_add_u32 s6, s6, 0x70e000
	s_addc_u32 s7, s7, 0
	global_load_dwordx4 v[200:203], v7, s[4:5]
	global_load_dwordx4 v[204:207], v7, s[8:9]
	global_load_dwordx4 v[208:211], v7, s[6:7]
	s_add_u32 s4, s4, 0x204000
	s_addc_u32 s5, s5, 0
	s_add_u32 s8, s8, 0x204000
	s_addc_u32 s9, s9, 0
	s_add_u32 s6, s6, 0x70e000
	s_addc_u32 s7, s7, 0
	global_load_dwordx4 v[212:215], v7, s[4:5]
	global_load_dwordx4 v[216:219], v7, s[8:9]
	global_load_dwordx4 v[220:223], v7, s[6:7]
	s_add_u32 s4, s4, 0x204000
	s_addc_u32 s5, s5, 0
	s_add_u32 s8, s8, 0x204000
	s_addc_u32 s9, s9, 0
	s_add_u32 s6, s6, 0x70e000
	s_addc_u32 s7, s7, 0
	global_load_dwordx4 v[224:227], v7, s[4:5]
	global_load_dwordx4 v[228:231], v7, s[8:9]
	global_load_dwordx4 v[232:235], v7, s[6:7]
	s_waitcnt vmcnt(45)
; __device__ __forceinline__ unsigned cvt_pk(float lo, float hi) { unsigned r; asm("v_cvt_pk_bf16_f32 %0, %1, %2" : "=v"(r) : "v"(lo), "v"(hi)); return r; }
; __device__ __forceinline__ float bflo(unsigned w) { return __uint_as_float(w << 16); }
; __device__ __forceinline__ float bfhi(unsigned w) { return __uint_as_float(w & 0xffff0000u); }
; __device__ __forceinline__ void rnn_combine(const Params& p) {
;     ...
;         for (int k = 0; k < 4; ++k) { const int rr = r0 + k * NW;
;             float y[8]; float q = 0.f;
; #pragma unroll
;             for (int i = 0; i < 4; ++i) { const unsigned a = hf[k][i], c = hb[k][i], gg = gw[k][i];
; #pragma unroll
;                 for (int e = 0; e < 2; ++e) { const float hs = (e ? bfhi(a) : bflo(a)) + (e ? bfhi(c) : bflo(c)); const float gt = e ? bfhi(gg) : bflo(gg);
;                     const float u = 0.7978845608028654f * (gt + 0.044715f * gt * gt * gt); const float th = 1.0f - 2.0f * __builtin_amdgcn_rcpf(1.0f + __builtin_amdgcn_exp2f(2.8853900817779268f * u));
;                     const float yv = hs * (0.5f * gt * (1.0f + th)); y[2 * i + e] = yv; q += yv * yv; } }
;             q = wave_sum(q);
;             if (rr < MR) { u32x4 w; w.x = cvt_pk(y[0], y[1]); w.y = cvt_pk(y[2], y[3]); w.z = cvt_pk(y[4], y[5]); w.w = cvt_pk(y[6], y[7]);
	v_lshlrev_b32_e32 v8, 16, v40
	v_and_b32_e32 v9, 0xffff0000, v40
	v_lshlrev_b32_e32 v10, 16, v41
	v_and_b32_e32 v11, 0xffff0000, v41
	v_lshlrev_b32_e32 v12, 16, v42
	v_and_b32_e32 v13, 0xffff0000, v42
	v_lshlrev_b32_e32 v14, 16, v43
	v_and_b32_e32 v15, 0xffff0000, v43
	v_mul_f32_e32 v16, 0x3d372713, v8
	v_mul_f32_e32 v17, 0x3d372713, v9
	v_mul_f32_e32 v18, 0x3d372713, v10
	v_mul_f32_e32 v19, 0x3d372713, v11
	v_mul_f32_e32 v20, 0x3d372713, v12
	v_mul_f32_e32 v21, 0x3d372713, v13
	v_mul_f32_e32 v22, 0x3d372713, v14
	v_mul_f32_e32 v23, 0x3d372713, v15
	v_mul_f32_e32 v16, v16, v8
	v_mul_f32_e32 v17, v17, v9
	v_mul_f32_e32 v18, v18, v10
	v_mul_f32_e32 v19, v19, v11
	v_mul_f32_e32 v20, v20, v12
	v_mul_f32_e32 v21, v21, v13
	v_mul_f32_e32 v22, v22, v14
	v_mul_f32_e32 v23, v23, v15
	v_fma_f32 v16, v16, v8, v8
	v_fma_f32 v17, v17, v9, v9
	v_fma_f32 v18, v18, v10, v10
	v_fma_f32 v19, v19, v11, v11
	v_fma_f32 v20, v20, v12, v12
	v_fma_f32 v21, v21, v13, v13
	v_fma_f32 v22, v22, v14, v14
	v_fma_f32 v23, v23, v15, v15
	v_mul_f32_e32 v16, 0x3f4c422a, v16
	v_mul_f32_e32 v17, 0x3f4c422a, v17
	v_mul_f32_e32 v18, 0x3f4c422a, v18
	v_mul_f32_e32 v19, 0x3f4c422a, v19
	v_mul_f32_e32 v20, 0x3f4c422a, v20
	v_mul_f32_e32 v21, 0x3f4c422a, v21
	v_mul_f32_e32 v22, 0x3f4c422a, v22
	v_mul_f32_e32 v23, 0x3f4c422a, v23
	v_mul_f32_e32 v16, 0x4038aa3b, v16
	v_mul_f32_e32 v17, 0x4038aa3b, v17
	v_mul_f32_e32 v18, 0x4038aa3b, v18
	v_mul_f32_e32 v19, 0x4038aa3b, v19
	v_mul_f32_e32 v20, 0x4038aa3b, v20
	v_mul_f32_e32 v21, 0x4038aa3b, v21
	v_mul_f32_e32 v22, 0x4038aa3b, v22
	v_mul_f32_e32 v23, 0x4038aa3b, v23
	v_exp_f32_e32 v16, v16
	v_exp_f32_e32 v17, v17
	v_exp_f32_e32 v18, v18
	v_exp_f32_e32 v19, v19
	v_exp_f32_e32 v20, v20
	v_exp_f32_e32 v21, v21
	v_exp_f32_e32 v22, v22
	v_exp_f32_e32 v23, v23
	v_lshlrev_b32_e32 v24, 16, v32
	v_and_b32_e32 v25, 0xffff0000, v32
	v_lshlrev_b32_e32 v26, 16, v33
	v_and_b32_e32 v27, 0xffff0000, v33
	v_lshlrev_b32_e32 v28, 16, v34
	v_and_b32_e32 v29, 0xffff0000, v34
	v_lshlrev_b32_e32 v30, 16, v35
	v_and_b32_e32 v31, 0xffff0000, v35
	v_add_f32_e32 v16, 1.0, v16
	v_add_f32_e32 v17, 1.0, v17
	v_add_f32_e32 v18, 1.0, v18
	v_add_f32_e32 v19, 1.0, v19
	v_add_f32_e32 v20, 1.0, v20
	v_add_f32_e32 v21, 1.0, v21
	v_add_f32_e32 v22, 1.0, v22
	v_add_f32_e32 v23, 1.0, v23
	v_rcp_f32_e32 v16, v16
	v_rcp_f32_e32 v17, v17
	v_rcp_f32_e32 v18, v18
	v_rcp_f32_e32 v19, v19
	v_rcp_f32_e32 v20, v20
	v_rcp_f32_e32 v21, v21
	v_rcp_f32_e32 v22, v22
	v_rcp_f32_e32 v23, v23
	v_lshlrev_b32_e32 v32, 16, v36
	v_and_b32_e32 v36, 0xffff0000, v36
	v_lshlrev_b32_e32 v33, 16, v37
	v_and_b32_e32 v37, 0xffff0000, v37
	v_lshlrev_b32_e32 v34, 16, v38
	v_and_b32_e32 v38, 0xffff0000, v38
	v_lshlrev_b32_e32 v35, 16, v39
	v_and_b32_e32 v39, 0xffff0000, v39
	v_add_f32_e32 v24, v32, v24
	v_add_f32_e32 v25, v36, v25
	v_add_f32_e32 v26, v33, v26
	v_add_f32_e32 v27, v37, v27
	v_add_f32_e32 v28, v34, v28
	v_add_f32_e32 v29, v38, v29
	v_add_f32_e32 v30, v35, v30
	v_add_f32_e32 v31, v39, v31
	v_fma_f32 v16, v16, -2.0, 1.0
	v_fma_f32 v17, v17, -2.0, 1.0
	v_fma_f32 v18, v18, -2.0, 1.0
	v_fma_f32 v19, v19, -2.0, 1.0
	v_fma_f32 v20, v20, -2.0, 1.0
	v_fma_f32 v21, v21, -2.0, 1.0
	v_fma_f32 v22, v22, -2.0, 1.0
	v_fma_f32 v23, v23, -2.0, 1.0
	v_mul_f32_e32 v8, 0.5, v8
	v_mul_f32_e32 v9, 0.5, v9
	v_mul_f32_e32 v10, 0.5, v10
	v_mul_f32_e32 v11, 0.5, v11
	v_mul_f32_e32 v12, 0.5, v12
	v_mul_f32_e32 v13, 0.5, v13
	v_mul_f32_e32 v14, 0.5, v14
	v_mul_f32_e32 v15, 0.5, v15
	v_add_f32_e32 v16, 1.0, v16
	v_add_f32_e32 v17, 1.0, v17
	v_add_f32_e32 v18, 1.0, v18
	v_add_f32_e32 v19, 1.0, v19
	v_add_f32_e32 v20, 1.0, v20
	v_add_f32_e32 v21, 1.0, v21
	v_add_f32_e32 v22, 1.0, v22
	v_add_f32_e32 v23, 1.0, v23
	v_mul_f32_e32 v8, v8, v16
	v_mul_f32_e32 v9, v9, v17
	v_mul_f32_e32 v10, v10, v18
	v_mul_f32_e32 v11, v11, v19
	v_mul_f32_e32 v12, v12, v20
	v_mul_f32_e32 v13, v13, v21
	v_mul_f32_e32 v14, v14, v22
	v_mul_f32_e32 v15, v15, v23
	v_mul_f32_e32 v24, v24, v8
	v_mul_f32_e32 v25, v25, v9
	v_mul_f32_e32 v26, v26, v10
	v_mul_f32_e32 v27, v27, v11
	v_mul_f32_e32 v28, v28, v12
	v_mul_f32_e32 v29, v29, v13
	v_mul_f32_e32 v30, v30, v14
	v_mul_f32_e32 v31, v31, v15
	v_mul_f32_e32 v36, v25, v25
	v_cvt_pk_bf16_f32 v32, v24, v25
	v_fmac_f32_e32 v36, v24, v24
	v_cvt_pk_bf16_f32 v33, v26, v27
	v_fmac_f32_e32 v36, v26, v26
	v_cvt_pk_bf16_f32 v34, v28, v29
	v_fmac_f32_e32 v36, v27, v27
	v_cvt_pk_bf16_f32 v35, v30, v31
	v_fmac_f32_e32 v36, v28, v28
	v_fmac_f32_e32 v36, v29, v29
	v_fmac_f32_e32 v36, v30, v30
	v_fmac_f32_e32 v36, v31, v31
	s_waitcnt vmcnt(42)
; __device__ __forceinline__ unsigned cvt_pk(float lo, float hi) { unsigned r; asm("v_cvt_pk_bf16_f32 %0, %1, %2" : "=v"(r) : "v"(lo), "v"(hi)); return r; }
; __device__ __forceinline__ float bflo(unsigned w) { return __uint_as_float(w << 16); }
; __device__ __forceinline__ float bfhi(unsigned w) { return __uint_as_float(w & 0xffff0000u); }
; __device__ __forceinline__ void rnn_combine(const Params& p) {
;     ...
;         for (int k = 0; k < 4; ++k) { const int rr = r0 + k * NW;
;             float y[8]; float q = 0.f;
; #pragma unroll
;             for (int i = 0; i < 4; ++i) { const unsigned a = hf[k][i], c = hb[k][i], gg = gw[k][i];
; #pragma unroll
;                 for (int e = 0; e < 2; ++e) { const float hs = (e ? bfhi(a) : bflo(a)) + (e ? bfhi(c) : bflo(c)); const float gt = e ? bfhi(gg) : bflo(gg);
;                     const float u = 0.7978845608028654f * (gt + 0.044715f * gt * gt * gt); const float th = 1.0f - 2.0f * __builtin_amdgcn_rcpf(1.0f + __builtin_amdgcn_exp2f(2.8853900817779268f * u));
;                     const float yv = hs * (0.5f * gt * (1.0f + th)); y[2 * i + e] = yv; q += yv * yv; } }
;             q = wave_sum(q);
;             if (rr < MR) { u32x4 w; w.x = cvt_pk(y[0], y[1]); w.y = cvt_pk(y[2], y[3]); w.z = cvt_pk(y[4], y[5]); w.w = cvt_pk(y[6], y[7]);
	v_lshlrev_b32_e32 v8, 16, v52
	v_and_b32_e32 v9, 0xffff0000, v52
	v_lshlrev_b32_e32 v10, 16, v53
	v_and_b32_e32 v11, 0xffff0000, v53
	v_lshlrev_b32_e32 v12, 16, v54
	v_and_b32_e32 v13, 0xffff0000, v54
	v_lshlrev_b32_e32 v14, 16, v55
	v_and_b32_e32 v15, 0xffff0000, v55
	v_mul_f32_e32 v16, 0x3d372713, v8
	v_mul_f32_e32 v17, 0x3d372713, v9
	v_mul_f32_e32 v18, 0x3d372713, v10
	v_mul_f32_e32 v19, 0x3d372713, v11
	v_mul_f32_e32 v20, 0x3d372713, v12
	v_mul_f32_e32 v21, 0x3d372713, v13
	v_mul_f32_e32 v22, 0x3d372713, v14
	v_mul_f32_e32 v23, 0x3d372713, v15
	v_mul_f32_e32 v16, v16, v8
	v_mul_f32_e32 v17, v17, v9
	v_mul_f32_e32 v18, v18, v10
	v_mul_f32_e32 v19, v19, v11
	v_mul_f32_e32 v20, v20, v12
	v_mul_f32_e32 v21, v21, v13
	v_mul_f32_e32 v22, v22, v14
	v_mul_f32_e32 v23, v23, v15
	v_fma_f32 v16, v16, v8, v8
	v_fma_f32 v17, v17, v9, v9
	v_fma_f32 v18, v18, v10, v10
	v_fma_f32 v19, v19, v11, v11
	v_fma_f32 v20, v20, v12, v12
	v_fma_f32 v21, v21, v13, v13
	v_fma_f32 v22, v22, v14, v14
	v_fma_f32 v23, v23, v15, v15
	v_mul_f32_e32 v16, 0x3f4c422a, v16
	v_mul_f32_e32 v17, 0x3f4c422a, v17
	v_mul_f32_e32 v18, 0x3f4c422a, v18
	v_mul_f32_e32 v19, 0x3f4c422a, v19
	v_mul_f32_e32 v20, 0x3f4c422a, v20
	v_mul_f32_e32 v21, 0x3f4c422a, v21
	v_mul_f32_e32 v22, 0x3f4c422a, v22
	v_mul_f32_e32 v23, 0x3f4c422a, v23
	v_mul_f32_e32 v16, 0x4038aa3b, v16
	v_mul_f32_e32 v17, 0x4038aa3b, v17
	v_mul_f32_e32 v18, 0x4038aa3b, v18
	v_mul_f32_e32 v19, 0x4038aa3b, v19
	v_mul_f32_e32 v20, 0x4038aa3b, v20
	v_mul_f32_e32 v21, 0x4038aa3b, v21
	v_mul_f32_e32 v22, 0x4038aa3b, v22
	v_mul_f32_e32 v23, 0x4038aa3b, v23
	v_exp_f32_e32 v16, v16
	v_exp_f32_e32 v17, v17
	v_exp_f32_e32 v18, v18
	v_exp_f32_e32 v19, v19
	v_exp_f32_e32 v20, v20
	v_exp_f32_e32 v21, v21
	v_exp_f32_e32 v22, v22
	v_exp_f32_e32 v23, v23
	v_lshlrev_b32_e32 v24, 16, v44
	v_and_b32_e32 v25, 0xffff0000, v44
	v_lshlrev_b32_e32 v26, 16, v45
	v_and_b32_e32 v27, 0xffff0000, v45
	v_lshlrev_b32_e32 v28, 16, v46
	v_and_b32_e32 v29, 0xffff0000, v46
	v_lshlrev_b32_e32 v30, 16, v47
	v_and_b32_e32 v31, 0xffff0000, v47
	v_add_f32_e32 v16, 1.0, v16
	v_add_f32_e32 v17, 1.0, v17
	v_add_f32_e32 v18, 1.0, v18
	v_add_f32_e32 v19, 1.0, v19
	v_add_f32_e32 v20, 1.0, v20
	v_add_f32_e32 v21, 1.0, v21
	v_add_f32_e32 v22, 1.0, v22
	v_add_f32_e32 v23, 1.0, v23
	v_rcp_f32_e32 v16, v16
	v_rcp_f32_e32 v17, v17
	v_rcp_f32_e32 v18, v18
	v_rcp_f32_e32 v19, v19
	v_rcp_f32_e32 v20, v20
	v_rcp_f32_e32 v21, v21
	v_rcp_f32_e32 v22, v22
	v_rcp_f32_e32 v23, v23
	v_lshlrev_b32_e32 v44, 16, v48
	v_and_b32_e32 v48, 0xffff0000, v48
	v_lshlrev_b32_e32 v45, 16, v49
	v_and_b32_e32 v49, 0xffff0000, v49
	v_lshlrev_b32_e32 v46, 16, v50
	v_and_b32_e32 v50, 0xffff0000, v50
	v_lshlrev_b32_e32 v47, 16, v51
	v_and_b32_e32 v51, 0xffff0000, v51
	v_add_f32_e32 v24, v44, v24
	v_add_f32_e32 v25, v48, v25
	v_add_f32_e32 v26, v45, v26
	v_add_f32_e32 v27, v49, v27
	v_add_f32_e32 v28, v46, v28
	v_add_f32_e32 v29, v50, v29
	v_add_f32_e32 v30, v47, v30
	v_add_f32_e32 v31, v51, v31
	v_fma_f32 v16, v16, -2.0, 1.0
	v_fma_f32 v17, v17, -2.0, 1.0
	v_fma_f32 v18, v18, -2.0, 1.0
	v_fma_f32 v19, v19, -2.0, 1.0
	v_fma_f32 v20, v20, -2.0, 1.0
	v_fma_f32 v21, v21, -2.0, 1.0
	v_fma_f32 v22, v22, -2.0, 1.0
	v_fma_f32 v23, v23, -2.0, 1.0
	v_mul_f32_e32 v8, 0.5, v8
	v_mul_f32_e32 v9, 0.5, v9
	v_mul_f32_e32 v10, 0.5, v10
	v_mul_f32_e32 v11, 0.5, v11
	v_mul_f32_e32 v12, 0.5, v12
	v_mul_f32_e32 v13, 0.5, v13
	v_mul_f32_e32 v14, 0.5, v14
	v_mul_f32_e32 v15, 0.5, v15
	v_add_f32_e32 v16, 1.0, v16
	v_add_f32_e32 v17, 1.0, v17
	v_add_f32_e32 v18, 1.0, v18
	v_add_f32_e32 v19, 1.0, v19
	v_add_f32_e32 v20, 1.0, v20
	v_add_f32_e32 v21, 1.0, v21
	v_add_f32_e32 v22, 1.0, v22
	v_add_f32_e32 v23, 1.0, v23
	v_mul_f32_e32 v8, v8, v16
	v_mul_f32_e32 v9, v9, v17
	v_mul_f32_e32 v10, v10, v18
	v_mul_f32_e32 v11, v11, v19
	v_mul_f32_e32 v12, v12, v20
	v_mul_f32_e32 v13, v13, v21
	v_mul_f32_e32 v14, v14, v22
	v_mul_f32_e32 v15, v15, v23
	v_mul_f32_e32 v24, v24, v8
	v_mul_f32_e32 v25, v25, v9
	v_mul_f32_e32 v26, v26, v10
	v_mul_f32_e32 v27, v27, v11
	v_mul_f32_e32 v28, v28, v12
	v_mul_f32_e32 v29, v29, v13
	v_mul_f32_e32 v30, v30, v14
	v_mul_f32_e32 v31, v31, v15
	v_mul_f32_e32 v48, v25, v25
	v_cvt_pk_bf16_f32 v44, v24, v25
	v_fmac_f32_e32 v48, v24, v24
	v_cvt_pk_bf16_f32 v45, v26, v27
	v_fmac_f32_e32 v48, v26, v26
	v_cvt_pk_bf16_f32 v46, v28, v29
	v_fmac_f32_e32 v48, v27, v27
	v_cvt_pk_bf16_f32 v47, v30, v31
	v_fmac_f32_e32 v48, v28, v28
	v_fmac_f32_e32 v48, v29, v29
	v_fmac_f32_e32 v48, v30, v30
	v_fmac_f32_e32 v48, v31, v31
	s_waitcnt vmcnt(39)
; __device__ __forceinline__ unsigned cvt_pk(float lo, float hi) { unsigned r; asm("v_cvt_pk_bf16_f32 %0, %1, %2" : "=v"(r) : "v"(lo), "v"(hi)); return r; }
; __device__ __forceinline__ float bflo(unsigned w) { return __uint_as_float(w << 16); }
; __device__ __forceinline__ float bfhi(unsigned w) { return __uint_as_float(w & 0xffff0000u); }
; __device__ __forceinline__ void rnn_combine(const Params& p) {
;     ...
;         for (int k = 0; k < 4; ++k) { const int rr = r0 + k * NW;
;             float y[8]; float q = 0.f;
; #pragma unroll
;             for (int i = 0; i < 4; ++i) { const unsigned a = hf[k][i], c = hb[k][i], gg = gw[k][i];
; #pragma unroll
;                 for (int e = 0; e < 2; ++e) { const float hs = (e ? bfhi(a) : bflo(a)) + (e ? bfhi(c) : bflo(c)); const float gt = e ? bfhi(gg) : bflo(gg);
;                     const float u = 0.7978845608028654f * (gt + 0.044715f * gt * gt * gt); const float th = 1.0f - 2.0f * __builtin_amdgcn_rcpf(1.0f + __builtin_amdgcn_exp2f(2.8853900817779268f * u));
;                     const float yv = hs * (0.5f * gt * (1.0f + th)); y[2 * i + e] = yv; q += yv * yv; } }
;             q = wave_sum(q);
;             if (rr < MR) { u32x4 w; w.x = cvt_pk(y[0], y[1]); w.y = cvt_pk(y[2], y[3]); w.z = cvt_pk(y[4], y[5]); w.w = cvt_pk(y[6], y[7]);
	v_lshlrev_b32_e32 v8, 16, v64
	v_and_b32_e32 v9, 0xffff0000, v64
	v_lshlrev_b32_e32 v10, 16, v65
	v_and_b32_e32 v11, 0xffff0000, v65
	v_lshlrev_b32_e32 v12, 16, v66
	v_and_b32_e32 v13, 0xffff0000, v66
	v_lshlrev_b32_e32 v14, 16, v67
	v_and_b32_e32 v15, 0xffff0000, v67
	v_mul_f32_e32 v16, 0x3d372713, v8
	v_mul_f32_e32 v17, 0x3d372713, v9
	v_mul_f32_e32 v18, 0x3d372713, v10
	v_mul_f32_e32 v19, 0x3d372713, v11
	v_mul_f32_e32 v20, 0x3d372713, v12
	v_mul_f32_e32 v21, 0x3d372713, v13
	v_mul_f32_e32 v22, 0x3d372713, v14
	v_mul_f32_e32 v23, 0x3d372713, v15
	v_mul_f32_e32 v16, v16, v8
	v_mul_f32_e32 v17, v17, v9
	v_mul_f32_e32 v18, v18, v10
	v_mul_f32_e32 v19, v19, v11
	v_mul_f32_e32 v20, v20, v12
	v_mul_f32_e32 v21, v21, v13
	v_mul_f32_e32 v22, v22, v14
	v_mul_f32_e32 v23, v23, v15
	v_fma_f32 v16, v16, v8, v8
	v_fma_f32 v17, v17, v9, v9
	v_fma_f32 v18, v18, v10, v10
	v_fma_f32 v19, v19, v11, v11
	v_fma_f32 v20, v20, v12, v12
	v_fma_f32 v21, v21, v13, v13
	v_fma_f32 v22, v22, v14, v14
	v_fma_f32 v23, v23, v15, v15
	v_mul_f32_e32 v16, 0x3f4c422a, v16
	v_mul_f32_e32 v17, 0x3f4c422a, v17
	v_mul_f32_e32 v18, 0x3f4c422a, v18
	v_mul_f32_e32 v19, 0x3f4c422a, v19
	v_mul_f32_e32 v20, 0x3f4c422a, v20
	v_mul_f32_e32 v21, 0x3f4c422a, v21
	v_mul_f32_e32 v22, 0x3f4c422a, v22
	v_mul_f32_e32 v23, 0x3f4c422a, v23
	v_mul_f32_e32 v16, 0x4038aa3b, v16
	v_mul_f32_e32 v17, 0x4038aa3b, v17
	v_mul_f32_e32 v18, 0x4038aa3b, v18
	v_mul_f32_e32 v19, 0x4038aa3b, v19
	v_mul_f32_e32 v20, 0x4038aa3b, v20
	v_mul_f32_e32 v21, 0x4038aa3b, v21
	v_mul_f32_e32 v22, 0x4038aa3b, v22
	v_mul_f32_e32 v23, 0x4038aa3b, v23
	v_exp_f32_e32 v16, v16
	v_exp_f32_e32 v17, v17
	v_exp_f32_e32 v18, v18
	v_exp_f32_e32 v19, v19
	v_exp_f32_e32 v20, v20
	v_exp_f32_e32 v21, v21
	v_exp_f32_e32 v22, v22
	v_exp_f32_e32 v23, v23
	v_lshlrev_b32_e32 v24, 16, v56
	v_and_b32_e32 v25, 0xffff0000, v56
	v_lshlrev_b32_e32 v26, 16, v57
	v_and_b32_e32 v27, 0xffff0000, v57
	v_lshlrev_b32_e32 v28, 16, v58
	v_and_b32_e32 v29, 0xffff0000, v58
	v_lshlrev_b32_e32 v30, 16, v59
	v_and_b32_e32 v31, 0xffff0000, v59
	v_add_f32_e32 v16, 1.0, v16
	v_add_f32_e32 v17, 1.0, v17
	v_add_f32_e32 v18, 1.0, v18
	v_add_f32_e32 v19, 1.0, v19
	v_add_f32_e32 v20, 1.0, v20
	v_add_f32_e32 v21, 1.0, v21
	v_add_f32_e32 v22, 1.0, v22
	v_add_f32_e32 v23, 1.0, v23
	v_rcp_f32_e32 v16, v16
	v_rcp_f32_e32 v17, v17
	v_rcp_f32_e32 v18, v18
	v_rcp_f32_e32 v19, v19
	v_rcp_f32_e32 v20, v20
	v_rcp_f32_e32 v21, v21
	v_rcp_f32_e32 v22, v22
	v_rcp_f32_e32 v23, v23
	v_lshlrev_b32_e32 v56, 16, v60
	v_and_b32_e32 v60, 0xffff0000, v60
	v_lshlrev_b32_e32 v57, 16, v61
	v_and_b32_e32 v61, 0xffff0000, v61
	v_lshlrev_b32_e32 v58, 16, v62
	v_and_b32_e32 v62, 0xffff0000, v62
	v_lshlrev_b32_e32 v59, 16, v63
	v_and_b32_e32 v63, 0xffff0000, v63
	v_add_f32_e32 v24, v56, v24
	v_add_f32_e32 v25, v60, v25
	v_add_f32_e32 v26, v57, v26
	v_add_f32_e32 v27, v61, v27
	v_add_f32_e32 v28, v58, v28
	v_add_f32_e32 v29, v62, v29
	v_add_f32_e32 v30, v59, v30
	v_add_f32_e32 v31, v63, v31
	v_fma_f32 v16, v16, -2.0, 1.0
	v_fma_f32 v17, v17, -2.0, 1.0
	v_fma_f32 v18, v18, -2.0, 1.0
	v_fma_f32 v19, v19, -2.0, 1.0
	v_fma_f32 v20, v20, -2.0, 1.0
	v_fma_f32 v21, v21, -2.0, 1.0
	v_fma_f32 v22, v22, -2.0, 1.0
	v_fma_f32 v23, v23, -2.0, 1.0
	v_mul_f32_e32 v8, 0.5, v8
	v_mul_f32_e32 v9, 0.5, v9
	v_mul_f32_e32 v10, 0.5, v10
	v_mul_f32_e32 v11, 0.5, v11
	v_mul_f32_e32 v12, 0.5, v12
	v_mul_f32_e32 v13, 0.5, v13
	v_mul_f32_e32 v14, 0.5, v14
	v_mul_f32_e32 v15, 0.5, v15
	v_add_f32_e32 v16, 1.0, v16
	v_add_f32_e32 v17, 1.0, v17
	v_add_f32_e32 v18, 1.0, v18
	v_add_f32_e32 v19, 1.0, v19
	v_add_f32_e32 v20, 1.0, v20
	v_add_f32_e32 v21, 1.0, v21
	v_add_f32_e32 v22, 1.0, v22
	v_add_f32_e32 v23, 1.0, v23
	v_mul_f32_e32 v8, v8, v16
	v_mul_f32_e32 v9, v9, v17
	v_mul_f32_e32 v10, v10, v18
	v_mul_f32_e32 v11, v11, v19
	v_mul_f32_e32 v12, v12, v20
	v_mul_f32_e32 v13, v13, v21
	v_mul_f32_e32 v14, v14, v22
	v_mul_f32_e32 v15, v15, v23
	v_mul_f32_e32 v24, v24, v8
	v_mul_f32_e32 v25, v25, v9
	v_mul_f32_e32 v26, v26, v10
	v_mul_f32_e32 v27, v27, v11
	v_mul_f32_e32 v28, v28, v12
	v_mul_f32_e32 v29, v29, v13
	v_mul_f32_e32 v30, v30, v14
	v_mul_f32_e32 v31, v31, v15
	v_mul_f32_e32 v60, v25, v25
	v_cvt_pk_bf16_f32 v56, v24, v25
	v_fmac_f32_e32 v60, v24, v24
	v_cvt_pk_bf16_f32 v57, v26, v27
	v_fmac_f32_e32 v60, v26, v26
	v_cvt_pk_bf16_f32 v58, v28, v29
	v_fmac_f32_e32 v60, v27, v27
	v_cvt_pk_bf16_f32 v59, v30, v31
	v_fmac_f32_e32 v60, v28, v28
	v_fmac_f32_e32 v60, v29, v29
	v_fmac_f32_e32 v60, v30, v30
	v_fmac_f32_e32 v60, v31, v31
	s_waitcnt vmcnt(36)
; __device__ __forceinline__ unsigned cvt_pk(float lo, float hi) { unsigned r; asm("v_cvt_pk_bf16_f32 %0, %1, %2" : "=v"(r) : "v"(lo), "v"(hi)); return r; }
; __device__ __forceinline__ float bflo(unsigned w) { return __uint_as_float(w << 16); }
; __device__ __forceinline__ float bfhi(unsigned w) { return __uint_as_float(w & 0xffff0000u); }
; __device__ __forceinline__ void rnn_combine(const Params& p) {
;     ...
;         for (int k = 0; k < 4; ++k) { const int rr = r0 + k * NW;
;             float y[8]; float q = 0.f;
; #pragma unroll
;             for (int i = 0; i < 4; ++i) { const unsigned a = hf[k][i], c = hb[k][i], gg = gw[k][i];
; #pragma unroll
;                 for (int e = 0; e < 2; ++e) { const float hs = (e ? bfhi(a) : bflo(a)) + (e ? bfhi(c) : bflo(c)); const float gt = e ? bfhi(gg) : bflo(gg);
;                     const float u = 0.7978845608028654f * (gt + 0.044715f * gt * gt * gt); const float th = 1.0f - 2.0f * __builtin_amdgcn_rcpf(1.0f + __builtin_amdgcn_exp2f(2.8853900817779268f * u));
;                     const float yv = hs * (0.5f * gt * (1.0f + th)); y[2 * i + e] = yv; q += yv * yv; } }
;             q = wave_sum(q);
;             if (rr < MR) { u32x4 w; w.x = cvt_pk(y[0], y[1]); w.y = cvt_pk(y[2], y[3]); w.z = cvt_pk(y[4], y[5]); w.w = cvt_pk(y[6], y[7]);
	v_lshlrev_b32_e32 v8, 16, v76
	v_and_b32_e32 v9, 0xffff0000, v76
	v_lshlrev_b32_e32 v10, 16, v77
	v_and_b32_e32 v11, 0xffff0000, v77
	v_lshlrev_b32_e32 v12, 16, v78
	v_and_b32_e32 v13, 0xffff0000, v78
	v_lshlrev_b32_e32 v14, 16, v79
	v_and_b32_e32 v15, 0xffff0000, v79
	v_mul_f32_e32 v16, 0x3d372713, v8
	v_mul_f32_e32 v17, 0x3d372713, v9
	v_mul_f32_e32 v18, 0x3d372713, v10
	v_mul_f32_e32 v19, 0x3d372713, v11
	v_mul_f32_e32 v20, 0x3d372713, v12
	v_mul_f32_e32 v21, 0x3d372713, v13
	v_mul_f32_e32 v22, 0x3d372713, v14
	v_mul_f32_e32 v23, 0x3d372713, v15
	v_mul_f32_e32 v16, v16, v8
	v_mul_f32_e32 v17, v17, v9
	v_mul_f32_e32 v18, v18, v10
	v_mul_f32_e32 v19, v19, v11
	v_mul_f32_e32 v20, v20, v12
	v_mul_f32_e32 v21, v21, v13
	v_mul_f32_e32 v22, v22, v14
	v_mul_f32_e32 v23, v23, v15
	v_fma_f32 v16, v16, v8, v8
	v_fma_f32 v17, v17, v9, v9
	v_fma_f32 v18, v18, v10, v10
	v_fma_f32 v19, v19, v11, v11
	v_fma_f32 v20, v20, v12, v12
	v_fma_f32 v21, v21, v13, v13
	v_fma_f32 v22, v22, v14, v14
	v_fma_f32 v23, v23, v15, v15
	v_mul_f32_e32 v16, 0x3f4c422a, v16
	v_mul_f32_e32 v17, 0x3f4c422a, v17
	v_mul_f32_e32 v18, 0x3f4c422a, v18
	v_mul_f32_e32 v19, 0x3f4c422a, v19
	v_mul_f32_e32 v20, 0x3f4c422a, v20
	v_mul_f32_e32 v21, 0x3f4c422a, v21
	v_mul_f32_e32 v22, 0x3f4c422a, v22
	v_mul_f32_e32 v23, 0x3f4c422a, v23
	v_mul_f32_e32 v16, 0x4038aa3b, v16
	v_mul_f32_e32 v17, 0x4038aa3b, v17
	v_mul_f32_e32 v18, 0x4038aa3b, v18
	v_mul_f32_e32 v19, 0x4038aa3b, v19
	v_mul_f32_e32 v20, 0x4038aa3b, v20
	v_mul_f32_e32 v21, 0x4038aa3b, v21
	v_mul_f32_e32 v22, 0x4038aa3b, v22
	v_mul_f32_e32 v23, 0x4038aa3b, v23
	v_exp_f32_e32 v16, v16
	v_exp_f32_e32 v17, v17
	v_exp_f32_e32 v18, v18
	v_exp_f32_e32 v19, v19
	v_exp_f32_e32 v20, v20
	v_exp_f32_e32 v21, v21
	v_exp_f32_e32 v22, v22
	v_exp_f32_e32 v23, v23
	v_lshlrev_b32_e32 v24, 16, v68
	v_and_b32_e32 v25, 0xffff0000, v68
	v_lshlrev_b32_e32 v26, 16, v69
	v_and_b32_e32 v27, 0xffff0000, v69
	v_lshlrev_b32_e32 v28, 16, v70
	v_and_b32_e32 v29, 0xffff0000, v70
	v_lshlrev_b32_e32 v30, 16, v71
	v_and_b32_e32 v31, 0xffff0000, v71
	v_add_f32_e32 v16, 1.0, v16
	v_add_f32_e32 v17, 1.0, v17
	v_add_f32_e32 v18, 1.0, v18
	v_add_f32_e32 v19, 1.0, v19
	v_add_f32_e32 v20, 1.0, v20
	v_add_f32_e32 v21, 1.0, v21
	v_add_f32_e32 v22, 1.0, v22
	v_add_f32_e32 v23, 1.0, v23
	v_rcp_f32_e32 v16, v16
	v_rcp_f32_e32 v17, v17
	v_rcp_f32_e32 v18, v18
	v_rcp_f32_e32 v19, v19
	v_rcp_f32_e32 v20, v20
	v_rcp_f32_e32 v21, v21
	v_rcp_f32_e32 v22, v22
	v_rcp_f32_e32 v23, v23
	v_lshlrev_b32_e32 v68, 16, v72
	v_and_b32_e32 v72, 0xffff0000, v72
	v_lshlrev_b32_e32 v69, 16, v73
	v_and_b32_e32 v73, 0xffff0000, v73
	v_lshlrev_b32_e32 v70, 16, v74
	v_and_b32_e32 v74, 0xffff0000, v74
	v_lshlrev_b32_e32 v71, 16, v75
	v_and_b32_e32 v75, 0xffff0000, v75
	v_add_f32_e32 v24, v68, v24
	v_add_f32_e32 v25, v72, v25
	v_add_f32_e32 v26, v69, v26
	v_add_f32_e32 v27, v73, v27
	v_add_f32_e32 v28, v70, v28
	v_add_f32_e32 v29, v74, v29
	v_add_f32_e32 v30, v71, v30
	v_add_f32_e32 v31, v75, v31
	v_fma_f32 v16, v16, -2.0, 1.0
	v_fma_f32 v17, v17, -2.0, 1.0
	v_fma_f32 v18, v18, -2.0, 1.0
	v_fma_f32 v19, v19, -2.0, 1.0
	v_fma_f32 v20, v20, -2.0, 1.0
	v_fma_f32 v21, v21, -2.0, 1.0
	v_fma_f32 v22, v22, -2.0, 1.0
	v_fma_f32 v23, v23, -2.0, 1.0
	v_mul_f32_e32 v8, 0.5, v8
	v_mul_f32_e32 v9, 0.5, v9
	v_mul_f32_e32 v10, 0.5, v10
	v_mul_f32_e32 v11, 0.5, v11
	v_mul_f32_e32 v12, 0.5, v12
	v_mul_f32_e32 v13, 0.5, v13
	v_mul_f32_e32 v14, 0.5, v14
	v_mul_f32_e32 v15, 0.5, v15
	v_add_f32_e32 v16, 1.0, v16
	v_add_f32_e32 v17, 1.0, v17
	v_add_f32_e32 v18, 1.0, v18
	v_add_f32_e32 v19, 1.0, v19
	v_add_f32_e32 v20, 1.0, v20
	v_add_f32_e32 v21, 1.0, v21
	v_add_f32_e32 v22, 1.0, v22
	v_add_f32_e32 v23, 1.0, v23
	v_mul_f32_e32 v8, v8, v16
	v_mul_f32_e32 v9, v9, v17
	v_mul_f32_e32 v10, v10, v18
	v_mul_f32_e32 v11, v11, v19
	v_mul_f32_e32 v12, v12, v20
	v_mul_f32_e32 v13, v13, v21
	v_mul_f32_e32 v14, v14, v22
	v_mul_f32_e32 v15, v15, v23
	v_mul_f32_e32 v24, v24, v8
	v_mul_f32_e32 v25, v25, v9
	v_mul_f32_e32 v26, v26, v10
	v_mul_f32_e32 v27, v27, v11
	v_mul_f32_e32 v28, v28, v12
	v_mul_f32_e32 v29, v29, v13
	v_mul_f32_e32 v30, v30, v14
	v_mul_f32_e32 v31, v31, v15
	v_mul_f32_e32 v72, v25, v25
	v_cvt_pk_bf16_f32 v68, v24, v25
	v_fmac_f32_e32 v72, v24, v24
	v_cvt_pk_bf16_f32 v69, v26, v27
	v_fmac_f32_e32 v72, v26, v26
	v_cvt_pk_bf16_f32 v70, v28, v29
	v_fmac_f32_e32 v72, v27, v27
	v_cvt_pk_bf16_f32 v71, v30, v31
	v_fmac_f32_e32 v72, v28, v28
	v_fmac_f32_e32 v72, v29, v29
	v_fmac_f32_e32 v72, v30, v30
	v_fmac_f32_e32 v72, v31, v31
	s_waitcnt vmcnt(33)
; __device__ __forceinline__ unsigned cvt_pk(float lo, float hi) { unsigned r; asm("v_cvt_pk_bf16_f32 %0, %1, %2" : "=v"(r) : "v"(lo), "v"(hi)); return r; }
; __device__ __forceinline__ float bflo(unsigned w) { return __uint_as_float(w << 16); }
; __device__ __forceinline__ float bfhi(unsigned w) { return __uint_as_float(w & 0xffff0000u); }
; __device__ __forceinline__ void rnn_combine(const Params& p) {
;     ...
;         for (int k = 0; k < 4; ++k) { const int rr = r0 + k * NW;
;             float y[8]; float q = 0.f;
; #pragma unroll
;             for (int i = 0; i < 4; ++i) { const unsigned a = hf[k][i], c = hb[k][i], gg = gw[k][i];
; #pragma unroll
;                 for (int e = 0; e < 2; ++e) { const float hs = (e ? bfhi(a) : bflo(a)) + (e ? bfhi(c) : bflo(c)); const float gt = e ? bfhi(gg) : bflo(gg);
;                     const float u = 0.7978845608028654f * (gt + 0.044715f * gt * gt * gt); const float th = 1.0f - 2.0f * __builtin_amdgcn_rcpf(1.0f + __builtin_amdgcn_exp2f(2.8853900817779268f * u));
;                     const float yv = hs * (0.5f * gt * (1.0f + th)); y[2 * i + e] = yv; q += yv * yv; } }
;             q = wave_sum(q);
;             if (rr < MR) { u32x4 w; w.x = cvt_pk(y[0], y[1]); w.y = cvt_pk(y[2], y[3]); w.z = cvt_pk(y[4], y[5]); w.w = cvt_pk(y[6], y[7]);
	v_lshlrev_b32_e32 v8, 16, v88
	v_and_b32_e32 v9, 0xffff0000, v88
	v_lshlrev_b32_e32 v10, 16, v89
	v_and_b32_e32 v11, 0xffff0000, v89
	v_lshlrev_b32_e32 v12, 16, v90
	v_and_b32_e32 v13, 0xffff0000, v90
	v_lshlrev_b32_e32 v14, 16, v91
	v_and_b32_e32 v15, 0xffff0000, v91
	v_mul_f32_e32 v16, 0x3d372713, v8
	v_mul_f32_e32 v17, 0x3d372713, v9
	v_mul_f32_e32 v18, 0x3d372713, v10
	v_mul_f32_e32 v19, 0x3d372713, v11
	v_mul_f32_e32 v20, 0x3d372713, v12
	v_mul_f32_e32 v21, 0x3d372713, v13
	v_mul_f32_e32 v22, 0x3d372713, v14
	v_mul_f32_e32 v23, 0x3d372713, v15
	v_mul_f32_e32 v16, v16, v8
	v_mul_f32_e32 v17, v17, v9
	v_mul_f32_e32 v18, v18, v10
	v_mul_f32_e32 v19, v19, v11
	v_mul_f32_e32 v20, v20, v12
	v_mul_f32_e32 v21, v21, v13
	v_mul_f32_e32 v22, v22, v14
	v_mul_f32_e32 v23, v23, v15
	v_fma_f32 v16, v16, v8, v8
	v_fma_f32 v17, v17, v9, v9
	v_fma_f32 v18, v18, v10, v10
	v_fma_f32 v19, v19, v11, v11
	v_fma_f32 v20, v20, v12, v12
	v_fma_f32 v21, v21, v13, v13
	v_fma_f32 v22, v22, v14, v14
	v_fma_f32 v23, v23, v15, v15
	v_mul_f32_e32 v16, 0x3f4c422a, v16
	v_mul_f32_e32 v17, 0x3f4c422a, v17
	v_mul_f32_e32 v18, 0x3f4c422a, v18
	v_mul_f32_e32 v19, 0x3f4c422a, v19
	v_mul_f32_e32 v20, 0x3f4c422a, v20
	v_mul_f32_e32 v21, 0x3f4c422a, v21
	v_mul_f32_e32 v22, 0x3f4c422a, v22
	v_mul_f32_e32 v23, 0x3f4c422a, v23
	v_mul_f32_e32 v16, 0x4038aa3b, v16
	v_mul_f32_e32 v17, 0x4038aa3b, v17
	v_mul_f32_e32 v18, 0x4038aa3b, v18
	v_mul_f32_e32 v19, 0x4038aa3b, v19
	v_mul_f32_e32 v20, 0x4038aa3b, v20
	v_mul_f32_e32 v21, 0x4038aa3b, v21
	v_mul_f32_e32 v22, 0x4038aa3b, v22
	v_mul_f32_e32 v23, 0x4038aa3b, v23
	v_exp_f32_e32 v16, v16
	v_exp_f32_e32 v17, v17
	v_exp_f32_e32 v18, v18
	v_exp_f32_e32 v19, v19
	v_exp_f32_e32 v20, v20
	v_exp_f32_e32 v21, v21
	v_exp_f32_e32 v22, v22
	v_exp_f32_e32 v23, v23
	v_lshlrev_b32_e32 v24, 16, v80
	v_and_b32_e32 v25, 0xffff0000, v80
	v_lshlrev_b32_e32 v26, 16, v81
	v_and_b32_e32 v27, 0xffff0000, v81
	v_lshlrev_b32_e32 v28, 16, v82
	v_and_b32_e32 v29, 0xffff0000, v82
	v_lshlrev_b32_e32 v30, 16, v83
	v_and_b32_e32 v31, 0xffff0000, v83
	v_add_f32_e32 v16, 1.0, v16
	v_add_f32_e32 v17, 1.0, v17
	v_add_f32_e32 v18, 1.0, v18
	v_add_f32_e32 v19, 1.0, v19
	v_add_f32_e32 v20, 1.0, v20
	v_add_f32_e32 v21, 1.0, v21
	v_add_f32_e32 v22, 1.0, v22
	v_add_f32_e32 v23, 1.0, v23
	v_rcp_f32_e32 v16, v16
	v_rcp_f32_e32 v17, v17
	v_rcp_f32_e32 v18, v18
	v_rcp_f32_e32 v19, v19
	v_rcp_f32_e32 v20, v20
	v_rcp_f32_e32 v21, v21
	v_rcp_f32_e32 v22, v22
	v_rcp_f32_e32 v23, v23
	v_lshlrev_b32_e32 v80, 16, v84
	v_and_b32_e32 v84, 0xffff0000, v84
	v_lshlrev_b32_e32 v81, 16, v85
	v_and_b32_e32 v85, 0xffff0000, v85
	v_lshlrev_b32_e32 v82, 16, v86
	v_and_b32_e32 v86, 0xffff0000, v86
	v_lshlrev_b32_e32 v83, 16, v87
	v_and_b32_e32 v87, 0xffff0000, v87
	v_add_f32_e32 v24, v80, v24
	v_add_f32_e32 v25, v84, v25
	v_add_f32_e32 v26, v81, v26
	v_add_f32_e32 v27, v85, v27
	v_add_f32_e32 v28, v82, v28
	v_add_f32_e32 v29, v86, v29
	v_add_f32_e32 v30, v83, v30
	v_add_f32_e32 v31, v87, v31
	v_fma_f32 v16, v16, -2.0, 1.0
	v_fma_f32 v17, v17, -2.0, 1.0
	v_fma_f32 v18, v18, -2.0, 1.0
	v_fma_f32 v19, v19, -2.0, 1.0
	v_fma_f32 v20, v20, -2.0, 1.0
	v_fma_f32 v21, v21, -2.0, 1.0
	v_fma_f32 v22, v22, -2.0, 1.0
	v_fma_f32 v23, v23, -2.0, 1.0
	v_mul_f32_e32 v8, 0.5, v8
	v_mul_f32_e32 v9, 0.5, v9
	v_mul_f32_e32 v10, 0.5, v10
	v_mul_f32_e32 v11, 0.5, v11
	v_mul_f32_e32 v12, 0.5, v12
	v_mul_f32_e32 v13, 0.5, v13
	v_mul_f32_e32 v14, 0.5, v14
	v_mul_f32_e32 v15, 0.5, v15
	v_add_f32_e32 v16, 1.0, v16
	v_add_f32_e32 v17, 1.0, v17
	v_add_f32_e32 v18, 1.0, v18
	v_add_f32_e32 v19, 1.0, v19
	v_add_f32_e32 v20, 1.0, v20
	v_add_f32_e32 v21, 1.0, v21
	v_add_f32_e32 v22, 1.0, v22
	v_add_f32_e32 v23, 1.0, v23
	v_mul_f32_e32 v8, v8, v16
	v_mul_f32_e32 v9, v9, v17
	v_mul_f32_e32 v10, v10, v18
	v_mul_f32_e32 v11, v11, v19
	v_mul_f32_e32 v12, v12, v20
	v_mul_f32_e32 v13, v13, v21
	v_mul_f32_e32 v14, v14, v22
	v_mul_f32_e32 v15, v15, v23
	v_mul_f32_e32 v24, v24, v8
	v_mul_f32_e32 v25, v25, v9
	v_mul_f32_e32 v26, v26, v10
	v_mul_f32_e32 v27, v27, v11
	v_mul_f32_e32 v28, v28, v12
	v_mul_f32_e32 v29, v29, v13
	v_mul_f32_e32 v30, v30, v14
	v_mul_f32_e32 v31, v31, v15
	v_mul_f32_e32 v84, v25, v25
	v_cvt_pk_bf16_f32 v80, v24, v25
	v_fmac_f32_e32 v84, v24, v24
	v_cvt_pk_bf16_f32 v81, v26, v27
	v_fmac_f32_e32 v84, v26, v26
	v_cvt_pk_bf16_f32 v82, v28, v29
	v_fmac_f32_e32 v84, v27, v27
	v_cvt_pk_bf16_f32 v83, v30, v31
	v_fmac_f32_e32 v84, v28, v28
	v_fmac_f32_e32 v84, v29, v29
	v_fmac_f32_e32 v84, v30, v30
	v_fmac_f32_e32 v84, v31, v31
	s_waitcnt vmcnt(30)
; __device__ __forceinline__ unsigned cvt_pk(float lo, float hi) { unsigned r; asm("v_cvt_pk_bf16_f32 %0, %1, %2" : "=v"(r) : "v"(lo), "v"(hi)); return r; }
; __device__ __forceinline__ float bflo(unsigned w) { return __uint_as_float(w << 16); }
; __device__ __forceinline__ float bfhi(unsigned w) { return __uint_as_float(w & 0xffff0000u); }
; __device__ __forceinline__ void rnn_combine(const Params& p) {
;     ...
;         for (int k = 0; k < 4; ++k) { const int rr = r0 + k * NW;
;             float y[8]; float q = 0.f;
; #pragma unroll
;             for (int i = 0; i < 4; ++i) { const unsigned a = hf[k][i], c = hb[k][i], gg = gw[k][i];
; #pragma unroll
;                 for (int e = 0; e < 2; ++e) { const float hs = (e ? bfhi(a) : bflo(a)) + (e ? bfhi(c) : bflo(c)); const float gt = e ? bfhi(gg) : bflo(gg);
;                     const float u = 0.7978845608028654f * (gt + 0.044715f * gt * gt * gt); const float th = 1.0f - 2.0f * __builtin_amdgcn_rcpf(1.0f + __builtin_amdgcn_exp2f(2.8853900817779268f * u));
;                     const float yv = hs * (0.5f * gt * (1.0f + th)); y[2 * i + e] = yv; q += yv * yv; } }
;             q = wave_sum(q);
;             if (rr < MR) { u32x4 w; w.x = cvt_pk(y[0], y[1]); w.y = cvt_pk(y[2], y[3]); w.z = cvt_pk(y[4], y[5]); w.w = cvt_pk(y[6], y[7]);
	v_lshlrev_b32_e32 v8, 16, v100
	v_and_b32_e32 v9, 0xffff0000, v100
	v_lshlrev_b32_e32 v10, 16, v101
	v_and_b32_e32 v11, 0xffff0000, v101
	v_lshlrev_b32_e32 v12, 16, v102
	v_and_b32_e32 v13, 0xffff0000, v102
	v_lshlrev_b32_e32 v14, 16, v103
	v_and_b32_e32 v15, 0xffff0000, v103
	v_mul_f32_e32 v16, 0x3d372713, v8
	v_mul_f32_e32 v17, 0x3d372713, v9
	v_mul_f32_e32 v18, 0x3d372713, v10
	v_mul_f32_e32 v19, 0x3d372713, v11
	v_mul_f32_e32 v20, 0x3d372713, v12
	v_mul_f32_e32 v21, 0x3d372713, v13
	v_mul_f32_e32 v22, 0x3d372713, v14
	v_mul_f32_e32 v23, 0x3d372713, v15
	v_mul_f32_e32 v16, v16, v8
	v_mul_f32_e32 v17, v17, v9
	v_mul_f32_e32 v18, v18, v10
	v_mul_f32_e32 v19, v19, v11
	v_mul_f32_e32 v20, v20, v12
	v_mul_f32_e32 v21, v21, v13
	v_mul_f32_e32 v22, v22, v14
	v_mul_f32_e32 v23, v23, v15
	v_fma_f32 v16, v16, v8, v8
	v_fma_f32 v17, v17, v9, v9
	v_fma_f32 v18, v18, v10, v10
	v_fma_f32 v19, v19, v11, v11
	v_fma_f32 v20, v20, v12, v12
	v_fma_f32 v21, v21, v13, v13
	v_fma_f32 v22, v22, v14, v14
	v_fma_f32 v23, v23, v15, v15
	v_mul_f32_e32 v16, 0x3f4c422a, v16
	v_mul_f32_e32 v17, 0x3f4c422a, v17
	v_mul_f32_e32 v18, 0x3f4c422a, v18
	v_mul_f32_e32 v19, 0x3f4c422a, v19
	v_mul_f32_e32 v20, 0x3f4c422a, v20
	v_mul_f32_e32 v21, 0x3f4c422a, v21
	v_mul_f32_e32 v22, 0x3f4c422a, v22
	v_mul_f32_e32 v23, 0x3f4c422a, v23
	v_mul_f32_e32 v16, 0x4038aa3b, v16
	v_mul_f32_e32 v17, 0x4038aa3b, v17
	v_mul_f32_e32 v18, 0x4038aa3b, v18
	v_mul_f32_e32 v19, 0x4038aa3b, v19
	v_mul_f32_e32 v20, 0x4038aa3b, v20
	v_mul_f32_e32 v21, 0x4038aa3b, v21
	v_mul_f32_e32 v22, 0x4038aa3b, v22
	v_mul_f32_e32 v23, 0x4038aa3b, v23
	v_exp_f32_e32 v16, v16
	v_exp_f32_e32 v17, v17
	v_exp_f32_e32 v18, v18
	v_exp_f32_e32 v19, v19
	v_exp_f32_e32 v20, v20
	v_exp_f32_e32 v21, v21
	v_exp_f32_e32 v22, v22
	v_exp_f32_e32 v23, v23
	v_lshlrev_b32_e32 v24, 16, v92
	v_and_b32_e32 v25, 0xffff0000, v92
	v_lshlrev_b32_e32 v26, 16, v93
	v_and_b32_e32 v27, 0xffff0000, v93
	v_lshlrev_b32_e32 v28, 16, v94
	v_and_b32_e32 v29, 0xffff0000, v94
	v_lshlrev_b32_e32 v30, 16, v95
	v_and_b32_e32 v31, 0xffff0000, v95
	v_add_f32_e32 v16, 1.0, v16
	v_add_f32_e32 v17, 1.0, v17
	v_add_f32_e32 v18, 1.0, v18
	v_add_f32_e32 v19, 1.0, v19
	v_add_f32_e32 v20, 1.0, v20
	v_add_f32_e32 v21, 1.0, v21
	v_add_f32_e32 v22, 1.0, v22
	v_add_f32_e32 v23, 1.0, v23
	v_rcp_f32_e32 v16, v16
	v_rcp_f32_e32 v17, v17
	v_rcp_f32_e32 v18, v18
	v_rcp_f32_e32 v19, v19
	v_rcp_f32_e32 v20, v20
	v_rcp_f32_e32 v21, v21
	v_rcp_f32_e32 v22, v22
	v_rcp_f32_e32 v23, v23
	v_lshlrev_b32_e32 v92, 16, v96
	v_and_b32_e32 v96, 0xffff0000, v96
	v_lshlrev_b32_e32 v93, 16, v97
	v_and_b32_e32 v97, 0xffff0000, v97
	v_lshlrev_b32_e32 v94, 16, v98
	v_and_b32_e32 v98, 0xffff0000, v98
	v_lshlrev_b32_e32 v95, 16, v99
	v_and_b32_e32 v99, 0xffff0000, v99
	v_add_f32_e32 v24, v92, v24
	v_add_f32_e32 v25, v96, v25
	v_add_f32_e32 v26, v93, v26
	v_add_f32_e32 v27, v97, v27
	v_add_f32_e32 v28, v94, v28
	v_add_f32_e32 v29, v98, v29
	v_add_f32_e32 v30, v95, v30
	v_add_f32_e32 v31, v99, v31
	v_fma_f32 v16, v16, -2.0, 1.0
	v_fma_f32 v17, v17, -2.0, 1.0
	v_fma_f32 v18, v18, -2.0, 1.0
	v_fma_f32 v19, v19, -2.0, 1.0
	v_fma_f32 v20, v20, -2.0, 1.0
	v_fma_f32 v21, v21, -2.0, 1.0
	v_fma_f32 v22, v22, -2.0, 1.0
	v_fma_f32 v23, v23, -2.0, 1.0
	v_mul_f32_e32 v8, 0.5, v8
	v_mul_f32_e32 v9, 0.5, v9
	v_mul_f32_e32 v10, 0.5, v10
	v_mul_f32_e32 v11, 0.5, v11
	v_mul_f32_e32 v12, 0.5, v12
	v_mul_f32_e32 v13, 0.5, v13
	v_mul_f32_e32 v14, 0.5, v14
	v_mul_f32_e32 v15, 0.5, v15
	v_add_f32_e32 v16, 1.0, v16
	v_add_f32_e32 v17, 1.0, v17
	v_add_f32_e32 v18, 1.0, v18
	v_add_f32_e32 v19, 1.0, v19
	v_add_f32_e32 v20, 1.0, v20
	v_add_f32_e32 v21, 1.0, v21
	v_add_f32_e32 v22, 1.0, v22
	v_add_f32_e32 v23, 1.0, v23
	v_mul_f32_e32 v8, v8, v16
	v_mul_f32_e32 v9, v9, v17
	v_mul_f32_e32 v10, v10, v18
	v_mul_f32_e32 v11, v11, v19
	v_mul_f32_e32 v12, v12, v20
	v_mul_f32_e32 v13, v13, v21
	v_mul_f32_e32 v14, v14, v22
	v_mul_f32_e32 v15, v15, v23
	v_mul_f32_e32 v24, v24, v8
	v_mul_f32_e32 v25, v25, v9
	v_mul_f32_e32 v26, v26, v10
	v_mul_f32_e32 v27, v27, v11
	v_mul_f32_e32 v28, v28, v12
	v_mul_f32_e32 v29, v29, v13
	v_mul_f32_e32 v30, v30, v14
	v_mul_f32_e32 v31, v31, v15
	v_mul_f32_e32 v96, v25, v25
	v_cvt_pk_bf16_f32 v92, v24, v25
	v_fmac_f32_e32 v96, v24, v24
	v_cvt_pk_bf16_f32 v93, v26, v27
	v_fmac_f32_e32 v96, v26, v26
	v_cvt_pk_bf16_f32 v94, v28, v29
	v_fmac_f32_e32 v96, v27, v27
	v_cvt_pk_bf16_f32 v95, v30, v31
	v_fmac_f32_e32 v96, v28, v28
	v_fmac_f32_e32 v96, v29, v29
	v_fmac_f32_e32 v96, v30, v30
	v_fmac_f32_e32 v96, v31, v31
	s_waitcnt vmcnt(27)
; __device__ __forceinline__ unsigned cvt_pk(float lo, float hi) { unsigned r; asm("v_cvt_pk_bf16_f32 %0, %1, %2" : "=v"(r) : "v"(lo), "v"(hi)); return r; }
; __device__ __forceinline__ float bflo(unsigned w) { return __uint_as_float(w << 16); }
; __device__ __forceinline__ float bfhi(unsigned w) { return __uint_as_float(w & 0xffff0000u); }
; __device__ __forceinline__ void rnn_combine(const Params& p) {
;     ...
;         for (int k = 0; k < 4; ++k) { const int rr = r0 + k * NW;
;             float y[8]; float q = 0.f;
; #pragma unroll
;             for (int i = 0; i < 4; ++i) { const unsigned a = hf[k][i], c = hb[k][i], gg = gw[k][i];
; #pragma unroll
;                 for (int e = 0; e < 2; ++e) { const float hs = (e ? bfhi(a) : bflo(a)) + (e ? bfhi(c) : bflo(c)); const float gt = e ? bfhi(gg) : bflo(gg);
;                     const float u = 0.7978845608028654f * (gt + 0.044715f * gt * gt * gt); const float th = 1.0f - 2.0f * __builtin_amdgcn_rcpf(1.0f + __builtin_amdgcn_exp2f(2.8853900817779268f * u));
;                     const float yv = hs * (0.5f * gt * (1.0f + th)); y[2 * i + e] = yv; q += yv * yv; } }
;             q = wave_sum(q);
;             if (rr < MR) { u32x4 w; w.x = cvt_pk(y[0], y[1]); w.y = cvt_pk(y[2], y[3]); w.z = cvt_pk(y[4], y[5]); w.w = cvt_pk(y[6], y[7]);
	v_lshlrev_b32_e32 v8, 16, v112
	v_and_b32_e32 v9, 0xffff0000, v112
	v_lshlrev_b32_e32 v10, 16, v113
	v_and_b32_e32 v11, 0xffff0000, v113
	v_lshlrev_b32_e32 v12, 16, v114
	v_and_b32_e32 v13, 0xffff0000, v114
	v_lshlrev_b32_e32 v14, 16, v115
	v_and_b32_e32 v15, 0xffff0000, v115
	v_mul_f32_e32 v16, 0x3d372713, v8
	v_mul_f32_e32 v17, 0x3d372713, v9
	v_mul_f32_e32 v18, 0x3d372713, v10
	v_mul_f32_e32 v19, 0x3d372713, v11
	v_mul_f32_e32 v20, 0x3d372713, v12
	v_mul_f32_e32 v21, 0x3d372713, v13
	v_mul_f32_e32 v22, 0x3d372713, v14
	v_mul_f32_e32 v23, 0x3d372713, v15
	v_mul_f32_e32 v16, v16, v8
	v_mul_f32_e32 v17, v17, v9
	v_mul_f32_e32 v18, v18, v10
	v_mul_f32_e32 v19, v19, v11
	v_mul_f32_e32 v20, v20, v12
	v_mul_f32_e32 v21, v21, v13
	v_mul_f32_e32 v22, v22, v14
	v_mul_f32_e32 v23, v23, v15
	v_fma_f32 v16, v16, v8, v8
	v_fma_f32 v17, v17, v9, v9
	v_fma_f32 v18, v18, v10, v10
	v_fma_f32 v19, v19, v11, v11
	v_fma_f32 v20, v20, v12, v12
	v_fma_f32 v21, v21, v13, v13
	v_fma_f32 v22, v22, v14, v14
	v_fma_f32 v23, v23, v15, v15
	v_mul_f32_e32 v16, 0x3f4c422a, v16
	v_mul_f32_e32 v17, 0x3f4c422a, v17
	v_mul_f32_e32 v18, 0x3f4c422a, v18
	v_mul_f32_e32 v19, 0x3f4c422a, v19
	v_mul_f32_e32 v20, 0x3f4c422a, v20
	v_mul_f32_e32 v21, 0x3f4c422a, v21
	v_mul_f32_e32 v22, 0x3f4c422a, v22
	v_mul_f32_e32 v23, 0x3f4c422a, v23
	v_mul_f32_e32 v16, 0x4038aa3b, v16
	v_mul_f32_e32 v17, 0x4038aa3b, v17
	v_mul_f32_e32 v18, 0x4038aa3b, v18
	v_mul_f32_e32 v19, 0x4038aa3b, v19
	v_mul_f32_e32 v20, 0x4038aa3b, v20
	v_mul_f32_e32 v21, 0x4038aa3b, v21
	v_mul_f32_e32 v22, 0x4038aa3b, v22
	v_mul_f32_e32 v23, 0x4038aa3b, v23
	v_exp_f32_e32 v16, v16
	v_exp_f32_e32 v17, v17
	v_exp_f32_e32 v18, v18
	v_exp_f32_e32 v19, v19
	v_exp_f32_e32 v20, v20
	v_exp_f32_e32 v21, v21
	v_exp_f32_e32 v22, v22
	v_exp_f32_e32 v23, v23
	v_lshlrev_b32_e32 v24, 16, v104
	v_and_b32_e32 v25, 0xffff0000, v104
	v_lshlrev_b32_e32 v26, 16, v105
	v_and_b32_e32 v27, 0xffff0000, v105
	v_lshlrev_b32_e32 v28, 16, v106
	v_and_b32_e32 v29, 0xffff0000, v106
	v_lshlrev_b32_e32 v30, 16, v107
	v_and_b32_e32 v31, 0xffff0000, v107
	v_add_f32_e32 v16, 1.0, v16
	v_add_f32_e32 v17, 1.0, v17
	v_add_f32_e32 v18, 1.0, v18
	v_add_f32_e32 v19, 1.0, v19
	v_add_f32_e32 v20, 1.0, v20
	v_add_f32_e32 v21, 1.0, v21
	v_add_f32_e32 v22, 1.0, v22
	v_add_f32_e32 v23, 1.0, v23
	v_rcp_f32_e32 v16, v16
	v_rcp_f32_e32 v17, v17
	v_rcp_f32_e32 v18, v18
	v_rcp_f32_e32 v19, v19
	v_rcp_f32_e32 v20, v20
	v_rcp_f32_e32 v21, v21
	v_rcp_f32_e32 v22, v22
	v_rcp_f32_e32 v23, v23
	v_lshlrev_b32_e32 v104, 16, v108
	v_and_b32_e32 v108, 0xffff0000, v108
	v_lshlrev_b32_e32 v105, 16, v109
	v_and_b32_e32 v109, 0xffff0000, v109
	v_lshlrev_b32_e32 v106, 16, v110
	v_and_b32_e32 v110, 0xffff0000, v110
	v_lshlrev_b32_e32 v107, 16, v111
	v_and_b32_e32 v111, 0xffff0000, v111
	v_add_f32_e32 v24, v104, v24
	v_add_f32_e32 v25, v108, v25
	v_add_f32_e32 v26, v105, v26
	v_add_f32_e32 v27, v109, v27
	v_add_f32_e32 v28, v106, v28
	v_add_f32_e32 v29, v110, v29
	v_add_f32_e32 v30, v107, v30
	v_add_f32_e32 v31, v111, v31
	v_fma_f32 v16, v16, -2.0, 1.0
	v_fma_f32 v17, v17, -2.0, 1.0
	v_fma_f32 v18, v18, -2.0, 1.0
	v_fma_f32 v19, v19, -2.0, 1.0
	v_fma_f32 v20, v20, -2.0, 1.0
	v_fma_f32 v21, v21, -2.0, 1.0
	v_fma_f32 v22, v22, -2.0, 1.0
	v_fma_f32 v23, v23, -2.0, 1.0
	v_mul_f32_e32 v8, 0.5, v8
	v_mul_f32_e32 v9, 0.5, v9
	v_mul_f32_e32 v10, 0.5, v10
	v_mul_f32_e32 v11, 0.5, v11
	v_mul_f32_e32 v12, 0.5, v12
	v_mul_f32_e32 v13, 0.5, v13
	v_mul_f32_e32 v14, 0.5, v14
	v_mul_f32_e32 v15, 0.5, v15
	v_add_f32_e32 v16, 1.0, v16
	v_add_f32_e32 v17, 1.0, v17
	v_add_f32_e32 v18, 1.0, v18
	v_add_f32_e32 v19, 1.0, v19
	v_add_f32_e32 v20, 1.0, v20
	v_add_f32_e32 v21, 1.0, v21
	v_add_f32_e32 v22, 1.0, v22
	v_add_f32_e32 v23, 1.0, v23
	v_mul_f32_e32 v8, v8, v16
	v_mul_f32_e32 v9, v9, v17
	v_mul_f32_e32 v10, v10, v18
	v_mul_f32_e32 v11, v11, v19
	v_mul_f32_e32 v12, v12, v20
	v_mul_f32_e32 v13, v13, v21
	v_mul_f32_e32 v14, v14, v22
	v_mul_f32_e32 v15, v15, v23
	v_mul_f32_e32 v24, v24, v8
	v_mul_f32_e32 v25, v25, v9
	v_mul_f32_e32 v26, v26, v10
	v_mul_f32_e32 v27, v27, v11
	v_mul_f32_e32 v28, v28, v12
	v_mul_f32_e32 v29, v29, v13
	v_mul_f32_e32 v30, v30, v14
	v_mul_f32_e32 v31, v31, v15
	v_mul_f32_e32 v108, v25, v25
	v_cvt_pk_bf16_f32 v104, v24, v25
	v_fmac_f32_e32 v108, v24, v24
	v_cvt_pk_bf16_f32 v105, v26, v27
	v_fmac_f32_e32 v108, v26, v26
	v_cvt_pk_bf16_f32 v106, v28, v29
	v_fmac_f32_e32 v108, v27, v27
	v_cvt_pk_bf16_f32 v107, v30, v31
	v_fmac_f32_e32 v108, v28, v28
	v_fmac_f32_e32 v108, v29, v29
	v_fmac_f32_e32 v108, v30, v30
	v_fmac_f32_e32 v108, v31, v31
	s_waitcnt vmcnt(24)
; __device__ __forceinline__ unsigned cvt_pk(float lo, float hi) { unsigned r; asm("v_cvt_pk_bf16_f32 %0, %1, %2" : "=v"(r) : "v"(lo), "v"(hi)); return r; }
; __device__ __forceinline__ float bflo(unsigned w) { return __uint_as_float(w << 16); }
; __device__ __forceinline__ float bfhi(unsigned w) { return __uint_as_float(w & 0xffff0000u); }
; __device__ __forceinline__ void rnn_combine(const Params& p) {
;     ...
;         for (int k = 0; k < 4; ++k) { const int rr = r0 + k * NW;
;             float y[8]; float q = 0.f;
; #pragma unroll
;             for (int i = 0; i < 4; ++i) { const unsigned a = hf[k][i], c = hb[k][i], gg = gw[k][i];
; #pragma unroll
;                 for (int e = 0; e < 2; ++e) { const float hs = (e ? bfhi(a) : bflo(a)) + (e ? bfhi(c) : bflo(c)); const float gt = e ? bfhi(gg) : bflo(gg);
;                     const float u = 0.7978845608028654f * (gt + 0.044715f * gt * gt * gt); const float th = 1.0f - 2.0f * __builtin_amdgcn_rcpf(1.0f + __builtin_amdgcn_exp2f(2.8853900817779268f * u));
;                     const float yv = hs * (0.5f * gt * (1.0f + th)); y[2 * i + e] = yv; q += yv * yv; } }
;             q = wave_sum(q);
;             if (rr < MR) { u32x4 w; w.x = cvt_pk(y[0], y[1]); w.y = cvt_pk(y[2], y[3]); w.z = cvt_pk(y[4], y[5]); w.w = cvt_pk(y[6], y[7]);
	v_lshlrev_b32_e32 v8, 16, v124
	v_and_b32_e32 v9, 0xffff0000, v124
	v_lshlrev_b32_e32 v10, 16, v125
	v_and_b32_e32 v11, 0xffff0000, v125
	v_lshlrev_b32_e32 v12, 16, v126
	v_and_b32_e32 v13, 0xffff0000, v126
	v_lshlrev_b32_e32 v14, 16, v127
	v_and_b32_e32 v15, 0xffff0000, v127
	v_mul_f32_e32 v16, 0x3d372713, v8
	v_mul_f32_e32 v17, 0x3d372713, v9
	v_mul_f32_e32 v18, 0x3d372713, v10
	v_mul_f32_e32 v19, 0x3d372713, v11
	v_mul_f32_e32 v20, 0x3d372713, v12
	v_mul_f32_e32 v21, 0x3d372713, v13
	v_mul_f32_e32 v22, 0x3d372713, v14
	v_mul_f32_e32 v23, 0x3d372713, v15
	v_mul_f32_e32 v16, v16, v8
	v_mul_f32_e32 v17, v17, v9
	v_mul_f32_e32 v18, v18, v10
	v_mul_f32_e32 v19, v19, v11
	v_mul_f32_e32 v20, v20, v12
	v_mul_f32_e32 v21, v21, v13
	v_mul_f32_e32 v22, v22, v14
	v_mul_f32_e32 v23, v23, v15
	v_fma_f32 v16, v16, v8, v8
	v_fma_f32 v17, v17, v9, v9
	v_fma_f32 v18, v18, v10, v10
	v_fma_f32 v19, v19, v11, v11
	v_fma_f32 v20, v20, v12, v12
	v_fma_f32 v21, v21, v13, v13
	v_fma_f32 v22, v22, v14, v14
	v_fma_f32 v23, v23, v15, v15
	v_mul_f32_e32 v16, 0x3f4c422a, v16
	v_mul_f32_e32 v17, 0x3f4c422a, v17
	v_mul_f32_e32 v18, 0x3f4c422a, v18
	v_mul_f32_e32 v19, 0x3f4c422a, v19
	v_mul_f32_e32 v20, 0x3f4c422a, v20
	v_mul_f32_e32 v21, 0x3f4c422a, v21
	v_mul_f32_e32 v22, 0x3f4c422a, v22
	v_mul_f32_e32 v23, 0x3f4c422a, v23
	v_mul_f32_e32 v16, 0x4038aa3b, v16
	v_mul_f32_e32 v17, 0x4038aa3b, v17
	v_mul_f32_e32 v18, 0x4038aa3b, v18
	v_mul_f32_e32 v19, 0x4038aa3b, v19
	v_mul_f32_e32 v20, 0x4038aa3b, v20
	v_mul_f32_e32 v21, 0x4038aa3b, v21
	v_mul_f32_e32 v22, 0x4038aa3b, v22
	v_mul_f32_e32 v23, 0x4038aa3b, v23
	v_exp_f32_e32 v16, v16
	v_exp_f32_e32 v17, v17
	v_exp_f32_e32 v18, v18
	v_exp_f32_e32 v19, v19
	v_exp_f32_e32 v20, v20
	v_exp_f32_e32 v21, v21
	v_exp_f32_e32 v22, v22
	v_exp_f32_e32 v23, v23
	v_lshlrev_b32_e32 v24, 16, v116
	v_and_b32_e32 v25, 0xffff0000, v116
	v_lshlrev_b32_e32 v26, 16, v117
	v_and_b32_e32 v27, 0xffff0000, v117
	v_lshlrev_b32_e32 v28, 16, v118
	v_and_b32_e32 v29, 0xffff0000, v118
	v_lshlrev_b32_e32 v30, 16, v119
	v_and_b32_e32 v31, 0xffff0000, v119
	v_add_f32_e32 v16, 1.0, v16
	v_add_f32_e32 v17, 1.0, v17
	v_add_f32_e32 v18, 1.0, v18
	v_add_f32_e32 v19, 1.0, v19
	v_add_f32_e32 v20, 1.0, v20
	v_add_f32_e32 v21, 1.0, v21
	v_add_f32_e32 v22, 1.0, v22
	v_add_f32_e32 v23, 1.0, v23
	v_rcp_f32_e32 v16, v16
	v_rcp_f32_e32 v17, v17
	v_rcp_f32_e32 v18, v18
	v_rcp_f32_e32 v19, v19
	v_rcp_f32_e32 v20, v20
	v_rcp_f32_e32 v21, v21
	v_rcp_f32_e32 v22, v22
	v_rcp_f32_e32 v23, v23
	v_lshlrev_b32_e32 v116, 16, v120
	v_and_b32_e32 v120, 0xffff0000, v120
	v_lshlrev_b32_e32 v117, 16, v121
	v_and_b32_e32 v121, 0xffff0000, v121
	v_lshlrev_b32_e32 v118, 16, v122
	v_and_b32_e32 v122, 0xffff0000, v122
	v_lshlrev_b32_e32 v119, 16, v123
	v_and_b32_e32 v123, 0xffff0000, v123
	v_add_f32_e32 v24, v116, v24
	v_add_f32_e32 v25, v120, v25
	v_add_f32_e32 v26, v117, v26
	v_add_f32_e32 v27, v121, v27
	v_add_f32_e32 v28, v118, v28
	v_add_f32_e32 v29, v122, v29
	v_add_f32_e32 v30, v119, v30
	v_add_f32_e32 v31, v123, v31
	v_fma_f32 v16, v16, -2.0, 1.0
	v_fma_f32 v17, v17, -2.0, 1.0
	v_fma_f32 v18, v18, -2.0, 1.0
	v_fma_f32 v19, v19, -2.0, 1.0
	v_fma_f32 v20, v20, -2.0, 1.0
	v_fma_f32 v21, v21, -2.0, 1.0
	v_fma_f32 v22, v22, -2.0, 1.0
	v_fma_f32 v23, v23, -2.0, 1.0
	v_mul_f32_e32 v8, 0.5, v8
	v_mul_f32_e32 v9, 0.5, v9
	v_mul_f32_e32 v10, 0.5, v10
	v_mul_f32_e32 v11, 0.5, v11
	v_mul_f32_e32 v12, 0.5, v12
	v_mul_f32_e32 v13, 0.5, v13
	v_mul_f32_e32 v14, 0.5, v14
	v_mul_f32_e32 v15, 0.5, v15
	v_add_f32_e32 v16, 1.0, v16
	v_add_f32_e32 v17, 1.0, v17
	v_add_f32_e32 v18, 1.0, v18
	v_add_f32_e32 v19, 1.0, v19
	v_add_f32_e32 v20, 1.0, v20
	v_add_f32_e32 v21, 1.0, v21
	v_add_f32_e32 v22, 1.0, v22
	v_add_f32_e32 v23, 1.0, v23
	v_mul_f32_e32 v8, v8, v16
	v_mul_f32_e32 v9, v9, v17
	v_mul_f32_e32 v10, v10, v18
	v_mul_f32_e32 v11, v11, v19
	v_mul_f32_e32 v12, v12, v20
	v_mul_f32_e32 v13, v13, v21
	v_mul_f32_e32 v14, v14, v22
	v_mul_f32_e32 v15, v15, v23
	v_mul_f32_e32 v24, v24, v8
	v_mul_f32_e32 v25, v25, v9
	v_mul_f32_e32 v26, v26, v10
	v_mul_f32_e32 v27, v27, v11
	v_mul_f32_e32 v28, v28, v12
	v_mul_f32_e32 v29, v29, v13
	v_mul_f32_e32 v30, v30, v14
	v_mul_f32_e32 v31, v31, v15
	v_mul_f32_e32 v120, v25, v25
	v_cvt_pk_bf16_f32 v116, v24, v25
	v_fmac_f32_e32 v120, v24, v24
	v_cvt_pk_bf16_f32 v117, v26, v27
	v_fmac_f32_e32 v120, v26, v26
	v_cvt_pk_bf16_f32 v118, v28, v29
	v_fmac_f32_e32 v120, v27, v27
	v_cvt_pk_bf16_f32 v119, v30, v31
	v_fmac_f32_e32 v120, v28, v28
	v_fmac_f32_e32 v120, v29, v29
	v_fmac_f32_e32 v120, v30, v30
	v_fmac_f32_e32 v120, v31, v31
	s_waitcnt vmcnt(21)
; __device__ __forceinline__ float bflo(unsigned w) { return __uint_as_float(w << 16); }
; __device__ __forceinline__ float bfhi(unsigned w) { return __uint_as_float(w & 0xffff0000u); }
; __device__ __forceinline__ void rnn_combine(const Params& p) {
;     ...
;             for (int i = 0; i < 4; ++i) { const unsigned a = hf[k][i], c = hb[k][i], gg = gw[k][i];
; #pragma unroll
;                 for (int e = 0; e < 2; ++e) { const float hs = (e ? bfhi(a) : bflo(a)) + (e ? bfhi(c) : bflo(c)); const float gt = e ? bfhi(gg) : bflo(gg);
;                     const float u = 0.7978845608028654f * (gt + 0.044715f * gt * gt * gt); const float th = 1.0f - 2.0f * __builtin_amdgcn_rcpf(1.0f + __builtin_amdgcn_exp2f(2.8853900817779268f * u));
;                     const float yv = hs * (0.5f * gt * (1.0f + th)); y[2 * i + e] = yv; q += yv * yv; } }
	v_lshlrev_b32_e32 v8, 16, v136
	v_and_b32_e32 v9, 0xffff0000, v136
	v_lshlrev_b32_e32 v10, 16, v137
	v_and_b32_e32 v11, 0xffff0000, v137
	v_lshlrev_b32_e32 v12, 16, v138
	v_and_b32_e32 v13, 0xffff0000, v138
	v_lshlrev_b32_e32 v14, 16, v139
	v_and_b32_e32 v15, 0xffff0000, v139
	v_mul_f32_e32 v16, 0x3d372713, v8
	v_mul_f32_e32 v17, 0x3d372713, v9
	v_mul_f32_e32 v18, 0x3d372713, v10
	v_mul_f32_e32 v19, 0x3d372713, v11
	v_mul_f32_e32 v20, 0x3d372713, v12
	v_mul_f32_e32 v21, 0x3d372713, v13
	v_mul_f32_e32 v22, 0x3d372713, v14
	v_mul_f32_e32 v23, 0x3d372713, v15
	v_mul_f32_e32 v16, v16, v8
	v_mul_f32_e32 v17, v17, v9
	v_mul_f32_e32 v18, v18, v10
	v_mul_f32_e32 v19, v19, v11
	v_mul_f32_e32 v20, v20, v12
	v_mul_f32_e32 v21, v21, v13
	v_mul_f32_e32 v22, v22, v14
	v_mul_f32_e32 v23, v23, v15
	v_fma_f32 v16, v16, v8, v8
	v_fma_f32 v17, v17, v9, v9
	v_fma_f32 v18, v18, v10, v10
	v_fma_f32 v19, v19, v11, v11
	v_fma_f32 v20, v20, v12, v12
	v_fma_f32 v21, v21, v13, v13
	v_fma_f32 v22, v22, v14, v14
	v_fma_f32 v23, v23, v15, v15
	v_mul_f32_e32 v16, 0x3f4c422a, v16
	v_mul_f32_e32 v17, 0x3f4c422a, v17
	v_mul_f32_e32 v18, 0x3f4c422a, v18
	v_mul_f32_e32 v19, 0x3f4c422a, v19
	v_mul_f32_e32 v20, 0x3f4c422a, v20
	v_mul_f32_e32 v21, 0x3f4c422a, v21
	v_mul_f32_e32 v22, 0x3f4c422a, v22
	v_mul_f32_e32 v23, 0x3f4c422a, v23
	v_mul_f32_e32 v16, 0x4038aa3b, v16
	v_mul_f32_e32 v17, 0x4038aa3b, v17
	v_mul_f32_e32 v18, 0x4038aa3b, v18
	v_mul_f32_e32 v19, 0x4038aa3b, v19
	v_mul_f32_e32 v20, 0x4038aa3b, v20
	v_mul_f32_e32 v21, 0x4038aa3b, v21
	v_mul_f32_e32 v22, 0x4038aa3b, v22
	v_mul_f32_e32 v23, 0x4038aa3b, v23
	v_exp_f32_e32 v16, v16
	v_exp_f32_e32 v17, v17
	v_exp_f32_e32 v18, v18
	v_exp_f32_e32 v19, v19
	v_exp_f32_e32 v20, v20
	v_exp_f32_e32 v21, v21
	v_exp_f32_e32 v22, v22
	v_exp_f32_e32 v23, v23
	v_lshlrev_b32_e32 v24, 16, v128
	v_and_b32_e32 v25, 0xffff0000, v128
	v_lshlrev_b32_e32 v26, 16, v129
	v_and_b32_e32 v27, 0xffff0000, v129
	v_lshlrev_b32_e32 v28, 16, v130
	v_and_b32_e32 v29, 0xffff0000, v130
	v_lshlrev_b32_e32 v30, 16, v131
	v_and_b32_e32 v31, 0xffff0000, v131
	v_add_f32_e32 v16, 1.0, v16
	v_add_f32_e32 v17, 1.0, v17
	v_add_f32_e32 v18, 1.0, v18
	v_add_f32_e32 v19, 1.0, v19
	v_add_f32_e32 v20, 1.0, v20
	v_add_f32_e32 v21, 1.0, v21
	v_add_f32_e32 v22, 1.0, v22
	v_add_f32_e32 v23, 1.0, v23
	v_rcp_f32_e32 v16, v16
	v_rcp_f32_e32 v17, v17
	v_rcp_f32_e32 v18, v18
	v_rcp_f32_e32 v19, v19
	v_rcp_f32_e32 v20, v20
	v_rcp_f32_e32 v21, v21
	v_rcp_f32_e32 v22, v22
	v_rcp_f32_e32 v23, v23
	v_lshlrev_b32_e32 v128, 16, v132
	v_and_b32_e32 v132, 0xffff0000, v132
	v_lshlrev_b32_e32 v129, 16, v133
	v_and_b32_e32 v133, 0xffff0000, v133
	v_lshlrev_b32_e32 v130, 16, v134
	v_and_b32_e32 v134, 0xffff0000, v134
	v_lshlrev_b32_e32 v131, 16, v135
	v_and_b32_e32 v135, 0xffff0000, v135
	v_add_f32_e32 v24, v128, v24
	v_add_f32_e32 v25, v132, v25
	v_add_f32_e32 v26, v129, v26
	v_add_f32_e32 v27, v133, v27
	v_add_f32_e32 v28, v130, v28
	v_add_f32_e32 v29, v134, v29
	v_add_f32_e32 v30, v131, v30
	v_add_f32_e32 v31, v135, v31
	v_fma_f32 v16, v16, -2.0, 1.0
	v_fma_f32 v17, v17, -2.0, 1.0
	v_fma_f32 v18, v18, -2.0, 1.0
	v_fma_f32 v19, v19, -2.0, 1.0
	v_fma_f32 v20, v20, -2.0, 1.0
	v_fma_f32 v21, v21, -2.0, 1.0
	v_fma_f32 v22, v22, -2.0, 1.0
	v_fma_f32 v23, v23, -2.0, 1.0
	v_mul_f32_e32 v8, 0.5, v8
	v_mul_f32_e32 v9, 0.5, v9
	v_mul_f32_e32 v10, 0.5, v10
	v_mul_f32_e32 v11, 0.5, v11
	v_mul_f32_e32 v12, 0.5, v12
	v_mul_f32_e32 v13, 0.5, v13
	v_mul_f32_e32 v14, 0.5, v14
	v_mul_f32_e32 v15, 0.5, v15
	v_add_f32_e32 v16, 1.0, v16
	v_add_f32_e32 v17, 1.0, v17
	v_add_f32_e32 v18, 1.0, v18
	v_add_f32_e32 v19, 1.0, v19
	v_add_f32_e32 v20, 1.0, v20
	v_add_f32_e32 v21, 1.0, v21
	v_add_f32_e32 v22, 1.0, v22
	v_add_f32_e32 v23, 1.0, v23
	v_mul_f32_e32 v8, v8, v16
	v_mul_f32_e32 v9, v9, v17
	v_mul_f32_e32 v10, v10, v18
	v_mul_f32_e32 v11, v11, v19
	v_mul_f32_e32 v12, v12, v20
	v_mul_f32_e32 v13, v13, v21
	v_mul_f32_e32 v14, v14, v22
	v_mul_f32_e32 v15, v15, v23
	v_mul_f32_e32 v24, v24, v8
	v_mul_f32_e32 v25, v25, v9
	v_mul_f32_e32 v26, v26, v10
	v_mul_f32_e32 v27, v27, v11
	v_mul_f32_e32 v28, v28, v12
	v_mul_f32_e32 v29, v29, v13
	v_mul_f32_e32 v30, v30, v14
	v_mul_f32_e32 v31, v31, v15
	v_mul_f32_e32 v132, v25, v25
	v_cvt_pk_bf16_f32 v128, v24, v25
	v_fmac_f32_e32 v132, v24, v24
	v_cvt_pk_bf16_f32 v129, v26, v27
	v_fmac_f32_e32 v132, v26, v26
	v_cvt_pk_bf16_f32 v130, v28, v29
	v_fmac_f32_e32 v132, v27, v27
	v_cvt_pk_bf16_f32 v131, v30, v31
	v_fmac_f32_e32 v132, v28, v28
	v_fmac_f32_e32 v132, v29, v29
	v_fmac_f32_e32 v132, v30, v30
	v_fmac_f32_e32 v132, v31, v31
	s_waitcnt vmcnt(18)
; __device__ __forceinline__ float bflo(unsigned w) { return __uint_as_float(w << 16); }
; __device__ __forceinline__ float bfhi(unsigned w) { return __uint_as_float(w & 0xffff0000u); }
; __device__ __forceinline__ void rnn_combine(const Params& p) {
;     ...
;             for (int i = 0; i < 4; ++i) { const unsigned a = hf[k][i], c = hb[k][i], gg = gw[k][i];
; #pragma unroll
;                 for (int e = 0; e < 2; ++e) { const float hs = (e ? bfhi(a) : bflo(a)) + (e ? bfhi(c) : bflo(c)); const float gt = e ? bfhi(gg) : bflo(gg);
;                     const float u = 0.7978845608028654f * (gt + 0.044715f * gt * gt * gt); const float th = 1.0f - 2.0f * __builtin_amdgcn_rcpf(1.0f + __builtin_amdgcn_exp2f(2.8853900817779268f * u));
;                     const float yv = hs * (0.5f * gt * (1.0f + th)); y[2 * i + e] = yv; q += yv * yv; } }
	v_lshlrev_b32_e32 v8, 16, v148
	v_and_b32_e32 v9, 0xffff0000, v148
	v_lshlrev_b32_e32 v10, 16, v149
	v_and_b32_e32 v11, 0xffff0000, v149
	v_lshlrev_b32_e32 v12, 16, v150
	v_and_b32_e32 v13, 0xffff0000, v150
	v_lshlrev_b32_e32 v14, 16, v151
	v_and_b32_e32 v15, 0xffff0000, v151
	v_mul_f32_e32 v16, 0x3d372713, v8
	v_mul_f32_e32 v17, 0x3d372713, v9
	v_mul_f32_e32 v18, 0x3d372713, v10
	v_mul_f32_e32 v19, 0x3d372713, v11
	v_mul_f32_e32 v20, 0x3d372713, v12
	v_mul_f32_e32 v21, 0x3d372713, v13
	v_mul_f32_e32 v22, 0x3d372713, v14
	v_mul_f32_e32 v23, 0x3d372713, v15
	v_mul_f32_e32 v16, v16, v8
	v_mul_f32_e32 v17, v17, v9
	v_mul_f32_e32 v18, v18, v10
	v_mul_f32_e32 v19, v19, v11
	v_mul_f32_e32 v20, v20, v12
	v_mul_f32_e32 v21, v21, v13
	v_mul_f32_e32 v22, v22, v14
	v_mul_f32_e32 v23, v23, v15
	v_fma_f32 v16, v16, v8, v8
	v_fma_f32 v17, v17, v9, v9
	v_fma_f32 v18, v18, v10, v10
	v_fma_f32 v19, v19, v11, v11
	v_fma_f32 v20, v20, v12, v12
	v_fma_f32 v21, v21, v13, v13
	v_fma_f32 v22, v22, v14, v14
	v_fma_f32 v23, v23, v15, v15
	v_mul_f32_e32 v16, 0x3f4c422a, v16
	v_mul_f32_e32 v17, 0x3f4c422a, v17
	v_mul_f32_e32 v18, 0x3f4c422a, v18
	v_mul_f32_e32 v19, 0x3f4c422a, v19
	v_mul_f32_e32 v20, 0x3f4c422a, v20
	v_mul_f32_e32 v21, 0x3f4c422a, v21
	v_mul_f32_e32 v22, 0x3f4c422a, v22
	v_mul_f32_e32 v23, 0x3f4c422a, v23
	v_mul_f32_e32 v16, 0x4038aa3b, v16
	v_mul_f32_e32 v17, 0x4038aa3b, v17
	v_mul_f32_e32 v18, 0x4038aa3b, v18
	v_mul_f32_e32 v19, 0x4038aa3b, v19
	v_mul_f32_e32 v20, 0x4038aa3b, v20
	v_mul_f32_e32 v21, 0x4038aa3b, v21
	v_mul_f32_e32 v22, 0x4038aa3b, v22
	v_mul_f32_e32 v23, 0x4038aa3b, v23
	v_exp_f32_e32 v16, v16
	v_exp_f32_e32 v17, v17
	v_exp_f32_e32 v18, v18
	v_exp_f32_e32 v19, v19
	v_exp_f32_e32 v20, v20
	v_exp_f32_e32 v21, v21
	v_exp_f32_e32 v22, v22
	v_exp_f32_e32 v23, v23
	v_lshlrev_b32_e32 v24, 16, v140
	v_and_b32_e32 v25, 0xffff0000, v140
	v_lshlrev_b32_e32 v26, 16, v141
	v_and_b32_e32 v27, 0xffff0000, v141
	v_lshlrev_b32_e32 v28, 16, v142
	v_and_b32_e32 v29, 0xffff0000, v142
	v_lshlrev_b32_e32 v30, 16, v143
	v_and_b32_e32 v31, 0xffff0000, v143
	v_add_f32_e32 v16, 1.0, v16
	v_add_f32_e32 v17, 1.0, v17
	v_add_f32_e32 v18, 1.0, v18
	v_add_f32_e32 v19, 1.0, v19
	v_add_f32_e32 v20, 1.0, v20
	v_add_f32_e32 v21, 1.0, v21
	v_add_f32_e32 v22, 1.0, v22
	v_add_f32_e32 v23, 1.0, v23
	v_rcp_f32_e32 v16, v16
	v_rcp_f32_e32 v17, v17
	v_rcp_f32_e32 v18, v18
	v_rcp_f32_e32 v19, v19
	v_rcp_f32_e32 v20, v20
	v_rcp_f32_e32 v21, v21
	v_rcp_f32_e32 v22, v22
	v_rcp_f32_e32 v23, v23
	v_lshlrev_b32_e32 v140, 16, v144
	v_and_b32_e32 v144, 0xffff0000, v144
	v_lshlrev_b32_e32 v141, 16, v145
	v_and_b32_e32 v145, 0xffff0000, v145
	v_lshlrev_b32_e32 v142, 16, v146
	v_and_b32_e32 v146, 0xffff0000, v146
	v_lshlrev_b32_e32 v143, 16, v147
	v_and_b32_e32 v147, 0xffff0000, v147
	v_add_f32_e32 v24, v140, v24
	v_add_f32_e32 v25, v144, v25
	v_add_f32_e32 v26, v141, v26
	v_add_f32_e32 v27, v145, v27
	v_add_f32_e32 v28, v142, v28
	v_add_f32_e32 v29, v146, v29
	v_add_f32_e32 v30, v143, v30
	v_add_f32_e32 v31, v147, v31
	v_fma_f32 v16, v16, -2.0, 1.0
	v_fma_f32 v17, v17, -2.0, 1.0
	v_fma_f32 v18, v18, -2.0, 1.0
	v_fma_f32 v19, v19, -2.0, 1.0
	v_fma_f32 v20, v20, -2.0, 1.0
	v_fma_f32 v21, v21, -2.0, 1.0
	v_fma_f32 v22, v22, -2.0, 1.0
	v_fma_f32 v23, v23, -2.0, 1.0
	v_mul_f32_e32 v8, 0.5, v8
	v_mul_f32_e32 v9, 0.5, v9
	v_mul_f32_e32 v10, 0.5, v10
	v_mul_f32_e32 v11, 0.5, v11
	v_mul_f32_e32 v12, 0.5, v12
	v_mul_f32_e32 v13, 0.5, v13
	v_mul_f32_e32 v14, 0.5, v14
	v_mul_f32_e32 v15, 0.5, v15
	v_add_f32_e32 v16, 1.0, v16
	v_add_f32_e32 v17, 1.0, v17
	v_add_f32_e32 v18, 1.0, v18
	v_add_f32_e32 v19, 1.0, v19
	v_add_f32_e32 v20, 1.0, v20
	v_add_f32_e32 v21, 1.0, v21
	v_add_f32_e32 v22, 1.0, v22
	v_add_f32_e32 v23, 1.0, v23
	v_mul_f32_e32 v8, v8, v16
	v_mul_f32_e32 v9, v9, v17
	v_mul_f32_e32 v10, v10, v18
	v_mul_f32_e32 v11, v11, v19
	v_mul_f32_e32 v12, v12, v20
	v_mul_f32_e32 v13, v13, v21
	v_mul_f32_e32 v14, v14, v22
	v_mul_f32_e32 v15, v15, v23
	v_mul_f32_e32 v24, v24, v8
	v_mul_f32_e32 v25, v25, v9
	v_mul_f32_e32 v26, v26, v10
	v_mul_f32_e32 v27, v27, v11
	v_mul_f32_e32 v28, v28, v12
	v_mul_f32_e32 v29, v29, v13
	v_mul_f32_e32 v30, v30, v14
	v_mul_f32_e32 v31, v31, v15
	v_mul_f32_e32 v144, v25, v25
	v_cvt_pk_bf16_f32 v140, v24, v25
	v_fmac_f32_e32 v144, v24, v24
	v_cvt_pk_bf16_f32 v141, v26, v27
	v_fmac_f32_e32 v144, v26, v26
	v_cvt_pk_bf16_f32 v142, v28, v29
	v_fmac_f32_e32 v144, v27, v27
	v_cvt_pk_bf16_f32 v143, v30, v31
	v_fmac_f32_e32 v144, v28, v28
	v_fmac_f32_e32 v144, v29, v29
	v_fmac_f32_e32 v144, v30, v30
	v_fmac_f32_e32 v144, v31, v31
	s_waitcnt vmcnt(15)
; __device__ __forceinline__ float bflo(unsigned w) { return __uint_as_float(w << 16); }
; __device__ __forceinline__ float bfhi(unsigned w) { return __uint_as_float(w & 0xffff0000u); }
; __device__ __forceinline__ void rnn_combine(const Params& p) {
;     ...
;             for (int i = 0; i < 4; ++i) { const unsigned a = hf[k][i], c = hb[k][i], gg = gw[k][i];
; #pragma unroll
;                 for (int e = 0; e < 2; ++e) { const float hs = (e ? bfhi(a) : bflo(a)) + (e ? bfhi(c) : bflo(c)); const float gt = e ? bfhi(gg) : bflo(gg);
;                     const float u = 0.7978845608028654f * (gt + 0.044715f * gt * gt * gt); const float th = 1.0f - 2.0f * __builtin_amdgcn_rcpf(1.0f + __builtin_amdgcn_exp2f(2.8853900817779268f * u));
;                     const float yv = hs * (0.5f * gt * (1.0f + th)); y[2 * i + e] = yv; q += yv * yv; } }
	v_lshlrev_b32_e32 v8, 16, v172
	v_and_b32_e32 v9, 0xffff0000, v172
	v_lshlrev_b32_e32 v10, 16, v173
	v_and_b32_e32 v11, 0xffff0000, v173
	v_lshlrev_b32_e32 v12, 16, v174
	v_and_b32_e32 v13, 0xffff0000, v174
	v_lshlrev_b32_e32 v14, 16, v175
	v_and_b32_e32 v15, 0xffff0000, v175
	v_mul_f32_e32 v16, 0x3d372713, v8
	v_mul_f32_e32 v17, 0x3d372713, v9
	v_mul_f32_e32 v18, 0x3d372713, v10
	v_mul_f32_e32 v19, 0x3d372713, v11
	v_mul_f32_e32 v20, 0x3d372713, v12
	v_mul_f32_e32 v21, 0x3d372713, v13
	v_mul_f32_e32 v22, 0x3d372713, v14
	v_mul_f32_e32 v23, 0x3d372713, v15
	v_mul_f32_e32 v16, v16, v8
	v_mul_f32_e32 v17, v17, v9
	v_mul_f32_e32 v18, v18, v10
	v_mul_f32_e32 v19, v19, v11
	v_mul_f32_e32 v20, v20, v12
	v_mul_f32_e32 v21, v21, v13
	v_mul_f32_e32 v22, v22, v14
	v_mul_f32_e32 v23, v23, v15
	v_fma_f32 v16, v16, v8, v8
	v_fma_f32 v17, v17, v9, v9
	v_fma_f32 v18, v18, v10, v10
	v_fma_f32 v19, v19, v11, v11
	v_fma_f32 v20, v20, v12, v12
	v_fma_f32 v21, v21, v13, v13
	v_fma_f32 v22, v22, v14, v14
	v_fma_f32 v23, v23, v15, v15
	v_mul_f32_e32 v16, 0x3f4c422a, v16
	v_mul_f32_e32 v17, 0x3f4c422a, v17
	v_mul_f32_e32 v18, 0x3f4c422a, v18
	v_mul_f32_e32 v19, 0x3f4c422a, v19
	v_mul_f32_e32 v20, 0x3f4c422a, v20
	v_mul_f32_e32 v21, 0x3f4c422a, v21
	v_mul_f32_e32 v22, 0x3f4c422a, v22
	v_mul_f32_e32 v23, 0x3f4c422a, v23
	v_mul_f32_e32 v16, 0x4038aa3b, v16
	v_mul_f32_e32 v17, 0x4038aa3b, v17
	v_mul_f32_e32 v18, 0x4038aa3b, v18
	v_mul_f32_e32 v19, 0x4038aa3b, v19
	v_mul_f32_e32 v20, 0x4038aa3b, v20
	v_mul_f32_e32 v21, 0x4038aa3b, v21
	v_mul_f32_e32 v22, 0x4038aa3b, v22
	v_mul_f32_e32 v23, 0x4038aa3b, v23
	v_exp_f32_e32 v16, v16
	v_exp_f32_e32 v17, v17
	v_exp_f32_e32 v18, v18
	v_exp_f32_e32 v19, v19
	v_exp_f32_e32 v20, v20
	v_exp_f32_e32 v21, v21
	v_exp_f32_e32 v22, v22
	v_exp_f32_e32 v23, v23
	v_lshlrev_b32_e32 v24, 16, v164
	v_and_b32_e32 v25, 0xffff0000, v164
	v_lshlrev_b32_e32 v26, 16, v165
	v_and_b32_e32 v27, 0xffff0000, v165
	v_lshlrev_b32_e32 v28, 16, v166
	v_and_b32_e32 v29, 0xffff0000, v166
	v_lshlrev_b32_e32 v30, 16, v167
	v_and_b32_e32 v31, 0xffff0000, v167
	v_add_f32_e32 v16, 1.0, v16
	v_add_f32_e32 v17, 1.0, v17
	v_add_f32_e32 v18, 1.0, v18
	v_add_f32_e32 v19, 1.0, v19
	v_add_f32_e32 v20, 1.0, v20
	v_add_f32_e32 v21, 1.0, v21
	v_add_f32_e32 v22, 1.0, v22
	v_add_f32_e32 v23, 1.0, v23
	v_rcp_f32_e32 v16, v16
	v_rcp_f32_e32 v17, v17
	v_rcp_f32_e32 v18, v18
	v_rcp_f32_e32 v19, v19
	v_rcp_f32_e32 v20, v20
	v_rcp_f32_e32 v21, v21
	v_rcp_f32_e32 v22, v22
	v_rcp_f32_e32 v23, v23
	v_lshlrev_b32_e32 v164, 16, v168
	v_and_b32_e32 v168, 0xffff0000, v168
	v_lshlrev_b32_e32 v165, 16, v169
	v_and_b32_e32 v169, 0xffff0000, v169
	v_lshlrev_b32_e32 v166, 16, v170
	v_and_b32_e32 v170, 0xffff0000, v170
	v_lshlrev_b32_e32 v167, 16, v171
	v_and_b32_e32 v171, 0xffff0000, v171
	v_add_f32_e32 v24, v164, v24
	v_add_f32_e32 v25, v168, v25
	v_add_f32_e32 v26, v165, v26
	v_add_f32_e32 v27, v169, v27
	v_add_f32_e32 v28, v166, v28
	v_add_f32_e32 v29, v170, v29
	v_add_f32_e32 v30, v167, v30
	v_add_f32_e32 v31, v171, v31
	v_fma_f32 v16, v16, -2.0, 1.0
	v_fma_f32 v17, v17, -2.0, 1.0
	v_fma_f32 v18, v18, -2.0, 1.0
	v_fma_f32 v19, v19, -2.0, 1.0
	v_fma_f32 v20, v20, -2.0, 1.0
	v_fma_f32 v21, v21, -2.0, 1.0
	v_fma_f32 v22, v22, -2.0, 1.0
	v_fma_f32 v23, v23, -2.0, 1.0
	v_mul_f32_e32 v8, 0.5, v8
	v_mul_f32_e32 v9, 0.5, v9
	v_mul_f32_e32 v10, 0.5, v10
	v_mul_f32_e32 v11, 0.5, v11
	v_mul_f32_e32 v12, 0.5, v12
	v_mul_f32_e32 v13, 0.5, v13
	v_mul_f32_e32 v14, 0.5, v14
	v_mul_f32_e32 v15, 0.5, v15
	v_add_f32_e32 v16, 1.0, v16
	v_add_f32_e32 v17, 1.0, v17
	v_add_f32_e32 v18, 1.0, v18
	v_add_f32_e32 v19, 1.0, v19
	v_add_f32_e32 v20, 1.0, v20
	v_add_f32_e32 v21, 1.0, v21
	v_add_f32_e32 v22, 1.0, v22
	v_add_f32_e32 v23, 1.0, v23
	v_mul_f32_e32 v8, v8, v16
	v_mul_f32_e32 v9, v9, v17
	v_mul_f32_e32 v10, v10, v18
	v_mul_f32_e32 v11, v11, v19
	v_mul_f32_e32 v12, v12, v20
	v_mul_f32_e32 v13, v13, v21
	v_mul_f32_e32 v14, v14, v22
	v_mul_f32_e32 v15, v15, v23
	v_mul_f32_e32 v24, v24, v8
	v_mul_f32_e32 v25, v25, v9
	v_mul_f32_e32 v26, v26, v10
	v_mul_f32_e32 v27, v27, v11
	v_mul_f32_e32 v28, v28, v12
	v_mul_f32_e32 v29, v29, v13
	v_mul_f32_e32 v30, v30, v14
	v_mul_f32_e32 v31, v31, v15
	v_mul_f32_e32 v168, v25, v25
	v_cvt_pk_bf16_f32 v164, v24, v25
	v_fmac_f32_e32 v168, v24, v24
	v_cvt_pk_bf16_f32 v165, v26, v27
	v_fmac_f32_e32 v168, v26, v26
	v_cvt_pk_bf16_f32 v166, v28, v29
	v_fmac_f32_e32 v168, v27, v27
	v_cvt_pk_bf16_f32 v167, v30, v31
	v_fmac_f32_e32 v168, v28, v28
	v_fmac_f32_e32 v168, v29, v29
	v_fmac_f32_e32 v168, v30, v30
	v_fmac_f32_e32 v168, v31, v31
	s_waitcnt vmcnt(12)
; __device__ __forceinline__ float bflo(unsigned w) { return __uint_as_float(w << 16); }
; __device__ __forceinline__ float bfhi(unsigned w) { return __uint_as_float(w & 0xffff0000u); }
; __device__ __forceinline__ void rnn_combine(const Params& p) {
;     ...
;             for (int i = 0; i < 4; ++i) { const unsigned a = hf[k][i], c = hb[k][i], gg = gw[k][i];
; #pragma unroll
;                 for (int e = 0; e < 2; ++e) { const float hs = (e ? bfhi(a) : bflo(a)) + (e ? bfhi(c) : bflo(c)); const float gt = e ? bfhi(gg) : bflo(gg);
;                     const float u = 0.7978845608028654f * (gt + 0.044715f * gt * gt * gt); const float th = 1.0f - 2.0f * __builtin_amdgcn_rcpf(1.0f + __builtin_amdgcn_exp2f(2.8853900817779268f * u));
;                     const float yv = hs * (0.5f * gt * (1.0f + th)); y[2 * i + e] = yv; q += yv * yv; } }
	v_lshlrev_b32_e32 v8, 16, v184
	v_and_b32_e32 v9, 0xffff0000, v184
	v_lshlrev_b32_e32 v10, 16, v185
	v_and_b32_e32 v11, 0xffff0000, v185
	v_lshlrev_b32_e32 v12, 16, v186
	v_and_b32_e32 v13, 0xffff0000, v186
	v_lshlrev_b32_e32 v14, 16, v187
	v_and_b32_e32 v15, 0xffff0000, v187
	v_mul_f32_e32 v16, 0x3d372713, v8
	v_mul_f32_e32 v17, 0x3d372713, v9
	v_mul_f32_e32 v18, 0x3d372713, v10
	v_mul_f32_e32 v19, 0x3d372713, v11
	v_mul_f32_e32 v20, 0x3d372713, v12
	v_mul_f32_e32 v21, 0x3d372713, v13
	v_mul_f32_e32 v22, 0x3d372713, v14
	v_mul_f32_e32 v23, 0x3d372713, v15
	v_mul_f32_e32 v16, v16, v8
	v_mul_f32_e32 v17, v17, v9
	v_mul_f32_e32 v18, v18, v10
	v_mul_f32_e32 v19, v19, v11
	v_mul_f32_e32 v20, v20, v12
	v_mul_f32_e32 v21, v21, v13
	v_mul_f32_e32 v22, v22, v14
	v_mul_f32_e32 v23, v23, v15
	v_fma_f32 v16, v16, v8, v8
	v_fma_f32 v17, v17, v9, v9
	v_fma_f32 v18, v18, v10, v10
	v_fma_f32 v19, v19, v11, v11
	v_fma_f32 v20, v20, v12, v12
	v_fma_f32 v21, v21, v13, v13
	v_fma_f32 v22, v22, v14, v14
	v_fma_f32 v23, v23, v15, v15
	v_mul_f32_e32 v16, 0x3f4c422a, v16
	v_mul_f32_e32 v17, 0x3f4c422a, v17
	v_mul_f32_e32 v18, 0x3f4c422a, v18
	v_mul_f32_e32 v19, 0x3f4c422a, v19
	v_mul_f32_e32 v20, 0x3f4c422a, v20
	v_mul_f32_e32 v21, 0x3f4c422a, v21
	v_mul_f32_e32 v22, 0x3f4c422a, v22
	v_mul_f32_e32 v23, 0x3f4c422a, v23
	v_mul_f32_e32 v16, 0x4038aa3b, v16
	v_mul_f32_e32 v17, 0x4038aa3b, v17
	v_mul_f32_e32 v18, 0x4038aa3b, v18
	v_mul_f32_e32 v19, 0x4038aa3b, v19
	v_mul_f32_e32 v20, 0x4038aa3b, v20
	v_mul_f32_e32 v21, 0x4038aa3b, v21
	v_mul_f32_e32 v22, 0x4038aa3b, v22
	v_mul_f32_e32 v23, 0x4038aa3b, v23
	v_exp_f32_e32 v16, v16
	v_exp_f32_e32 v17, v17
	v_exp_f32_e32 v18, v18
	v_exp_f32_e32 v19, v19
	v_exp_f32_e32 v20, v20
	v_exp_f32_e32 v21, v21
	v_exp_f32_e32 v22, v22
	v_exp_f32_e32 v23, v23
	v_lshlrev_b32_e32 v24, 16, v176
	v_and_b32_e32 v25, 0xffff0000, v176
	v_lshlrev_b32_e32 v26, 16, v177
	v_and_b32_e32 v27, 0xffff0000, v177
	v_lshlrev_b32_e32 v28, 16, v178
	v_and_b32_e32 v29, 0xffff0000, v178
	v_lshlrev_b32_e32 v30, 16, v179
	v_and_b32_e32 v31, 0xffff0000, v179
	v_add_f32_e32 v16, 1.0, v16
	v_add_f32_e32 v17, 1.0, v17
	v_add_f32_e32 v18, 1.0, v18
	v_add_f32_e32 v19, 1.0, v19
	v_add_f32_e32 v20, 1.0, v20
	v_add_f32_e32 v21, 1.0, v21
	v_add_f32_e32 v22, 1.0, v22
	v_add_f32_e32 v23, 1.0, v23
	v_rcp_f32_e32 v16, v16
	v_rcp_f32_e32 v17, v17
	v_rcp_f32_e32 v18, v18
	v_rcp_f32_e32 v19, v19
	v_rcp_f32_e32 v20, v20
	v_rcp_f32_e32 v21, v21
	v_rcp_f32_e32 v22, v22
	v_rcp_f32_e32 v23, v23
	v_lshlrev_b32_e32 v176, 16, v180
	v_and_b32_e32 v180, 0xffff0000, v180
	v_lshlrev_b32_e32 v177, 16, v181
	v_and_b32_e32 v181, 0xffff0000, v181
	v_lshlrev_b32_e32 v178, 16, v182
	v_and_b32_e32 v182, 0xffff0000, v182
	v_lshlrev_b32_e32 v179, 16, v183
	v_and_b32_e32 v183, 0xffff0000, v183
	v_add_f32_e32 v24, v176, v24
	v_add_f32_e32 v25, v180, v25
	v_add_f32_e32 v26, v177, v26
	v_add_f32_e32 v27, v181, v27
	v_add_f32_e32 v28, v178, v28
	v_add_f32_e32 v29, v182, v29
	v_add_f32_e32 v30, v179, v30
	v_add_f32_e32 v31, v183, v31
	v_fma_f32 v16, v16, -2.0, 1.0
	v_fma_f32 v17, v17, -2.0, 1.0
	v_fma_f32 v18, v18, -2.0, 1.0
	v_fma_f32 v19, v19, -2.0, 1.0
	v_fma_f32 v20, v20, -2.0, 1.0
	v_fma_f32 v21, v21, -2.0, 1.0
	v_fma_f32 v22, v22, -2.0, 1.0
	v_fma_f32 v23, v23, -2.0, 1.0
	v_mul_f32_e32 v8, 0.5, v8
	v_mul_f32_e32 v9, 0.5, v9
	v_mul_f32_e32 v10, 0.5, v10
	v_mul_f32_e32 v11, 0.5, v11
	v_mul_f32_e32 v12, 0.5, v12
	v_mul_f32_e32 v13, 0.5, v13
	v_mul_f32_e32 v14, 0.5, v14
	v_mul_f32_e32 v15, 0.5, v15
	v_add_f32_e32 v16, 1.0, v16
	v_add_f32_e32 v17, 1.0, v17
	v_add_f32_e32 v18, 1.0, v18
	v_add_f32_e32 v19, 1.0, v19
	v_add_f32_e32 v20, 1.0, v20
	v_add_f32_e32 v21, 1.0, v21
	v_add_f32_e32 v22, 1.0, v22
	v_add_f32_e32 v23, 1.0, v23
	v_mul_f32_e32 v8, v8, v16
	v_mul_f32_e32 v9, v9, v17
	v_mul_f32_e32 v10, v10, v18
	v_mul_f32_e32 v11, v11, v19
	v_mul_f32_e32 v12, v12, v20
	v_mul_f32_e32 v13, v13, v21
	v_mul_f32_e32 v14, v14, v22
	v_mul_f32_e32 v15, v15, v23
	v_mul_f32_e32 v24, v24, v8
	v_mul_f32_e32 v25, v25, v9
	v_mul_f32_e32 v26, v26, v10
	v_mul_f32_e32 v27, v27, v11
	v_mul_f32_e32 v28, v28, v12
	v_mul_f32_e32 v29, v29, v13
	v_mul_f32_e32 v30, v30, v14
	v_mul_f32_e32 v31, v31, v15
	v_mul_f32_e32 v180, v25, v25
	v_cvt_pk_bf16_f32 v176, v24, v25
	v_fmac_f32_e32 v180, v24, v24
	v_cvt_pk_bf16_f32 v177, v26, v27
	v_fmac_f32_e32 v180, v26, v26
	v_cvt_pk_bf16_f32 v178, v28, v29
	v_fmac_f32_e32 v180, v27, v27
	v_cvt_pk_bf16_f32 v179, v30, v31
	v_fmac_f32_e32 v180, v28, v28
	v_fmac_f32_e32 v180, v29, v29
	v_fmac_f32_e32 v180, v30, v30
	v_fmac_f32_e32 v180, v31, v31
	s_waitcnt vmcnt(9)
; __device__ __forceinline__ float bflo(unsigned w) { return __uint_as_float(w << 16); }
; __device__ __forceinline__ float bfhi(unsigned w) { return __uint_as_float(w & 0xffff0000u); }
; __device__ __forceinline__ void rnn_combine(const Params& p) {
;     ...
;             for (int i = 0; i < 4; ++i) { const unsigned a = hf[k][i], c = hb[k][i], gg = gw[k][i];
; #pragma unroll
;                 for (int e = 0; e < 2; ++e) { const float hs = (e ? bfhi(a) : bflo(a)) + (e ? bfhi(c) : bflo(c)); const float gt = e ? bfhi(gg) : bflo(gg);
;                     const float u = 0.7978845608028654f * (gt + 0.044715f * gt * gt * gt); const float th = 1.0f - 2.0f * __builtin_amdgcn_rcpf(1.0f + __builtin_amdgcn_exp2f(2.8853900817779268f * u));
;                     const float yv = hs * (0.5f * gt * (1.0f + th)); y[2 * i + e] = yv; q += yv * yv; } }
	v_lshlrev_b32_e32 v8, 16, v196
	v_and_b32_e32 v9, 0xffff0000, v196
	v_lshlrev_b32_e32 v10, 16, v197
	v_and_b32_e32 v11, 0xffff0000, v197
	v_lshlrev_b32_e32 v12, 16, v198
	v_and_b32_e32 v13, 0xffff0000, v198
	v_lshlrev_b32_e32 v14, 16, v199
	v_and_b32_e32 v15, 0xffff0000, v199
	v_mul_f32_e32 v16, 0x3d372713, v8
	v_mul_f32_e32 v17, 0x3d372713, v9
	v_mul_f32_e32 v18, 0x3d372713, v10
	v_mul_f32_e32 v19, 0x3d372713, v11
	v_mul_f32_e32 v20, 0x3d372713, v12
	v_mul_f32_e32 v21, 0x3d372713, v13
	v_mul_f32_e32 v22, 0x3d372713, v14
	v_mul_f32_e32 v23, 0x3d372713, v15
	v_mul_f32_e32 v16, v16, v8
	v_mul_f32_e32 v17, v17, v9
	v_mul_f32_e32 v18, v18, v10
	v_mul_f32_e32 v19, v19, v11
	v_mul_f32_e32 v20, v20, v12
	v_mul_f32_e32 v21, v21, v13
	v_mul_f32_e32 v22, v22, v14
	v_mul_f32_e32 v23, v23, v15
	v_fma_f32 v16, v16, v8, v8
	v_fma_f32 v17, v17, v9, v9
	v_fma_f32 v18, v18, v10, v10
	v_fma_f32 v19, v19, v11, v11
	v_fma_f32 v20, v20, v12, v12
	v_fma_f32 v21, v21, v13, v13
	v_fma_f32 v22, v22, v14, v14
	v_fma_f32 v23, v23, v15, v15
	v_mul_f32_e32 v16, 0x3f4c422a, v16
	v_mul_f32_e32 v17, 0x3f4c422a, v17
	v_mul_f32_e32 v18, 0x3f4c422a, v18
	v_mul_f32_e32 v19, 0x3f4c422a, v19
	v_mul_f32_e32 v20, 0x3f4c422a, v20
	v_mul_f32_e32 v21, 0x3f4c422a, v21
	v_mul_f32_e32 v22, 0x3f4c422a, v22
	v_mul_f32_e32 v23, 0x3f4c422a, v23
	v_mul_f32_e32 v16, 0x4038aa3b, v16
	v_mul_f32_e32 v17, 0x4038aa3b, v17
	v_mul_f32_e32 v18, 0x4038aa3b, v18
	v_mul_f32_e32 v19, 0x4038aa3b, v19
	v_mul_f32_e32 v20, 0x4038aa3b, v20
	v_mul_f32_e32 v21, 0x4038aa3b, v21
	v_mul_f32_e32 v22, 0x4038aa3b, v22
	v_mul_f32_e32 v23, 0x4038aa3b, v23
	v_exp_f32_e32 v16, v16
	v_exp_f32_e32 v17, v17
	v_exp_f32_e32 v18, v18
	v_exp_f32_e32 v19, v19
	v_exp_f32_e32 v20, v20
	v_exp_f32_e32 v21, v21
	v_exp_f32_e32 v22, v22
	v_exp_f32_e32 v23, v23
	v_lshlrev_b32_e32 v24, 16, v188
	v_and_b32_e32 v25, 0xffff0000, v188
	v_lshlrev_b32_e32 v26, 16, v189
	v_and_b32_e32 v27, 0xffff0000, v189
	v_lshlrev_b32_e32 v28, 16, v190
	v_and_b32_e32 v29, 0xffff0000, v190
	v_lshlrev_b32_e32 v30, 16, v191
	v_and_b32_e32 v31, 0xffff0000, v191
	v_add_f32_e32 v16, 1.0, v16
	v_add_f32_e32 v17, 1.0, v17
	v_add_f32_e32 v18, 1.0, v18
	v_add_f32_e32 v19, 1.0, v19
	v_add_f32_e32 v20, 1.0, v20
	v_add_f32_e32 v21, 1.0, v21
	v_add_f32_e32 v22, 1.0, v22
	v_add_f32_e32 v23, 1.0, v23
	v_rcp_f32_e32 v16, v16
	v_rcp_f32_e32 v17, v17
	v_rcp_f32_e32 v18, v18
	v_rcp_f32_e32 v19, v19
	v_rcp_f32_e32 v20, v20
	v_rcp_f32_e32 v21, v21
	v_rcp_f32_e32 v22, v22
	v_rcp_f32_e32 v23, v23
	v_lshlrev_b32_e32 v188, 16, v192
	v_and_b32_e32 v192, 0xffff0000, v192
	v_lshlrev_b32_e32 v189, 16, v193
	v_and_b32_e32 v193, 0xffff0000, v193
	v_lshlrev_b32_e32 v190, 16, v194
	v_and_b32_e32 v194, 0xffff0000, v194
	v_lshlrev_b32_e32 v191, 16, v195
	v_and_b32_e32 v195, 0xffff0000, v195
	v_add_f32_e32 v24, v188, v24
	v_add_f32_e32 v25, v192, v25
	v_add_f32_e32 v26, v189, v26
	v_add_f32_e32 v27, v193, v27
	v_add_f32_e32 v28, v190, v28
	v_add_f32_e32 v29, v194, v29
	v_add_f32_e32 v30, v191, v30
	v_add_f32_e32 v31, v195, v31
	v_fma_f32 v16, v16, -2.0, 1.0
	v_fma_f32 v17, v17, -2.0, 1.0
	v_fma_f32 v18, v18, -2.0, 1.0
	v_fma_f32 v19, v19, -2.0, 1.0
	v_fma_f32 v20, v20, -2.0, 1.0
	v_fma_f32 v21, v21, -2.0, 1.0
	v_fma_f32 v22, v22, -2.0, 1.0
	v_fma_f32 v23, v23, -2.0, 1.0
	v_mul_f32_e32 v8, 0.5, v8
	v_mul_f32_e32 v9, 0.5, v9
	v_mul_f32_e32 v10, 0.5, v10
	v_mul_f32_e32 v11, 0.5, v11
	v_mul_f32_e32 v12, 0.5, v12
	v_mul_f32_e32 v13, 0.5, v13
	v_mul_f32_e32 v14, 0.5, v14
	v_mul_f32_e32 v15, 0.5, v15
	v_add_f32_e32 v16, 1.0, v16
	v_add_f32_e32 v17, 1.0, v17
	v_add_f32_e32 v18, 1.0, v18
	v_add_f32_e32 v19, 1.0, v19
	v_add_f32_e32 v20, 1.0, v20
	v_add_f32_e32 v21, 1.0, v21
	v_add_f32_e32 v22, 1.0, v22
	v_add_f32_e32 v23, 1.0, v23
	v_mul_f32_e32 v8, v8, v16
	v_mul_f32_e32 v9, v9, v17
	v_mul_f32_e32 v10, v10, v18
	v_mul_f32_e32 v11, v11, v19
	v_mul_f32_e32 v12, v12, v20
	v_mul_f32_e32 v13, v13, v21
	v_mul_f32_e32 v14, v14, v22
	v_mul_f32_e32 v15, v15, v23
	v_mul_f32_e32 v24, v24, v8
	v_mul_f32_e32 v25, v25, v9
	v_mul_f32_e32 v26, v26, v10
	v_mul_f32_e32 v27, v27, v11
	v_mul_f32_e32 v28, v28, v12
	v_mul_f32_e32 v29, v29, v13
	v_mul_f32_e32 v30, v30, v14
	v_mul_f32_e32 v31, v31, v15
	v_mul_f32_e32 v192, v25, v25
	v_cvt_pk_bf16_f32 v188, v24, v25
	v_fmac_f32_e32 v192, v24, v24
	v_cvt_pk_bf16_f32 v189, v26, v27
	v_fmac_f32_e32 v192, v26, v26
	v_cvt_pk_bf16_f32 v190, v28, v29
	v_fmac_f32_e32 v192, v27, v27
	v_cvt_pk_bf16_f32 v191, v30, v31
	v_fmac_f32_e32 v192, v28, v28
	v_fmac_f32_e32 v192, v29, v29
	v_fmac_f32_e32 v192, v30, v30
	v_fmac_f32_e32 v192, v31, v31
	s_waitcnt vmcnt(6)
; __device__ __forceinline__ float bflo(unsigned w) { return __uint_as_float(w << 16); }
; __device__ __forceinline__ float bfhi(unsigned w) { return __uint_as_float(w & 0xffff0000u); }
; __device__ __forceinline__ void rnn_combine(const Params& p) {
;     ...
;             for (int i = 0; i < 4; ++i) { const unsigned a = hf[k][i], c = hb[k][i], gg = gw[k][i];
; #pragma unroll
;                 for (int e = 0; e < 2; ++e) { const float hs = (e ? bfhi(a) : bflo(a)) + (e ? bfhi(c) : bflo(c)); const float gt = e ? bfhi(gg) : bflo(gg);
;                     const float u = 0.7978845608028654f * (gt + 0.044715f * gt * gt * gt); const float th = 1.0f - 2.0f * __builtin_amdgcn_rcpf(1.0f + __builtin_amdgcn_exp2f(2.8853900817779268f * u));
;                     const float yv = hs * (0.5f * gt * (1.0f + th)); y[2 * i + e] = yv; q += yv * yv; } }
	v_lshlrev_b32_e32 v8, 16, v208
	v_and_b32_e32 v9, 0xffff0000, v208
	v_lshlrev_b32_e32 v10, 16, v209
	v_and_b32_e32 v11, 0xffff0000, v209
	v_lshlrev_b32_e32 v12, 16, v210
	v_and_b32_e32 v13, 0xffff0000, v210
	v_lshlrev_b32_e32 v14, 16, v211
	v_and_b32_e32 v15, 0xffff0000, v211
	v_mul_f32_e32 v16, 0x3d372713, v8
	v_mul_f32_e32 v17, 0x3d372713, v9
	v_mul_f32_e32 v18, 0x3d372713, v10
	v_mul_f32_e32 v19, 0x3d372713, v11
	v_mul_f32_e32 v20, 0x3d372713, v12
	v_mul_f32_e32 v21, 0x3d372713, v13
	v_mul_f32_e32 v22, 0x3d372713, v14
	v_mul_f32_e32 v23, 0x3d372713, v15
	v_mul_f32_e32 v16, v16, v8
	v_mul_f32_e32 v17, v17, v9
	v_mul_f32_e32 v18, v18, v10
	v_mul_f32_e32 v19, v19, v11
	v_mul_f32_e32 v20, v20, v12
	v_mul_f32_e32 v21, v21, v13
	v_mul_f32_e32 v22, v22, v14
	v_mul_f32_e32 v23, v23, v15
	v_fma_f32 v16, v16, v8, v8
	v_fma_f32 v17, v17, v9, v9
	v_fma_f32 v18, v18, v10, v10
	v_fma_f32 v19, v19, v11, v11
	v_fma_f32 v20, v20, v12, v12
	v_fma_f32 v21, v21, v13, v13
	v_fma_f32 v22, v22, v14, v14
	v_fma_f32 v23, v23, v15, v15
	v_mul_f32_e32 v16, 0x3f4c422a, v16
	v_mul_f32_e32 v17, 0x3f4c422a, v17
	v_mul_f32_e32 v18, 0x3f4c422a, v18
	v_mul_f32_e32 v19, 0x3f4c422a, v19
	v_mul_f32_e32 v20, 0x3f4c422a, v20
	v_mul_f32_e32 v21, 0x3f4c422a, v21
	v_mul_f32_e32 v22, 0x3f4c422a, v22
	v_mul_f32_e32 v23, 0x3f4c422a, v23
	v_mul_f32_e32 v16, 0x4038aa3b, v16
	v_mul_f32_e32 v17, 0x4038aa3b, v17
	v_mul_f32_e32 v18, 0x4038aa3b, v18
	v_mul_f32_e32 v19, 0x4038aa3b, v19
	v_mul_f32_e32 v20, 0x4038aa3b, v20
	v_mul_f32_e32 v21, 0x4038aa3b, v21
	v_mul_f32_e32 v22, 0x4038aa3b, v22
	v_mul_f32_e32 v23, 0x4038aa3b, v23
	v_exp_f32_e32 v16, v16
	v_exp_f32_e32 v17, v17
	v_exp_f32_e32 v18, v18
	v_exp_f32_e32 v19, v19
	v_exp_f32_e32 v20, v20
	v_exp_f32_e32 v21, v21
	v_exp_f32_e32 v22, v22
	v_exp_f32_e32 v23, v23
	v_lshlrev_b32_e32 v24, 16, v200
	v_and_b32_e32 v25, 0xffff0000, v200
	v_lshlrev_b32_e32 v26, 16, v201
	v_and_b32_e32 v27, 0xffff0000, v201
	v_lshlrev_b32_e32 v28, 16, v202
	v_and_b32_e32 v29, 0xffff0000, v202
	v_lshlrev_b32_e32 v30, 16, v203
	v_and_b32_e32 v31, 0xffff0000, v203
	v_add_f32_e32 v16, 1.0, v16
	v_add_f32_e32 v17, 1.0, v17
	v_add_f32_e32 v18, 1.0, v18
	v_add_f32_e32 v19, 1.0, v19
	v_add_f32_e32 v20, 1.0, v20
	v_add_f32_e32 v21, 1.0, v21
	v_add_f32_e32 v22, 1.0, v22
	v_add_f32_e32 v23, 1.0, v23
	v_rcp_f32_e32 v16, v16
	v_rcp_f32_e32 v17, v17
	v_rcp_f32_e32 v18, v18
	v_rcp_f32_e32 v19, v19
	v_rcp_f32_e32 v20, v20
	v_rcp_f32_e32 v21, v21
	v_rcp_f32_e32 v22, v22
	v_rcp_f32_e32 v23, v23
	v_lshlrev_b32_e32 v200, 16, v204
	v_and_b32_e32 v204, 0xffff0000, v204
	v_lshlrev_b32_e32 v201, 16, v205
	v_and_b32_e32 v205, 0xffff0000, v205
	v_lshlrev_b32_e32 v202, 16, v206
	v_and_b32_e32 v206, 0xffff0000, v206
	v_lshlrev_b32_e32 v203, 16, v207
	v_and_b32_e32 v207, 0xffff0000, v207
	v_add_f32_e32 v24, v200, v24
	v_add_f32_e32 v25, v204, v25
	v_add_f32_e32 v26, v201, v26
	v_add_f32_e32 v27, v205, v27
	v_add_f32_e32 v28, v202, v28
	v_add_f32_e32 v29, v206, v29
	v_add_f32_e32 v30, v203, v30
	v_add_f32_e32 v31, v207, v31
	v_fma_f32 v16, v16, -2.0, 1.0
	v_fma_f32 v17, v17, -2.0, 1.0
	v_fma_f32 v18, v18, -2.0, 1.0
	v_fma_f32 v19, v19, -2.0, 1.0
	v_fma_f32 v20, v20, -2.0, 1.0
	v_fma_f32 v21, v21, -2.0, 1.0
	v_fma_f32 v22, v22, -2.0, 1.0
	v_fma_f32 v23, v23, -2.0, 1.0
	v_mul_f32_e32 v8, 0.5, v8
	v_mul_f32_e32 v9, 0.5, v9
	v_mul_f32_e32 v10, 0.5, v10
	v_mul_f32_e32 v11, 0.5, v11
	v_mul_f32_e32 v12, 0.5, v12
	v_mul_f32_e32 v13, 0.5, v13
	v_mul_f32_e32 v14, 0.5, v14
	v_mul_f32_e32 v15, 0.5, v15
	v_add_f32_e32 v16, 1.0, v16
	v_add_f32_e32 v17, 1.0, v17
	v_add_f32_e32 v18, 1.0, v18
	v_add_f32_e32 v19, 1.0, v19
	v_add_f32_e32 v20, 1.0, v20
	v_add_f32_e32 v21, 1.0, v21
	v_add_f32_e32 v22, 1.0, v22
	v_add_f32_e32 v23, 1.0, v23
	v_mul_f32_e32 v8, v8, v16
	v_mul_f32_e32 v9, v9, v17
	v_mul_f32_e32 v10, v10, v18
	v_mul_f32_e32 v11, v11, v19
	v_mul_f32_e32 v12, v12, v20
	v_mul_f32_e32 v13, v13, v21
	v_mul_f32_e32 v14, v14, v22
	v_mul_f32_e32 v15, v15, v23
	v_mul_f32_e32 v24, v24, v8
	v_mul_f32_e32 v25, v25, v9
	v_mul_f32_e32 v26, v26, v10
	v_mul_f32_e32 v27, v27, v11
	v_mul_f32_e32 v28, v28, v12
	v_mul_f32_e32 v29, v29, v13
	v_mul_f32_e32 v30, v30, v14
	v_mul_f32_e32 v31, v31, v15
	v_mul_f32_e32 v204, v25, v25
	v_cvt_pk_bf16_f32 v200, v24, v25
	v_fmac_f32_e32 v204, v24, v24
	v_cvt_pk_bf16_f32 v201, v26, v27
	v_fmac_f32_e32 v204, v26, v26
	v_cvt_pk_bf16_f32 v202, v28, v29
	v_fmac_f32_e32 v204, v27, v27
	v_cvt_pk_bf16_f32 v203, v30, v31
	v_fmac_f32_e32 v204, v28, v28
	v_fmac_f32_e32 v204, v29, v29
	v_fmac_f32_e32 v204, v30, v30
	v_fmac_f32_e32 v204, v31, v31
	s_waitcnt vmcnt(3)
; __device__ __forceinline__ float bflo(unsigned w) { return __uint_as_float(w << 16); }
; __device__ __forceinline__ float bfhi(unsigned w) { return __uint_as_float(w & 0xffff0000u); }
; __device__ __forceinline__ void rnn_combine(const Params& p) {
;     ...
;             for (int i = 0; i < 4; ++i) { const unsigned a = hf[k][i], c = hb[k][i], gg = gw[k][i];
; #pragma unroll
;                 for (int e = 0; e < 2; ++e) { const float hs = (e ? bfhi(a) : bflo(a)) + (e ? bfhi(c) : bflo(c)); const float gt = e ? bfhi(gg) : bflo(gg);
;                     const float u = 0.7978845608028654f * (gt + 0.044715f * gt * gt * gt); const float th = 1.0f - 2.0f * __builtin_amdgcn_rcpf(1.0f + __builtin_amdgcn_exp2f(2.8853900817779268f * u));
;                     const float yv = hs * (0.5f * gt * (1.0f + th)); y[2 * i + e] = yv; q += yv * yv; } }
	v_lshlrev_b32_e32 v8, 16, v220
	v_and_b32_e32 v9, 0xffff0000, v220
	v_lshlrev_b32_e32 v10, 16, v221
	v_and_b32_e32 v11, 0xffff0000, v221
	v_lshlrev_b32_e32 v12, 16, v222
	v_and_b32_e32 v13, 0xffff0000, v222
	v_lshlrev_b32_e32 v14, 16, v223
	v_and_b32_e32 v15, 0xffff0000, v223
	v_mul_f32_e32 v16, 0x3d372713, v8
	v_mul_f32_e32 v17, 0x3d372713, v9
	v_mul_f32_e32 v18, 0x3d372713, v10
	v_mul_f32_e32 v19, 0x3d372713, v11
	v_mul_f32_e32 v20, 0x3d372713, v12
	v_mul_f32_e32 v21, 0x3d372713, v13
	v_mul_f32_e32 v22, 0x3d372713, v14
	v_mul_f32_e32 v23, 0x3d372713, v15
	v_mul_f32_e32 v16, v16, v8
	v_mul_f32_e32 v17, v17, v9
	v_mul_f32_e32 v18, v18, v10
	v_mul_f32_e32 v19, v19, v11
	v_mul_f32_e32 v20, v20, v12
	v_mul_f32_e32 v21, v21, v13
	v_mul_f32_e32 v22, v22, v14
	v_mul_f32_e32 v23, v23, v15
	v_fma_f32 v16, v16, v8, v8
	v_fma_f32 v17, v17, v9, v9
	v_fma_f32 v18, v18, v10, v10
	v_fma_f32 v19, v19, v11, v11
	v_fma_f32 v20, v20, v12, v12
	v_fma_f32 v21, v21, v13, v13
	v_fma_f32 v22, v22, v14, v14
	v_fma_f32 v23, v23, v15, v15
	v_mul_f32_e32 v16, 0x3f4c422a, v16
	v_mul_f32_e32 v17, 0x3f4c422a, v17
	v_mul_f32_e32 v18, 0x3f4c422a, v18
	v_mul_f32_e32 v19, 0x3f4c422a, v19
	v_mul_f32_e32 v20, 0x3f4c422a, v20
	v_mul_f32_e32 v21, 0x3f4c422a, v21
	v_mul_f32_e32 v22, 0x3f4c422a, v22
	v_mul_f32_e32 v23, 0x3f4c422a, v23
	v_mul_f32_e32 v16, 0x4038aa3b, v16
	v_mul_f32_e32 v17, 0x4038aa3b, v17
	v_mul_f32_e32 v18, 0x4038aa3b, v18
	v_mul_f32_e32 v19, 0x4038aa3b, v19
	v_mul_f32_e32 v20, 0x4038aa3b, v20
	v_mul_f32_e32 v21, 0x4038aa3b, v21
	v_mul_f32_e32 v22, 0x4038aa3b, v22
	v_mul_f32_e32 v23, 0x4038aa3b, v23
	v_exp_f32_e32 v16, v16
	v_exp_f32_e32 v17, v17
	v_exp_f32_e32 v18, v18
	v_exp_f32_e32 v19, v19
	v_exp_f32_e32 v20, v20
	v_exp_f32_e32 v21, v21
	v_exp_f32_e32 v22, v22
	v_exp_f32_e32 v23, v23
	v_lshlrev_b32_e32 v24, 16, v212
	v_and_b32_e32 v25, 0xffff0000, v212
	v_lshlrev_b32_e32 v26, 16, v213
	v_and_b32_e32 v27, 0xffff0000, v213
	v_lshlrev_b32_e32 v28, 16, v214
	v_and_b32_e32 v29, 0xffff0000, v214
	v_lshlrev_b32_e32 v30, 16, v215
	v_and_b32_e32 v31, 0xffff0000, v215
	v_add_f32_e32 v16, 1.0, v16
	v_add_f32_e32 v17, 1.0, v17
	v_add_f32_e32 v18, 1.0, v18
	v_add_f32_e32 v19, 1.0, v19
	v_add_f32_e32 v20, 1.0, v20
	v_add_f32_e32 v21, 1.0, v21
	v_add_f32_e32 v22, 1.0, v22
	v_add_f32_e32 v23, 1.0, v23
	v_rcp_f32_e32 v16, v16
	v_rcp_f32_e32 v17, v17
	v_rcp_f32_e32 v18, v18
	v_rcp_f32_e32 v19, v19
	v_rcp_f32_e32 v20, v20
	v_rcp_f32_e32 v21, v21
	v_rcp_f32_e32 v22, v22
	v_rcp_f32_e32 v23, v23
	v_lshlrev_b32_e32 v212, 16, v216
	v_and_b32_e32 v216, 0xffff0000, v216
	v_lshlrev_b32_e32 v213, 16, v217
	v_and_b32_e32 v217, 0xffff0000, v217
	v_lshlrev_b32_e32 v214, 16, v218
	v_and_b32_e32 v218, 0xffff0000, v218
	v_lshlrev_b32_e32 v215, 16, v219
	v_and_b32_e32 v219, 0xffff0000, v219
	v_add_f32_e32 v24, v212, v24
	v_add_f32_e32 v25, v216, v25
	v_add_f32_e32 v26, v213, v26
	v_add_f32_e32 v27, v217, v27
	v_add_f32_e32 v28, v214, v28
	v_add_f32_e32 v29, v218, v29
	v_add_f32_e32 v30, v215, v30
	v_add_f32_e32 v31, v219, v31
	v_fma_f32 v16, v16, -2.0, 1.0
	v_fma_f32 v17, v17, -2.0, 1.0
	v_fma_f32 v18, v18, -2.0, 1.0
	v_fma_f32 v19, v19, -2.0, 1.0
	v_fma_f32 v20, v20, -2.0, 1.0
	v_fma_f32 v21, v21, -2.0, 1.0
	v_fma_f32 v22, v22, -2.0, 1.0
	v_fma_f32 v23, v23, -2.0, 1.0
	v_mul_f32_e32 v8, 0.5, v8
	v_mul_f32_e32 v9, 0.5, v9
	v_mul_f32_e32 v10, 0.5, v10
	v_mul_f32_e32 v11, 0.5, v11
	v_mul_f32_e32 v12, 0.5, v12
	v_mul_f32_e32 v13, 0.5, v13
	v_mul_f32_e32 v14, 0.5, v14
	v_mul_f32_e32 v15, 0.5, v15
	v_add_f32_e32 v16, 1.0, v16
	v_add_f32_e32 v17, 1.0, v17
	v_add_f32_e32 v18, 1.0, v18
	v_add_f32_e32 v19, 1.0, v19
	v_add_f32_e32 v20, 1.0, v20
	v_add_f32_e32 v21, 1.0, v21
	v_add_f32_e32 v22, 1.0, v22
	v_add_f32_e32 v23, 1.0, v23
	v_mul_f32_e32 v8, v8, v16
	v_mul_f32_e32 v9, v9, v17
	v_mul_f32_e32 v10, v10, v18
	v_mul_f32_e32 v11, v11, v19
	v_mul_f32_e32 v12, v12, v20
	v_mul_f32_e32 v13, v13, v21
	v_mul_f32_e32 v14, v14, v22
	v_mul_f32_e32 v15, v15, v23
	v_mul_f32_e32 v24, v24, v8
	v_mul_f32_e32 v25, v25, v9
	v_mul_f32_e32 v26, v26, v10
	v_mul_f32_e32 v27, v27, v11
	v_mul_f32_e32 v28, v28, v12
	v_mul_f32_e32 v29, v29, v13
	v_mul_f32_e32 v30, v30, v14
	v_mul_f32_e32 v31, v31, v15
	v_mul_f32_e32 v216, v25, v25
	v_cvt_pk_bf16_f32 v212, v24, v25
	v_fmac_f32_e32 v216, v24, v24
	v_cvt_pk_bf16_f32 v213, v26, v27
	v_fmac_f32_e32 v216, v26, v26
	v_cvt_pk_bf16_f32 v214, v28, v29
	v_fmac_f32_e32 v216, v27, v27
	v_cvt_pk_bf16_f32 v215, v30, v31
	v_fmac_f32_e32 v216, v28, v28
	v_fmac_f32_e32 v216, v29, v29
	v_fmac_f32_e32 v216, v30, v30
	v_fmac_f32_e32 v216, v31, v31
	s_waitcnt vmcnt(0)
; __device__ __forceinline__ unsigned cvt_pk(float lo, float hi) { unsigned r; asm("v_cvt_pk_bf16_f32 %0, %1, %2" : "=v"(r) : "v"(lo), "v"(hi)); return r; }
; __device__ __forceinline__ float bflo(unsigned w) { return __uint_as_float(w << 16); }
; __device__ __forceinline__ float bfhi(unsigned w) { return __uint_as_float(w & 0xffff0000u); }
; __device__ __forceinline__ void rnn_combine(const Params& p) {
;     ...
;             for (int i = 0; i < 4; ++i) { const unsigned a = hf[k][i], c = hb[k][i], gg = gw[k][i];
; #pragma unroll
;                 for (int e = 0; e < 2; ++e) { const float hs = (e ? bfhi(a) : bflo(a)) + (e ? bfhi(c) : bflo(c)); const float gt = e ? bfhi(gg) : bflo(gg);
;                     const float u = 0.7978845608028654f * (gt + 0.044715f * gt * gt * gt); const float th = 1.0f - 2.0f * __builtin_amdgcn_rcpf(1.0f + __builtin_amdgcn_exp2f(2.8853900817779268f * u));
;                     const float yv = hs * (0.5f * gt * (1.0f + th)); y[2 * i + e] = yv; q += yv * yv; } }
;             q = wave_sum(q);
;             if (rr < MR) { u32x4 w; w.x = cvt_pk(y[0], y[1]); w.y = cvt_pk(y[2], y[3]); w.z = cvt_pk(y[4], y[5]); w.w = cvt_pk(y[6], y[7]);
;                 *(u32x4*)(MIX + (size_t)rr * DM + 512 + 8 * lane) = w;
	v_lshlrev_b32_e32 v8, 16, v232
	v_and_b32_e32 v9, 0xffff0000, v232
	v_lshlrev_b32_e32 v10, 16, v233
	v_and_b32_e32 v11, 0xffff0000, v233
	v_lshlrev_b32_e32 v12, 16, v234
	v_and_b32_e32 v13, 0xffff0000, v234
	v_lshlrev_b32_e32 v14, 16, v235
	v_and_b32_e32 v15, 0xffff0000, v235
	v_mul_f32_e32 v16, 0x3d372713, v8
	v_mul_f32_e32 v17, 0x3d372713, v9
	v_mul_f32_e32 v18, 0x3d372713, v10
	v_mul_f32_e32 v19, 0x3d372713, v11
	v_mul_f32_e32 v20, 0x3d372713, v12
	v_mul_f32_e32 v21, 0x3d372713, v13
	v_mul_f32_e32 v22, 0x3d372713, v14
	v_mul_f32_e32 v23, 0x3d372713, v15
	v_mul_f32_e32 v16, v16, v8
	v_mul_f32_e32 v17, v17, v9
	v_mul_f32_e32 v18, v18, v10
	v_mul_f32_e32 v19, v19, v11
	v_mul_f32_e32 v20, v20, v12
	v_mul_f32_e32 v21, v21, v13
	v_mul_f32_e32 v22, v22, v14
	v_mul_f32_e32 v23, v23, v15
	v_fma_f32 v16, v16, v8, v8
	v_fma_f32 v17, v17, v9, v9
	v_fma_f32 v18, v18, v10, v10
	v_fma_f32 v19, v19, v11, v11
	v_fma_f32 v20, v20, v12, v12
	v_fma_f32 v21, v21, v13, v13
	v_fma_f32 v22, v22, v14, v14
	v_fma_f32 v23, v23, v15, v15
	v_mul_f32_e32 v16, 0x3f4c422a, v16
	v_mul_f32_e32 v17, 0x3f4c422a, v17
	v_mul_f32_e32 v18, 0x3f4c422a, v18
	v_mul_f32_e32 v19, 0x3f4c422a, v19
	v_mul_f32_e32 v20, 0x3f4c422a, v20
	v_mul_f32_e32 v21, 0x3f4c422a, v21
	v_mul_f32_e32 v22, 0x3f4c422a, v22
	v_mul_f32_e32 v23, 0x3f4c422a, v23
	v_mul_f32_e32 v16, 0x4038aa3b, v16
	v_mul_f32_e32 v17, 0x4038aa3b, v17
	v_mul_f32_e32 v18, 0x4038aa3b, v18
	v_mul_f32_e32 v19, 0x4038aa3b, v19
	v_mul_f32_e32 v20, 0x4038aa3b, v20
	v_mul_f32_e32 v21, 0x4038aa3b, v21
	v_mul_f32_e32 v22, 0x4038aa3b, v22
	v_mul_f32_e32 v23, 0x4038aa3b, v23
	v_exp_f32_e32 v16, v16
	v_exp_f32_e32 v17, v17
	v_exp_f32_e32 v18, v18
	v_exp_f32_e32 v19, v19
	v_exp_f32_e32 v20, v20
	v_exp_f32_e32 v21, v21
	v_exp_f32_e32 v22, v22
	v_exp_f32_e32 v23, v23
	v_lshlrev_b32_e32 v24, 16, v224
	v_and_b32_e32 v25, 0xffff0000, v224
	v_lshlrev_b32_e32 v26, 16, v225
	v_and_b32_e32 v27, 0xffff0000, v225
	v_lshlrev_b32_e32 v28, 16, v226
	v_and_b32_e32 v29, 0xffff0000, v226
	v_lshlrev_b32_e32 v30, 16, v227
	v_and_b32_e32 v31, 0xffff0000, v227
	v_add_f32_e32 v16, 1.0, v16
	v_add_f32_e32 v17, 1.0, v17
	v_add_f32_e32 v18, 1.0, v18
	v_add_f32_e32 v19, 1.0, v19
	v_add_f32_e32 v20, 1.0, v20
	v_add_f32_e32 v21, 1.0, v21
	v_add_f32_e32 v22, 1.0, v22
	v_add_f32_e32 v23, 1.0, v23
	v_rcp_f32_e32 v16, v16
	v_rcp_f32_e32 v17, v17
	v_rcp_f32_e32 v18, v18
	v_rcp_f32_e32 v19, v19
	v_rcp_f32_e32 v20, v20
	v_rcp_f32_e32 v21, v21
	v_rcp_f32_e32 v22, v22
	v_rcp_f32_e32 v23, v23
	v_lshlrev_b32_e32 v224, 16, v228
	v_and_b32_e32 v228, 0xffff0000, v228
	v_lshlrev_b32_e32 v225, 16, v229
	v_and_b32_e32 v229, 0xffff0000, v229
	v_lshlrev_b32_e32 v226, 16, v230
	v_and_b32_e32 v230, 0xffff0000, v230
	v_lshlrev_b32_e32 v227, 16, v231
	v_and_b32_e32 v231, 0xffff0000, v231
	v_add_f32_e32 v24, v224, v24
	v_add_f32_e32 v25, v228, v25
	v_add_f32_e32 v26, v225, v26
	v_add_f32_e32 v27, v229, v27
	v_add_f32_e32 v28, v226, v28
	v_add_f32_e32 v29, v230, v29
	v_add_f32_e32 v30, v227, v30
	v_add_f32_e32 v31, v231, v31
	v_fma_f32 v16, v16, -2.0, 1.0
	v_fma_f32 v17, v17, -2.0, 1.0
	v_fma_f32 v18, v18, -2.0, 1.0
	v_fma_f32 v19, v19, -2.0, 1.0
	v_fma_f32 v20, v20, -2.0, 1.0
	v_fma_f32 v21, v21, -2.0, 1.0
	v_fma_f32 v22, v22, -2.0, 1.0
	v_fma_f32 v23, v23, -2.0, 1.0
	v_mul_f32_e32 v8, 0.5, v8
	v_mul_f32_e32 v9, 0.5, v9
	v_mul_f32_e32 v10, 0.5, v10
	v_mul_f32_e32 v11, 0.5, v11
	v_mul_f32_e32 v12, 0.5, v12
	v_mul_f32_e32 v13, 0.5, v13
	v_mul_f32_e32 v14, 0.5, v14
	v_mul_f32_e32 v15, 0.5, v15
	v_add_f32_e32 v16, 1.0, v16
	v_add_f32_e32 v17, 1.0, v17
	v_add_f32_e32 v18, 1.0, v18
	v_add_f32_e32 v19, 1.0, v19
	v_add_f32_e32 v20, 1.0, v20
	v_add_f32_e32 v21, 1.0, v21
	v_add_f32_e32 v22, 1.0, v22
	v_add_f32_e32 v23, 1.0, v23
	v_mul_f32_e32 v8, v8, v16
	v_mul_f32_e32 v9, v9, v17
	v_mul_f32_e32 v10, v10, v18
	v_mul_f32_e32 v11, v11, v19
	v_mul_f32_e32 v12, v12, v20
	v_mul_f32_e32 v13, v13, v21
	v_mul_f32_e32 v14, v14, v22
	v_mul_f32_e32 v15, v15, v23
	v_mul_f32_e32 v24, v24, v8
	v_mul_f32_e32 v25, v25, v9
	v_mul_f32_e32 v26, v26, v10
	v_mul_f32_e32 v27, v27, v11
	v_mul_f32_e32 v28, v28, v12
	v_mul_f32_e32 v29, v29, v13
	v_mul_f32_e32 v30, v30, v14
	v_mul_f32_e32 v31, v31, v15
	v_mul_f32_e32 v228, v25, v25
	v_cvt_pk_bf16_f32 v224, v24, v25
	v_fmac_f32_e32 v228, v24, v24
	v_cvt_pk_bf16_f32 v225, v26, v27
	v_fmac_f32_e32 v228, v26, v26
	v_cvt_pk_bf16_f32 v226, v28, v29
	v_fmac_f32_e32 v228, v27, v27
	v_cvt_pk_bf16_f32 v227, v30, v31
	v_fmac_f32_e32 v228, v28, v28
	v_fmac_f32_e32 v228, v29, v29
	v_fmac_f32_e32 v228, v30, v30
	v_fmac_f32_e32 v228, v31, v31
	s_lshl_b32 s2, s0, 11
	s_add_u32 s4, s22, s2
	s_addc_u32 s5, s23, 0
	s_add_u32 s4, s4, 0x15800400
	s_addc_u32 s5, s5, 0
	global_store_dwordx4 v7, v[32:35], s[4:5]
	s_add_u32 s4, s4, 0x400000
	s_addc_u32 s5, s5, 0
	global_store_dwordx4 v7, v[44:47], s[4:5]
	s_add_u32 s4, s4, 0x400000
	s_addc_u32 s5, s5, 0
	global_store_dwordx4 v7, v[56:59], s[4:5]
	s_add_u32 s4, s4, 0x400000
	s_addc_u32 s5, s5, 0
	global_store_dwordx4 v7, v[68:71], s[4:5]
	s_add_u32 s4, s4, 0x400000
	s_addc_u32 s5, s5, 0
	global_store_dwordx4 v7, v[80:83], s[4:5]
	s_add_u32 s4, s4, 0x400000
	s_addc_u32 s5, s5, 0
	global_store_dwordx4 v7, v[92:95], s[4:5]
	s_add_u32 s4, s4, 0x400000
	s_addc_u32 s5, s5, 0
	global_store_dwordx4 v7, v[104:107], s[4:5]
	s_add_u32 s4, s4, 0x400000
	s_addc_u32 s5, s5, 0
	global_store_dwordx4 v7, v[116:119], s[4:5]
	s_add_u32 s4, s4, 0x400000
	s_addc_u32 s5, s5, 0
	global_store_dwordx4 v7, v[128:131], s[4:5]
	s_add_u32 s4, s4, 0x400000
	s_addc_u32 s5, s5, 0
	global_store_dwordx4 v7, v[140:143], s[4:5]
	s_add_u32 s4, s4, 0x400000
	s_addc_u32 s5, s5, 0
	global_store_dwordx4 v7, v[164:167], s[4:5]
	s_add_u32 s4, s4, 0x400000
	s_addc_u32 s5, s5, 0
	global_store_dwordx4 v7, v[176:179], s[4:5]
	s_add_u32 s4, s4, 0x400000
	s_addc_u32 s5, s5, 0
	global_store_dwordx4 v7, v[188:191], s[4:5]
	s_add_u32 s4, s4, 0x400000
	s_addc_u32 s5, s5, 0
	global_store_dwordx4 v7, v[200:203], s[4:5]
	s_add_u32 s4, s4, 0x400000
	s_addc_u32 s5, s5, 0
	global_store_dwordx4 v7, v[212:215], s[4:5]
	s_add_u32 s4, s4, 0x400000
	s_addc_u32 s5, s5, 0
	global_store_dwordx4 v7, v[224:227], s[4:5]
	ds_bpermute_b32 v37, v1, v36
	ds_bpermute_b32 v49, v1, v48
	ds_bpermute_b32 v61, v1, v60
	ds_bpermute_b32 v73, v1, v72
	ds_bpermute_b32 v85, v1, v84
	ds_bpermute_b32 v97, v1, v96
	ds_bpermute_b32 v109, v1, v108
	ds_bpermute_b32 v121, v1, v120
	s_waitcnt lgkmcnt(0)
; __device__ __forceinline__ float wave_sum(float v) {
;     ...
;     for (int o = 1; o < 64; o <<= 1) v += __shfl_xor(v, o);
; __device__ __forceinline__ void rnn_combine(const Params& p) {
;     ...
;             q = wave_sum(q);
	v_add_f32_e32 v36, v36, v37
	v_add_f32_e32 v48, v48, v49
	v_add_f32_e32 v60, v60, v61
	v_add_f32_e32 v72, v72, v73
	v_add_f32_e32 v84, v84, v85
	v_add_f32_e32 v96, v96, v97
	v_add_f32_e32 v108, v108, v109
	v_add_f32_e32 v120, v120, v121
	ds_bpermute_b32 v133, v1, v132
	ds_bpermute_b32 v145, v1, v144
	ds_bpermute_b32 v169, v1, v168
	ds_bpermute_b32 v181, v1, v180
	ds_bpermute_b32 v193, v1, v192
	ds_bpermute_b32 v205, v1, v204
	ds_bpermute_b32 v217, v1, v216
	ds_bpermute_b32 v229, v1, v228
	s_waitcnt lgkmcnt(0)
	v_add_f32_e32 v132, v132, v133
	v_add_f32_e32 v144, v144, v145
	v_add_f32_e32 v168, v168, v169
	v_add_f32_e32 v180, v180, v181
	v_add_f32_e32 v192, v192, v193
	v_add_f32_e32 v204, v204, v205
	v_add_f32_e32 v216, v216, v217
	v_add_f32_e32 v228, v228, v229
	ds_bpermute_b32 v37, v2, v36
	ds_bpermute_b32 v49, v2, v48
	ds_bpermute_b32 v61, v2, v60
	ds_bpermute_b32 v73, v2, v72
	ds_bpermute_b32 v85, v2, v84
	ds_bpermute_b32 v97, v2, v96
	ds_bpermute_b32 v109, v2, v108
	ds_bpermute_b32 v121, v2, v120
	s_waitcnt lgkmcnt(0)
	v_add_f32_e32 v36, v36, v37
	v_add_f32_e32 v48, v48, v49
	v_add_f32_e32 v60, v60, v61
	v_add_f32_e32 v72, v72, v73
	v_add_f32_e32 v84, v84, v85
	v_add_f32_e32 v96, v96, v97
	v_add_f32_e32 v108, v108, v109
	v_add_f32_e32 v120, v120, v121
	ds_bpermute_b32 v133, v2, v132
	ds_bpermute_b32 v145, v2, v144
	ds_bpermute_b32 v169, v2, v168
	ds_bpermute_b32 v181, v2, v180
	ds_bpermute_b32 v193, v2, v192
	ds_bpermute_b32 v205, v2, v204
	ds_bpermute_b32 v217, v2, v216
	ds_bpermute_b32 v229, v2, v228
	s_waitcnt lgkmcnt(0)
	v_add_f32_e32 v132, v132, v133
	v_add_f32_e32 v144, v144, v145
	v_add_f32_e32 v168, v168, v169
	v_add_f32_e32 v180, v180, v181
	v_add_f32_e32 v192, v192, v193
	v_add_f32_e32 v204, v204, v205
	v_add_f32_e32 v216, v216, v217
	v_add_f32_e32 v228, v228, v229
	ds_bpermute_b32 v37, v3, v36
	ds_bpermute_b32 v49, v3, v48
	ds_bpermute_b32 v61, v3, v60
	ds_bpermute_b32 v73, v3, v72
	ds_bpermute_b32 v85, v3, v84
	ds_bpermute_b32 v97, v3, v96
	ds_bpermute_b32 v109, v3, v108
	ds_bpermute_b32 v121, v3, v120
	s_waitcnt lgkmcnt(0)
	v_add_f32_e32 v36, v36, v37
	v_add_f32_e32 v48, v48, v49
	v_add_f32_e32 v60, v60, v61
	v_add_f32_e32 v72, v72, v73
	v_add_f32_e32 v84, v84, v85
	v_add_f32_e32 v96, v96, v97
	v_add_f32_e32 v108, v108, v109
	v_add_f32_e32 v120, v120, v121
	ds_bpermute_b32 v133, v3, v132
	ds_bpermute_b32 v145, v3, v144
	ds_bpermute_b32 v169, v3, v168
	ds_bpermute_b32 v181, v3, v180
	ds_bpermute_b32 v193, v3, v192
	ds_bpermute_b32 v205, v3, v204
	ds_bpermute_b32 v217, v3, v216
	ds_bpermute_b32 v229, v3, v228
	s_waitcnt lgkmcnt(0)
	v_add_f32_e32 v132, v132, v133
	v_add_f32_e32 v144, v144, v145
	v_add_f32_e32 v168, v168, v169
	v_add_f32_e32 v180, v180, v181
	v_add_f32_e32 v192, v192, v193
	v_add_f32_e32 v204, v204, v205
	v_add_f32_e32 v216, v216, v217
	v_add_f32_e32 v228, v228, v229
	ds_bpermute_b32 v37, v4, v36
	ds_bpermute_b32 v49, v4, v48
	ds_bpermute_b32 v61, v4, v60
	ds_bpermute_b32 v73, v4, v72
	ds_bpermute_b32 v85, v4, v84
	ds_bpermute_b32 v97, v4, v96
	ds_bpermute_b32 v109, v4, v108
	ds_bpermute_b32 v121, v4, v120
	s_waitcnt lgkmcnt(0)
	v_add_f32_e32 v36, v36, v37
	v_add_f32_e32 v48, v48, v49
	v_add_f32_e32 v60, v60, v61
	v_add_f32_e32 v72, v72, v73
	v_add_f32_e32 v84, v84, v85
	v_add_f32_e32 v96, v96, v97
	v_add_f32_e32 v108, v108, v109
	v_add_f32_e32 v120, v120, v121
	ds_bpermute_b32 v133, v4, v132
	ds_bpermute_b32 v145, v4, v144
	ds_bpermute_b32 v169, v4, v168
	ds_bpermute_b32 v181, v4, v180
	ds_bpermute_b32 v193, v4, v192
	ds_bpermute_b32 v205, v4, v204
	ds_bpermute_b32 v217, v4, v216
	ds_bpermute_b32 v229, v4, v228
	s_waitcnt lgkmcnt(0)
	v_add_f32_e32 v132, v132, v133
	v_add_f32_e32 v144, v144, v145
	v_add_f32_e32 v168, v168, v169
	v_add_f32_e32 v180, v180, v181
	v_add_f32_e32 v192, v192, v193
	v_add_f32_e32 v204, v204, v205
	v_add_f32_e32 v216, v216, v217
	v_add_f32_e32 v228, v228, v229
	ds_bpermute_b32 v37, v5, v36
	ds_bpermute_b32 v49, v5, v48
	ds_bpermute_b32 v61, v5, v60
	ds_bpermute_b32 v73, v5, v72
	ds_bpermute_b32 v85, v5, v84
	ds_bpermute_b32 v97, v5, v96
	ds_bpermute_b32 v109, v5, v108
	ds_bpermute_b32 v121, v5, v120
	s_waitcnt lgkmcnt(0)
	v_add_f32_e32 v36, v36, v37
	v_add_f32_e32 v48, v48, v49
	v_add_f32_e32 v60, v60, v61
	v_add_f32_e32 v72, v72, v73
	v_add_f32_e32 v84, v84, v85
	v_add_f32_e32 v96, v96, v97
	v_add_f32_e32 v108, v108, v109
	v_add_f32_e32 v120, v120, v121
	ds_bpermute_b32 v133, v5, v132
	ds_bpermute_b32 v145, v5, v144
	ds_bpermute_b32 v169, v5, v168
	ds_bpermute_b32 v181, v5, v180
	ds_bpermute_b32 v193, v5, v192
	ds_bpermute_b32 v205, v5, v204
	ds_bpermute_b32 v217, v5, v216
	ds_bpermute_b32 v229, v5, v228
	s_waitcnt lgkmcnt(0)
; __device__ __forceinline__ unsigned cvt_pk(float lo, float hi) { unsigned r; asm("v_cvt_pk_bf16_f32 %0, %1, %2" : "=v"(r) : "v"(lo), "v"(hi)); return r; }
; __device__ __forceinline__ void rnn_combine(const Params& p) {
;     ...
;     for (int r0 = blockIdx.x * 8 + wave; r0 < MR; r0 += 4 * NW) {
;         u32x4 hf[4], hb[4], gw[4];
; #pragma unroll
;         for (int k = 0; k < 4; ++k) { const int rr = (r0 + k * NW < MR) ? r0 + k * NW : r0; const int b = rr / SEQ, sidx = rr % SEQ; const size_t src = (size_t)b * TT + sidx + NMETA;
;             hf[k] = *(const u32x4*)(H0 + src * 512 + 8 * lane); hb[k] = *(const u32x4*)(H1 + src * 512 + 8 * lane); gw[k] = *(const u32x4*)(P + src * INP + C_GATE + 8 * lane); }
;     ...
;             q = wave_sum(q);
;             if (rr < MR) { u32x4 w; w.x = cvt_pk(y[0], y[1]); w.y = cvt_pk(y[2], y[3]); w.z = cvt_pk(y[4], y[5]); w.w = cvt_pk(y[6], y[7]);
;                 *(u32x4*)(MIX + (size_t)rr * DM + 512 + 8 * lane) = w;
;                 if (lane == 0) ss_b[rr] = q; } }
	v_add_f32_e32 v132, v132, v133
	v_add_f32_e32 v144, v144, v145
	v_add_f32_e32 v168, v168, v169
	v_add_f32_e32 v180, v180, v181
	v_add_f32_e32 v192, v192, v193
	v_add_f32_e32 v204, v204, v205
	v_add_f32_e32 v216, v216, v217
	v_add_f32_e32 v228, v228, v229
	ds_bpermute_b32 v37, v6, v36
	ds_bpermute_b32 v49, v6, v48
	ds_bpermute_b32 v61, v6, v60
	ds_bpermute_b32 v73, v6, v72
	ds_bpermute_b32 v85, v6, v84
	ds_bpermute_b32 v97, v6, v96
	ds_bpermute_b32 v109, v6, v108
	ds_bpermute_b32 v121, v6, v120
	s_waitcnt lgkmcnt(0)
	v_add_f32_e32 v36, v36, v37
	v_add_f32_e32 v48, v48, v49
	v_add_f32_e32 v60, v60, v61
	v_add_f32_e32 v72, v72, v73
	v_add_f32_e32 v84, v84, v85
	v_add_f32_e32 v96, v96, v97
	v_add_f32_e32 v108, v108, v109
	v_add_f32_e32 v120, v120, v121
	ds_bpermute_b32 v133, v6, v132
	ds_bpermute_b32 v145, v6, v144
	ds_bpermute_b32 v169, v6, v168
	ds_bpermute_b32 v181, v6, v180
	ds_bpermute_b32 v193, v6, v192
	ds_bpermute_b32 v205, v6, v204
	ds_bpermute_b32 v217, v6, v216
	ds_bpermute_b32 v229, v6, v228
	s_waitcnt lgkmcnt(0)
	v_add_f32_e32 v132, v132, v133
	v_add_f32_e32 v144, v144, v145
	v_add_f32_e32 v168, v168, v169
	v_add_f32_e32 v180, v180, v181
	v_add_f32_e32 v192, v192, v193
	v_add_f32_e32 v204, v204, v205
	v_add_f32_e32 v216, v216, v217
	v_add_f32_e32 v228, v228, v229
	s_lshl_b32 s2, s0, 2
	s_add_u32 s4, s22, s2
	s_addc_u32 s5, s23, 0
	s_add_u32 s4, s4, 0x60800
	s_addc_u32 s5, s5, 0
	v_mov_b32_e32 v0, 0
	s_mov_b64 s[8:9], exec
	s_mov_b64 exec, 1
	global_store_dword v0, v36, s[4:5]
	s_add_u32 s4, s4, 0x2000
	s_addc_u32 s5, s5, 0
	global_store_dword v0, v48, s[4:5]
	s_add_u32 s4, s4, 0x2000
	s_addc_u32 s5, s5, 0
	global_store_dword v0, v60, s[4:5]
	s_add_u32 s4, s4, 0x2000
	s_addc_u32 s5, s5, 0
	global_store_dword v0, v72, s[4:5]
	s_add_u32 s4, s4, 0x2000
	s_addc_u32 s5, s5, 0
	global_store_dword v0, v84, s[4:5]
	s_add_u32 s4, s4, 0x2000
	s_addc_u32 s5, s5, 0
	global_store_dword v0, v96, s[4:5]
	s_add_u32 s4, s4, 0x2000
	s_addc_u32 s5, s5, 0
	global_store_dword v0, v108, s[4:5]
	s_add_u32 s4, s4, 0x2000
	s_addc_u32 s5, s5, 0
	global_store_dword v0, v120, s[4:5]
	s_add_u32 s4, s4, 0x2000
	s_addc_u32 s5, s5, 0
	global_store_dword v0, v132, s[4:5]
	s_add_u32 s4, s4, 0x2000
	s_addc_u32 s5, s5, 0
	global_store_dword v0, v144, s[4:5]
	s_add_u32 s4, s4, 0x2000
	s_addc_u32 s5, s5, 0
	global_store_dword v0, v168, s[4:5]
	s_add_u32 s4, s4, 0x2000
	s_addc_u32 s5, s5, 0
	global_store_dword v0, v180, s[4:5]
	s_add_u32 s4, s4, 0x2000
	s_addc_u32 s5, s5, 0
	global_store_dword v0, v192, s[4:5]
	s_add_u32 s4, s4, 0x2000
	s_addc_u32 s5, s5, 0
	global_store_dword v0, v204, s[4:5]
	s_add_u32 s4, s4, 0x2000
	s_addc_u32 s5, s5, 0
	global_store_dword v0, v216, s[4:5]
	s_add_u32 s4, s4, 0x2000
	s_addc_u32 s5, s5, 0
	global_store_dword v0, v228, s[4:5]
	s_mov_b64 exec, s[8:9]
	s_branch .Lcomb_done_b
.Lcomb_orig_b:
	v_lshl_add_u32 v54, s18, 3, v162
	s_mov_b32 s6, 0x8000
	v_cmp_gt_i32_e32 vcc, s6, v54
	s_and_saveexec_b64 s[12:13], vcc
	s_cbranch_execz .LBB0_776
	s_waitcnt lgkmcnt(0)
	v_and_b32_e32 v1, 63, v163
	v_mov_b32_e32 v49, 0
	v_lshlrev_b32_e32 v48, 4, v1
	v_lshl_add_u64 v[2:3], s[22:23], 0, v[48:49]
	s_mov_b64 s[0:1], 0x19800000
	v_lshl_add_u64 v[50:51], v[2:3], 0, s[0:1]
	s_mov_b64 s[0:1], 0x1b840000
	v_lshl_add_u64 v[52:53], v[2:3], 0, s[0:1]
	v_mbcnt_lo_u32_b32 v2, -1, 0
	v_mbcnt_hi_u32_b32 v2, -1, v2
	v_and_b32_e32 v3, 64, v2
	v_add_u32_e32 v3, 64, v3
	v_xor_b32_e32 v4, 1, v2
	v_cmp_lt_i32_e32 vcc, v4, v3
	s_add_u32 s14, s22, 0x60800
	v_lshlrev_b32_e32 v0, 3, v1
	v_cndmask_b32_e32 v4, v2, v4, vcc
	v_lshlrev_b32_e32 v60, 2, v4
	v_xor_b32_e32 v4, 2, v2
	v_cmp_lt_i32_e32 vcc, v4, v3
	s_addc_u32 s15, s23, 0
	s_lshl_b32 s7, s28, 3
	v_cndmask_b32_e32 v4, v2, v4, vcc
	v_lshlrev_b32_e32 v61, 2, v4
	v_xor_b32_e32 v4, 4, v2
	v_cmp_lt_i32_e32 vcc, v4, v3
	v_cmp_eq_u32_e64 s[0:1], 0, v1
	s_lshl_b32 s19, s28, 4
	v_cndmask_b32_e32 v4, v2, v4, vcc
	v_lshlrev_b32_e32 v62, 2, v4
	v_xor_b32_e32 v4, 8, v2
	v_cmp_lt_i32_e32 vcc, v4, v3
	s_mul_i32 s33, s28, 24
	s_mov_b64 s[16:17], 0
	v_cndmask_b32_e32 v4, v2, v4, vcc
	v_lshlrev_b32_e32 v63, 2, v4
	v_xor_b32_e32 v4, 16, v2
	v_cmp_lt_i32_e32 vcc, v4, v3
	s_movk_i32 s34, 0xe00
	v_mov_b64_e32 v[56:57], s[22:23]
	v_cndmask_b32_e32 v4, v2, v4, vcc
	v_lshlrev_b32_e32 v64, 2, v4
	v_xor_b32_e32 v4, 32, v2
	v_cmp_lt_i32_e32 vcc, v4, v3
	v_lshlrev_b32_e32 v48, 1, v0
	s_mov_b32 s35, 0x6400000
	v_cndmask_b32_e32 v2, v2, v4, vcc
	v_lshlrev_b32_e32 v65, 2, v2
	s_movk_i32 s38, 0x7fff
	s_branch .LBB0_765

; __device__ __forceinline__ void xcd_barrier(const XcdBarrier& b) {
;     asm volatile("s_waitcnt vmcnt(0)" ::: "memory");
;     __syncthreads();
;     if (threadIdx.x == 0) {
;         unsigned* bar = b.bar;
;         __builtin_amdgcn_s_waitcnt(0);
;         unsigned nloc = b.st[0], nx = b.st[1];
;         if (nloc == 0u) { xcd_barrier_complete(bar, b.x, nloc, nx); b.st[0] = nloc; b.st[1] = nx; }
.Lcomb_done_b:
.LBB0_777:
	s_cmp_gt_i32 s25, 4
	s_cselect_b64 s[0:1], -1, 0
	s_and_b64 s[2:3], s[86:87], s[0:1]
	s_andn2_b64 vcc, exec, s[2:3]
	s_cbranch_vccnz .LBB0_831
	s_waitcnt vmcnt(0)
	s_waitcnt lgkmcnt(0)
	s_barrier
	s_mov_b64 s[2:3], exec
	v_readlane_b32 s4, v244, 1
	v_readlane_b32 s5, v244, 2
	s_and_b64 s[4:5], s[2:3], s[4:5]
	s_mov_b64 exec, s[4:5]
	s_cbranch_execz .LBB0_830
	s_add_i32 s4, 0, 0x23ff0
	v_mov_b32_e32 v0, s4
	s_waitcnt vmcnt(0) expcnt(0) lgkmcnt(0)
	ds_read_b32 v2, v0
	s_add_i32 s4, 0, 0x23ff4
	v_mov_b32_e32 v0, s4
	ds_read_b32 v0, v0
	s_waitcnt lgkmcnt(1)
	v_cmp_ne_u32_e32 vcc, 0, v2
	s_cbranch_vccnz .LBB0_794
	v_readlane_b32 s4, v244, 0
	s_mul_i32 s6, s29, s4
	s_add_u32 s4, s26, 0x1000
	s_addc_u32 s5, s27, 0
	s_add_u32 s8, s26, 0x1100
	s_addc_u32 s9, s27, 0
	s_add_u32 s10, s26, 0x1200
	s_addc_u32 s11, s27, 0
	s_add_u32 s12, s26, 0x1300
	s_mul_i32 s6, s6, s28
	s_addc_u32 s13, s27, 0
	s_mov_b32 s7, 1
	v_mov_b32_e32 v16, 0
	s_branch .LBB0_782
